# GEMM mainloops: the two k-steps of each accumulator issued back to back inside every 16-MFMA block (same-D SrcC forwarding), accumulation order unchanged
# speedup vs baseline: 1.0104x; 1.0092x over previous
.LBB0_298:
	s_lshl_b64 s[4:5], s[20:21], 17
	s_add_u32 s24, s2, s4
	s_addc_u32 s25, s19, s5
	s_and_b64 s[4:5], s[36:37], exec
	s_cselect_b32 s37, s25, s31
	s_cselect_b32 s36, s24, s30
	s_add_u32 s56, s30, 0x100
	s_addc_u32 s57, s31, 0
	s_add_u32 s80, s34, 0x100
	s_addc_u32 s81, s35, 0
	s_add_u32 s38, s30, 0x180
	s_addc_u32 s39, s31, 0
	s_add_i32 s4, 0, 0x10000
	s_add_i32 s17, 0, 0x14000
	v_add_u32_e32 v128, s4, v134
	v_add_u32_e32 v129, s17, v134
	ds_read_b128 v[0:3], v128
	ds_read_b128 v[4:7], v128 offset:1024
	ds_read_b128 v[8:11], v128 offset:2048
	ds_read_b128 v[12:15], v128 offset:3072
	ds_read_b128 v[16:19], v129
	ds_read_b128 v[20:23], v129 offset:1024
	ds_read_b128 v[24:27], v129 offset:2048
	ds_read_b128 v[28:31], v129 offset:3072
	s_add_u32 s70, s30, 0x10080
	s_addc_u32 s71, s31, 0
	s_add_i32 s5, s13, 0xc000
	s_mov_b32 m0, s5
	s_add_i32 s15, s13, 0xe000
	ds_read_b128 v[32:35], v135
	ds_read_b128 v[36:39], v135 offset:1024
	ds_read_b128 v[40:43], v135 offset:2048
	ds_read_b128 v[44:47], v135 offset:3072
	ds_read_b128 v[48:51], v135 offset:4096
	ds_read_b128 v[52:55], v135 offset:5120
	ds_read_b128 v[56:59], v135 offset:6144
	ds_read_b128 v[60:63], v135 offset:7168
	s_nop 0
	global_load_lds_dwordx4 v130, s[70:71]
	s_mov_b32 m0, s15
	s_nop 0
	global_load_lds_dwordx4 v132, s[70:71]
	s_waitcnt vmcnt(8)
	s_waitcnt lgkmcnt(0)
	s_barrier
	s_setprio 1
	s_waitcnt lgkmcnt(0)
	v_mfma_f32_16x16x32_bf16 v[64:67], v[0:3], v[32:35], 0
	v_mfma_f32_16x16x32_bf16 v[68:71], v[8:11], v[32:35], 0
	v_mfma_f32_16x16x32_bf16 v[72:75], v[0:3], v[40:43], 0
	v_mfma_f32_16x16x32_bf16 v[76:79], v[8:11], v[40:43], 0
	v_mfma_f32_16x16x32_bf16 v[80:83], v[0:3], v[48:51], 0
	v_mfma_f32_16x16x32_bf16 v[84:87], v[8:11], v[48:51], 0
	v_mfma_f32_16x16x32_bf16 v[88:91], v[0:3], v[56:59], 0
	v_mfma_f32_16x16x32_bf16 v[92:95], v[8:11], v[56:59], 0
	v_mfma_f32_16x16x32_bf16 v[64:67], v[4:7], v[36:39], v[64:67]
	v_mfma_f32_16x16x32_bf16 v[68:71], v[12:15], v[36:39], v[68:71]
	v_mfma_f32_16x16x32_bf16 v[72:75], v[4:7], v[44:47], v[72:75]
	v_mfma_f32_16x16x32_bf16 v[76:79], v[12:15], v[44:47], v[76:79]
	v_mfma_f32_16x16x32_bf16 v[80:83], v[4:7], v[52:55], v[80:83]
	v_mfma_f32_16x16x32_bf16 v[84:87], v[12:15], v[52:55], v[84:87]
	v_mfma_f32_16x16x32_bf16 v[88:91], v[4:7], v[60:63], v[88:91]
	v_mfma_f32_16x16x32_bf16 v[92:95], v[12:15], v[60:63], v[92:95]
	s_setprio 0
	s_setprio 1
	v_mfma_f32_16x16x32_bf16 v[96:99], v[16:19], v[32:35], 0
	v_mfma_f32_16x16x32_bf16 v[32:35], v[24:27], v[32:35], 0
	v_mfma_f32_16x16x32_bf16 v[96:99], v[20:23], v[36:39], v[96:99]
	v_mfma_f32_16x16x32_bf16 v[32:35], v[28:31], v[36:39], v[32:35]
	v_mfma_f32_16x16x32_bf16 v[36:39], v[16:19], v[40:43], 0
	v_mfma_f32_16x16x32_bf16 v[40:43], v[24:27], v[40:43], 0
	v_mfma_f32_16x16x32_bf16 v[36:39], v[20:23], v[44:47], v[36:39]
	v_mfma_f32_16x16x32_bf16 v[40:43], v[28:31], v[44:47], v[40:43]
	v_mfma_f32_16x16x32_bf16 v[44:47], v[16:19], v[48:51], 0
	v_mfma_f32_16x16x32_bf16 v[48:51], v[24:27], v[48:51], 0
	v_mfma_f32_16x16x32_bf16 v[44:47], v[20:23], v[52:55], v[44:47]
	v_mfma_f32_16x16x32_bf16 v[48:51], v[28:31], v[52:55], v[48:51]
	v_mfma_f32_16x16x32_bf16 v[52:55], v[16:19], v[56:59], 0
	v_mfma_f32_16x16x32_bf16 v[56:59], v[24:27], v[56:59], 0
	v_mfma_f32_16x16x32_bf16 v[52:55], v[20:23], v[60:63], v[52:55]
	v_mfma_f32_16x16x32_bf16 v[56:59], v[28:31], v[60:63], v[56:59]
	s_setprio 0
	s_barrier
	s_add_i32 s70, s4, s97
	s_add_i32 s4, s70, 0x2000
	s_mov_b32 m0, s70
	s_add_u32 s74, s34, 0x80100
	ds_read_b128 v[60:63], v135 offset:16384
	ds_read_b128 v[100:103], v135 offset:17408
	ds_read_b128 v[104:107], v135 offset:18432
	ds_read_b128 v[108:111], v135 offset:19456
	ds_read_b128 v[112:115], v135 offset:20480
	ds_read_b128 v[116:119], v135 offset:21504
	ds_read_b128 v[120:123], v135 offset:22528
	ds_read_b128 v[124:127], v135 offset:23552
	s_addc_u32 s75, s35, 0
	global_load_lds_dwordx4 v131, s[80:81]
	s_mov_b32 m0, s4
	s_add_i32 s17, s17, s97
	s_add_i32 s21, s17, 0x2000
	global_load_lds_dwordx4 v133, s[80:81]
	s_mov_b32 m0, s17
	s_nop 0
	global_load_lds_dwordx4 v131, s[74:75]
	s_mov_b32 m0, s21
	s_nop 0
	global_load_lds_dwordx4 v133, s[74:75]
	s_mov_b32 m0, s13
	s_nop 0
	global_load_lds_dwordx4 v130, s[56:57]
	s_mov_b32 m0, s27
	s_nop 0
	global_load_lds_dwordx4 v132, s[56:57]
	s_waitcnt vmcnt(8)
	s_waitcnt lgkmcnt(0)
	s_barrier
	s_setprio 1
	s_waitcnt lgkmcnt(0)
	v_mfma_f32_16x16x32_bf16 v[136:139], v[0:3], v[60:63], 0
	v_mfma_f32_16x16x32_bf16 v[144:147], v[0:3], v[104:107], 0
	v_mfma_f32_16x16x32_bf16 v[152:155], v[0:3], v[112:115], 0
	v_mfma_f32_16x16x32_bf16 v[0:3], v[0:3], v[120:123], 0
	v_mfma_f32_16x16x32_bf16 v[136:139], v[4:7], v[100:103], v[136:139]
	v_mfma_f32_16x16x32_bf16 v[144:147], v[4:7], v[108:111], v[144:147]
	v_mfma_f32_16x16x32_bf16 v[152:155], v[4:7], v[116:119], v[152:155]
	v_mfma_f32_16x16x32_bf16 v[0:3], v[4:7], v[124:127], v[0:3]
	v_mfma_f32_16x16x32_bf16 v[4:7], v[8:11], v[120:123], 0
	v_mfma_f32_16x16x32_bf16 v[140:143], v[8:11], v[60:63], 0
	v_mfma_f32_16x16x32_bf16 v[148:151], v[8:11], v[104:107], 0
	v_mfma_f32_16x16x32_bf16 v[156:159], v[8:11], v[112:115], 0
	v_mfma_f32_16x16x32_bf16 v[4:7], v[12:15], v[124:127], v[4:7]
	v_mfma_f32_16x16x32_bf16 v[140:143], v[12:15], v[100:103], v[140:143]
	v_mfma_f32_16x16x32_bf16 v[148:151], v[12:15], v[108:111], v[148:151]
	v_mfma_f32_16x16x32_bf16 v[156:159], v[12:15], v[116:119], v[156:159]
	s_setprio 0
	s_setprio 1
	v_mfma_f32_16x16x32_bf16 v[8:11], v[16:19], v[60:63], 0
	v_mfma_f32_16x16x32_bf16 v[12:15], v[24:27], v[60:63], 0
	v_mfma_f32_16x16x32_bf16 v[8:11], v[20:23], v[100:103], v[8:11]
	v_mfma_f32_16x16x32_bf16 v[12:15], v[28:31], v[100:103], v[12:15]
	v_mfma_f32_16x16x32_bf16 v[60:63], v[16:19], v[104:107], 0
	v_mfma_f32_16x16x32_bf16 v[100:103], v[24:27], v[104:107], 0
	v_mfma_f32_16x16x32_bf16 v[104:107], v[16:19], v[112:115], 0
	v_mfma_f32_16x16x32_bf16 v[16:19], v[16:19], v[120:123], 0
	v_mfma_f32_16x16x32_bf16 v[60:63], v[20:23], v[108:111], v[60:63]
	v_mfma_f32_16x16x32_bf16 v[100:103], v[28:31], v[108:111], v[100:103]
	v_mfma_f32_16x16x32_bf16 v[104:107], v[20:23], v[116:119], v[104:107]
	v_mfma_f32_16x16x32_bf16 v[108:111], v[24:27], v[112:115], 0
	v_mfma_f32_16x16x32_bf16 v[16:19], v[20:23], v[124:127], v[16:19]
	v_mfma_f32_16x16x32_bf16 v[20:23], v[24:27], v[120:123], 0
	v_mfma_f32_16x16x32_bf16 v[108:111], v[28:31], v[116:119], v[108:111]
	v_mfma_f32_16x16x32_bf16 v[20:23], v[28:31], v[124:127], v[20:23]
	s_setprio 0
	s_barrier
	s_add_i32 s71, 0, 0x18000
	s_add_i32 s69, 0, 0x1c000
	v_add_u32_e32 v196, s71, v134
	v_add_u32_e32 v198, s69, v134
	ds_read_b128 v[24:27], v196
	ds_read_b128 v[28:31], v196 offset:1024
	ds_read_b128 v[112:115], v196 offset:2048
	ds_read_b128 v[116:119], v196 offset:3072
	ds_read_b128 v[120:123], v198
	ds_read_b128 v[124:127], v198 offset:1024
	ds_read_b128 v[160:163], v198 offset:2048
	ds_read_b128 v[164:167], v198 offset:3072
	s_add_u32 s56, s30, 0x10100
	s_addc_u32 s57, s31, 0
	s_mov_b32 m0, s29
	ds_read_b128 v[168:171], v135 offset:32768
	ds_read_b128 v[172:175], v135 offset:33792
	ds_read_b128 v[176:179], v135 offset:34816
	ds_read_b128 v[180:183], v135 offset:35840
	ds_read_b128 v[184:187], v135 offset:36864
	ds_read_b128 v[188:191], v135 offset:37888
	ds_read_b128 v[192:195], v135 offset:38912
	ds_read_b128 v[200:203], v135 offset:39936
	s_nop 0
	global_load_lds_dwordx4 v130, s[56:57]
	s_mov_b32 m0, s47
	s_nop 0
	global_load_lds_dwordx4 v132, s[56:57]
	s_waitcnt vmcnt(8)
	s_waitcnt lgkmcnt(0)
	s_barrier
	s_setprio 1
	s_waitcnt lgkmcnt(0)
	v_mfma_f32_16x16x32_bf16 v[64:67], v[24:27], v[168:171], v[64:67]
	v_mfma_f32_16x16x32_bf16 v[64:67], v[28:31], v[172:175], v[64:67]
	v_mfma_f32_16x16x32_bf16 v[68:71], v[112:115], v[168:171], v[68:71]
	v_mfma_f32_16x16x32_bf16 v[68:71], v[116:119], v[172:175], v[68:71]
	v_mfma_f32_16x16x32_bf16 v[72:75], v[24:27], v[176:179], v[72:75]
	v_mfma_f32_16x16x32_bf16 v[72:75], v[28:31], v[180:183], v[72:75]
	v_mfma_f32_16x16x32_bf16 v[76:79], v[112:115], v[176:179], v[76:79]
	v_mfma_f32_16x16x32_bf16 v[76:79], v[116:119], v[180:183], v[76:79]
	v_mfma_f32_16x16x32_bf16 v[80:83], v[24:27], v[184:187], v[80:83]
	v_mfma_f32_16x16x32_bf16 v[80:83], v[28:31], v[188:191], v[80:83]
	v_mfma_f32_16x16x32_bf16 v[84:87], v[112:115], v[184:187], v[84:87]
	v_mfma_f32_16x16x32_bf16 v[84:87], v[116:119], v[188:191], v[84:87]
	v_mfma_f32_16x16x32_bf16 v[88:91], v[24:27], v[192:195], v[88:91]
	v_mfma_f32_16x16x32_bf16 v[88:91], v[28:31], v[200:203], v[88:91]
	v_mfma_f32_16x16x32_bf16 v[92:95], v[112:115], v[192:195], v[92:95]
	v_mfma_f32_16x16x32_bf16 v[92:95], v[116:119], v[200:203], v[92:95]
	s_setprio 0
	s_setprio 1
	v_mfma_f32_16x16x32_bf16 v[96:99], v[120:123], v[168:171], v[96:99]
	v_mfma_f32_16x16x32_bf16 v[96:99], v[124:127], v[172:175], v[96:99]
	v_mfma_f32_16x16x32_bf16 v[32:35], v[160:163], v[168:171], v[32:35]
	v_mfma_f32_16x16x32_bf16 v[32:35], v[164:167], v[172:175], v[32:35]
	v_mfma_f32_16x16x32_bf16 v[36:39], v[120:123], v[176:179], v[36:39]
	v_mfma_f32_16x16x32_bf16 v[36:39], v[124:127], v[180:183], v[36:39]
	v_mfma_f32_16x16x32_bf16 v[40:43], v[160:163], v[176:179], v[40:43]
	v_mfma_f32_16x16x32_bf16 v[40:43], v[164:167], v[180:183], v[40:43]
	v_mfma_f32_16x16x32_bf16 v[44:47], v[120:123], v[184:187], v[44:47]
	v_mfma_f32_16x16x32_bf16 v[44:47], v[124:127], v[188:191], v[44:47]
	v_mfma_f32_16x16x32_bf16 v[48:51], v[160:163], v[184:187], v[48:51]
	v_mfma_f32_16x16x32_bf16 v[48:51], v[164:167], v[188:191], v[48:51]
	v_mfma_f32_16x16x32_bf16 v[52:55], v[120:123], v[192:195], v[52:55]
	v_mfma_f32_16x16x32_bf16 v[52:55], v[124:127], v[200:203], v[52:55]
	v_mfma_f32_16x16x32_bf16 v[56:59], v[160:163], v[192:195], v[56:59]
	v_mfma_f32_16x16x32_bf16 v[56:59], v[164:167], v[200:203], v[56:59]
	s_setprio 0
	s_barrier
	s_add_u32 s74, s34, 0x180
	s_addc_u32 s75, s35, 0
	s_add_i32 s71, s71, s97
	s_add_i32 s56, s71, 0x2000
	s_mov_b32 m0, s71
	s_add_u32 s34, s34, 0x80180
	ds_read_b128 v[168:171], v135 offset:49152
	ds_read_b128 v[172:175], v135 offset:50176
	ds_read_b128 v[176:179], v135 offset:51200
	ds_read_b128 v[180:183], v135 offset:52224
	ds_read_b128 v[184:187], v135 offset:53248
	ds_read_b128 v[188:191], v135 offset:54272
	ds_read_b128 v[192:195], v135 offset:55296
	ds_read_b128 v[200:203], v135 offset:56320
	s_addc_u32 s35, s35, 0
	global_load_lds_dwordx4 v131, s[74:75]
	s_mov_b32 m0, s56
	s_add_i32 s57, s69, s97
	s_add_i32 s69, s57, 0x2000
	global_load_lds_dwordx4 v133, s[74:75]
	s_mov_b32 m0, s57
	s_nop 0
	global_load_lds_dwordx4 v131, s[34:35]
	s_mov_b32 m0, s69
	s_nop 0
	global_load_lds_dwordx4 v133, s[34:35]
	s_mov_b32 m0, s48
	s_nop 0
	global_load_lds_dwordx4 v130, s[38:39]
	s_mov_b32 m0, s49
	s_nop 0
	global_load_lds_dwordx4 v132, s[38:39]
	s_waitcnt vmcnt(8)
	s_waitcnt lgkmcnt(0)
	s_barrier
	s_setprio 1
	s_waitcnt lgkmcnt(0)
	v_mfma_f32_16x16x32_bf16 v[0:3], v[24:27], v[192:195], v[0:3]
	v_mfma_f32_16x16x32_bf16 v[0:3], v[28:31], v[200:203], v[0:3]
	v_mfma_f32_16x16x32_bf16 v[4:7], v[112:115], v[192:195], v[4:7]
	v_mfma_f32_16x16x32_bf16 v[4:7], v[116:119], v[200:203], v[4:7]
	v_mfma_f32_16x16x32_bf16 v[136:139], v[24:27], v[168:171], v[136:139]
	v_mfma_f32_16x16x32_bf16 v[136:139], v[28:31], v[172:175], v[136:139]
	v_mfma_f32_16x16x32_bf16 v[140:143], v[112:115], v[168:171], v[140:143]
	v_mfma_f32_16x16x32_bf16 v[140:143], v[116:119], v[172:175], v[140:143]
	v_mfma_f32_16x16x32_bf16 v[144:147], v[24:27], v[176:179], v[144:147]
	v_mfma_f32_16x16x32_bf16 v[144:147], v[28:31], v[180:183], v[144:147]
	v_mfma_f32_16x16x32_bf16 v[148:151], v[112:115], v[176:179], v[148:151]
	v_mfma_f32_16x16x32_bf16 v[148:151], v[116:119], v[180:183], v[148:151]
	v_mfma_f32_16x16x32_bf16 v[152:155], v[24:27], v[184:187], v[152:155]
	v_mfma_f32_16x16x32_bf16 v[152:155], v[28:31], v[188:191], v[152:155]
	v_mfma_f32_16x16x32_bf16 v[156:159], v[112:115], v[184:187], v[156:159]
	v_mfma_f32_16x16x32_bf16 v[156:159], v[116:119], v[188:191], v[156:159]
	s_setprio 0
	s_setprio 1
	v_mfma_f32_16x16x32_bf16 v[8:11], v[120:123], v[168:171], v[8:11]
	v_mfma_f32_16x16x32_bf16 v[12:15], v[160:163], v[168:171], v[12:15]
	v_mfma_f32_16x16x32_bf16 v[24:27], v[120:123], v[176:179], v[60:63]
	v_mfma_f32_16x16x32_bf16 v[28:31], v[160:163], v[176:179], v[100:103]
	v_mfma_f32_16x16x32_bf16 v[60:63], v[120:123], v[184:187], v[104:107]
	v_mfma_f32_16x16x32_bf16 v[100:103], v[160:163], v[184:187], v[108:111]
	v_mfma_f32_16x16x32_bf16 v[16:19], v[120:123], v[192:195], v[16:19]
	v_mfma_f32_16x16x32_bf16 v[20:23], v[160:163], v[192:195], v[20:23]
	v_mfma_f32_16x16x32_bf16 v[8:11], v[124:127], v[172:175], v[8:11]
	v_mfma_f32_16x16x32_bf16 v[12:15], v[164:167], v[172:175], v[12:15]
	v_mfma_f32_16x16x32_bf16 v[24:27], v[124:127], v[180:183], v[24:27]
	v_mfma_f32_16x16x32_bf16 v[28:31], v[164:167], v[180:183], v[28:31]
	v_mfma_f32_16x16x32_bf16 v[60:63], v[124:127], v[188:191], v[60:63]
	v_mfma_f32_16x16x32_bf16 v[100:103], v[164:167], v[188:191], v[100:103]
	v_mfma_f32_16x16x32_bf16 v[16:19], v[124:127], v[200:203], v[16:19]
	v_mfma_f32_16x16x32_bf16 v[20:23], v[164:167], v[200:203], v[20:23]
	s_setprio 0
	s_barrier
	ds_read_b128 v[104:107], v128
	ds_read_b128 v[108:111], v128 offset:1024
	ds_read_b128 v[112:115], v128 offset:2048
	ds_read_b128 v[116:119], v128 offset:3072
	ds_read_b128 v[120:123], v129
	ds_read_b128 v[124:127], v129 offset:1024
	ds_read_b128 v[160:163], v129 offset:2048
	ds_read_b128 v[164:167], v129 offset:3072
	s_add_u32 s34, s36, 0x80
	s_addc_u32 s35, s37, 0
	s_add_u32 s30, s30, 0x10180
	s_addc_u32 s31, s31, 0
	s_mov_b32 m0, s5
	ds_read_b128 v[168:171], v135
	ds_read_b128 v[172:175], v135 offset:1024
	ds_read_b128 v[176:179], v135 offset:2048
	ds_read_b128 v[180:183], v135 offset:3072
	ds_read_b128 v[184:187], v135 offset:4096
	ds_read_b128 v[188:191], v135 offset:5120
	ds_read_b128 v[192:195], v135 offset:6144
	ds_read_b128 v[200:203], v135 offset:7168
	s_nop 0
	global_load_lds_dwordx4 v130, s[30:31]
	s_mov_b32 m0, s15
	s_nop 0
	global_load_lds_dwordx4 v132, s[30:31]
	s_waitcnt vmcnt(8)
	s_waitcnt lgkmcnt(0)
	s_barrier
	s_setprio 1
	s_waitcnt lgkmcnt(0)
	v_mfma_f32_16x16x32_bf16 v[64:67], v[104:107], v[168:171], v[64:67]
	v_mfma_f32_16x16x32_bf16 v[64:67], v[108:111], v[172:175], v[64:67]
	v_mfma_f32_16x16x32_bf16 v[68:71], v[112:115], v[168:171], v[68:71]
	v_mfma_f32_16x16x32_bf16 v[68:71], v[116:119], v[172:175], v[68:71]
	v_mfma_f32_16x16x32_bf16 v[72:75], v[104:107], v[176:179], v[72:75]
	v_mfma_f32_16x16x32_bf16 v[72:75], v[108:111], v[180:183], v[72:75]
	v_mfma_f32_16x16x32_bf16 v[76:79], v[112:115], v[176:179], v[76:79]
	v_mfma_f32_16x16x32_bf16 v[76:79], v[116:119], v[180:183], v[76:79]
	v_mfma_f32_16x16x32_bf16 v[80:83], v[104:107], v[184:187], v[80:83]
	v_mfma_f32_16x16x32_bf16 v[80:83], v[108:111], v[188:191], v[80:83]
	v_mfma_f32_16x16x32_bf16 v[84:87], v[112:115], v[184:187], v[84:87]
	v_mfma_f32_16x16x32_bf16 v[84:87], v[116:119], v[188:191], v[84:87]
	v_mfma_f32_16x16x32_bf16 v[88:91], v[104:107], v[192:195], v[88:91]
	v_mfma_f32_16x16x32_bf16 v[88:91], v[108:111], v[200:203], v[88:91]
	v_mfma_f32_16x16x32_bf16 v[92:95], v[112:115], v[192:195], v[92:95]
	v_mfma_f32_16x16x32_bf16 v[92:95], v[116:119], v[200:203], v[92:95]
	s_setprio 0
	s_setprio 1
	v_mfma_f32_16x16x32_bf16 v[32:35], v[160:163], v[168:171], v[32:35]
	v_mfma_f32_16x16x32_bf16 v[96:99], v[120:123], v[168:171], v[96:99]
	v_mfma_f32_16x16x32_bf16 v[168:171], v[164:167], v[172:175], v[32:35]
	v_mfma_f32_16x16x32_bf16 v[32:35], v[120:123], v[176:179], v[36:39]
	v_mfma_f32_16x16x32_bf16 v[36:39], v[124:127], v[180:183], v[32:35]
	v_mfma_f32_16x16x32_bf16 v[32:35], v[160:163], v[176:179], v[40:43]
	v_mfma_f32_16x16x32_bf16 v[204:207], v[124:127], v[172:175], v[96:99]
	v_mfma_f32_16x16x32_bf16 v[172:175], v[164:167], v[180:183], v[32:35]
	v_mfma_f32_16x16x32_bf16 v[32:35], v[120:123], v[184:187], v[44:47]
	v_mfma_f32_16x16x32_bf16 v[44:47], v[124:127], v[188:191], v[32:35]
	v_mfma_f32_16x16x32_bf16 v[32:35], v[160:163], v[184:187], v[48:51]
	v_mfma_f32_16x16x32_bf16 v[48:51], v[164:167], v[188:191], v[32:35]
	v_mfma_f32_16x16x32_bf16 v[32:35], v[120:123], v[192:195], v[52:55]
	v_mfma_f32_16x16x32_bf16 v[52:55], v[124:127], v[200:203], v[32:35]
	v_mfma_f32_16x16x32_bf16 v[32:35], v[160:163], v[192:195], v[56:59]
	v_mfma_f32_16x16x32_bf16 v[56:59], v[164:167], v[200:203], v[32:35]
	s_setprio 0
	s_barrier
	s_mov_b32 m0, s70
	s_mov_b64 s[30:31], s[22:23]
	s_nop 2
	ds_read_b128 v[32:35], v135 offset:16384
	ds_read_b128 v[40:43], v135 offset:17408
	ds_read_b128 v[96:99], v135 offset:18432
	ds_read_b128 v[176:179], v135 offset:19456
	ds_read_b128 v[180:183], v135 offset:20480
	ds_read_b128 v[184:187], v135 offset:21504
	ds_read_b128 v[188:191], v135 offset:22528
	ds_read_b128 v[192:195], v135 offset:23552
	s_nop 0
	global_load_lds_dwordx4 v131, s[30:31]
	s_mov_b32 m0, s4
	s_add_u32 s4, s22, 0x80000
	s_addc_u32 s5, s23, 0
	global_load_lds_dwordx4 v133, s[30:31]
	s_mov_b32 m0, s17
	s_nop 0
	global_load_lds_dwordx4 v131, s[4:5]
	s_mov_b32 m0, s21
	s_nop 0
	global_load_lds_dwordx4 v133, s[4:5]
	s_mov_b64 s[4:5], s[36:37]
	s_mov_b32 m0, s13
	s_nop 0
	global_load_lds_dwordx4 v130, s[4:5]
	s_mov_b32 m0, s27
	s_nop 0
	global_load_lds_dwordx4 v132, s[4:5]
	s_waitcnt vmcnt(8)
	s_waitcnt lgkmcnt(0)
	s_barrier
	s_setprio 1
	s_waitcnt lgkmcnt(0)
	v_mfma_f32_16x16x32_bf16 v[0:3], v[104:107], v[188:191], v[0:3]
	v_mfma_f32_16x16x32_bf16 v[0:3], v[108:111], v[192:195], v[0:3]
	v_mfma_f32_16x16x32_bf16 v[4:7], v[112:115], v[188:191], v[4:7]
	v_mfma_f32_16x16x32_bf16 v[4:7], v[116:119], v[192:195], v[4:7]
	v_mfma_f32_16x16x32_bf16 v[136:139], v[104:107], v[32:35], v[136:139]
	v_mfma_f32_16x16x32_bf16 v[136:139], v[108:111], v[40:43], v[136:139]
	v_mfma_f32_16x16x32_bf16 v[140:143], v[112:115], v[32:35], v[140:143]
	v_mfma_f32_16x16x32_bf16 v[140:143], v[116:119], v[40:43], v[140:143]
	v_mfma_f32_16x16x32_bf16 v[144:147], v[104:107], v[96:99], v[144:147]
	v_mfma_f32_16x16x32_bf16 v[144:147], v[108:111], v[176:179], v[144:147]
	v_mfma_f32_16x16x32_bf16 v[148:151], v[112:115], v[96:99], v[148:151]
	v_mfma_f32_16x16x32_bf16 v[148:151], v[116:119], v[176:179], v[148:151]
	v_mfma_f32_16x16x32_bf16 v[152:155], v[104:107], v[180:183], v[152:155]
	v_mfma_f32_16x16x32_bf16 v[152:155], v[108:111], v[184:187], v[152:155]
	v_mfma_f32_16x16x32_bf16 v[156:159], v[112:115], v[180:183], v[156:159]
	v_mfma_f32_16x16x32_bf16 v[156:159], v[116:119], v[184:187], v[156:159]
	s_setprio 0
	s_setprio 1
	v_mfma_f32_16x16x32_bf16 v[12:15], v[160:163], v[32:35], v[12:15]
	v_mfma_f32_16x16x32_bf16 v[200:203], v[164:167], v[40:43], v[12:15]
	v_mfma_f32_16x16x32_bf16 v[12:15], v[120:123], v[96:99], v[24:27]
	v_mfma_f32_16x16x32_bf16 v[24:27], v[124:127], v[176:179], v[12:15]
	v_mfma_f32_16x16x32_bf16 v[12:15], v[160:163], v[96:99], v[28:31]
	v_mfma_f32_16x16x32_bf16 v[176:179], v[164:167], v[176:179], v[12:15]
	v_mfma_f32_16x16x32_bf16 v[12:15], v[120:123], v[180:183], v[60:63]
	v_mfma_f32_16x16x32_bf16 v[208:211], v[124:127], v[184:187], v[12:15]
	v_mfma_f32_16x16x32_bf16 v[12:15], v[160:163], v[180:183], v[100:103]
	v_mfma_f32_16x16x32_bf16 v[8:11], v[120:123], v[32:35], v[8:11]
	v_mfma_f32_16x16x32_bf16 v[180:183], v[164:167], v[184:187], v[12:15]
	v_mfma_f32_16x16x32_bf16 v[12:15], v[120:123], v[188:191], v[16:19]
	v_mfma_f32_16x16x32_bf16 v[8:11], v[124:127], v[40:43], v[8:11]
	v_mfma_f32_16x16x32_bf16 v[184:187], v[124:127], v[192:195], v[12:15]
	v_mfma_f32_16x16x32_bf16 v[12:15], v[160:163], v[188:191], v[20:23]
	v_mfma_f32_16x16x32_bf16 v[160:163], v[164:167], v[192:195], v[12:15]
	s_setprio 0
	s_barrier
	s_nop 4
	ds_read_b128 v[12:15], v196
	ds_read_b128 v[16:19], v196 offset:1024
	ds_read_b128 v[164:167], v196 offset:2048
	ds_read_b128 v[188:191], v196 offset:3072
	ds_read_b128 v[192:195], v198
	ds_read_b128 v[220:223], v198 offset:1024
	ds_read_b128 v[224:227], v198 offset:2048
	ds_read_b128 v[228:231], v198 offset:3072
	s_add_u32 s4, s36, 0x10000
	s_addc_u32 s5, s37, 0
	s_mov_b32 m0, s29
	ds_read_b128 v[20:23], v135 offset:32768
	ds_read_b128 v[28:31], v135 offset:33792
	ds_read_b128 v[60:63], v135 offset:34816
	ds_read_b128 v[100:103], v135 offset:35840
	ds_read_b128 v[232:235], v135 offset:36864
	ds_read_b128 v[236:239], v135 offset:37888
	ds_read_b128 v[240:243], v135 offset:38912
	ds_read_b128 v[244:247], v135 offset:39936
	s_nop 0
	global_load_lds_dwordx4 v130, s[4:5]
	s_mov_b32 m0, s47
	s_nop 0
	global_load_lds_dwordx4 v132, s[4:5]
	s_waitcnt vmcnt(8)
	s_waitcnt lgkmcnt(0)
	s_barrier
	s_setprio 1
	s_waitcnt lgkmcnt(0)
	v_mfma_f32_16x16x32_bf16 v[32:35], v[12:15], v[20:23], v[64:67]
	v_mfma_f32_16x16x32_bf16 v[120:123], v[16:19], v[28:31], v[32:35]
	v_mfma_f32_16x16x32_bf16 v[32:35], v[164:167], v[20:23], v[68:71]
	v_mfma_f32_16x16x32_bf16 v[112:115], v[188:191], v[28:31], v[32:35]
	v_mfma_f32_16x16x32_bf16 v[32:35], v[12:15], v[60:63], v[72:75]
	v_mfma_f32_16x16x32_bf16 v[104:107], v[16:19], v[100:103], v[32:35]
	v_mfma_f32_16x16x32_bf16 v[32:35], v[164:167], v[60:63], v[76:79]
	v_mfma_f32_16x16x32_bf16 v[96:99], v[188:191], v[100:103], v[32:35]
	v_mfma_f32_16x16x32_bf16 v[32:35], v[12:15], v[232:235], v[80:83]
	v_mfma_f32_16x16x32_bf16 v[72:75], v[16:19], v[236:239], v[32:35]
	v_mfma_f32_16x16x32_bf16 v[32:35], v[164:167], v[232:235], v[84:87]
	v_mfma_f32_16x16x32_bf16 v[64:67], v[188:191], v[236:239], v[32:35]
	v_mfma_f32_16x16x32_bf16 v[32:35], v[12:15], v[240:243], v[88:91]
	v_mfma_f32_16x16x32_bf16 v[40:43], v[16:19], v[244:247], v[32:35]
	v_mfma_f32_16x16x32_bf16 v[32:35], v[164:167], v[240:243], v[92:95]
	v_mfma_f32_16x16x32_bf16 v[32:35], v[188:191], v[244:247], v[32:35]
	s_setprio 0
	s_setprio 1
	v_mfma_f32_16x16x32_bf16 v[68:71], v[192:195], v[20:23], v[204:207]
	v_mfma_f32_16x16x32_bf16 v[20:23], v[224:227], v[20:23], v[168:171]
	v_mfma_f32_16x16x32_bf16 v[116:119], v[228:231], v[28:31], v[20:23]
	v_mfma_f32_16x16x32_bf16 v[20:23], v[192:195], v[60:63], v[36:39]
	v_mfma_f32_16x16x32_bf16 v[108:111], v[220:223], v[100:103], v[20:23]
	v_mfma_f32_16x16x32_bf16 v[20:23], v[224:227], v[60:63], v[172:175]
	v_mfma_f32_16x16x32_bf16 v[100:103], v[228:231], v[100:103], v[20:23]
	v_mfma_f32_16x16x32_bf16 v[20:23], v[192:195], v[232:235], v[44:47]
	v_mfma_f32_16x16x32_bf16 v[76:79], v[220:223], v[236:239], v[20:23]
	v_mfma_f32_16x16x32_bf16 v[20:23], v[224:227], v[232:235], v[48:51]
	v_mfma_f32_16x16x32_bf16 v[124:127], v[220:223], v[28:31], v[68:71]
	v_mfma_f32_16x16x32_bf16 v[68:71], v[228:231], v[236:239], v[20:23]
	v_mfma_f32_16x16x32_bf16 v[20:23], v[192:195], v[240:243], v[52:55]
	v_mfma_f32_16x16x32_bf16 v[44:47], v[220:223], v[244:247], v[20:23]
	v_mfma_f32_16x16x32_bf16 v[20:23], v[224:227], v[240:243], v[56:59]
	v_mfma_f32_16x16x32_bf16 v[36:39], v[228:231], v[244:247], v[20:23]
	s_setprio 0
	s_barrier
	s_add_u32 s4, s22, 0x80
	s_mov_b32 m0, s71
	s_addc_u32 s5, s23, 0
	ds_read_b128 v[48:51], v135 offset:49152
	ds_read_b128 v[56:59], v135 offset:50176
	ds_read_b128 v[168:171], v135 offset:51200
	ds_read_b128 v[172:175], v135 offset:52224
	ds_read_b128 v[204:207], v135 offset:53248
	ds_read_b128 v[232:235], v135 offset:54272
	ds_read_b128 v[236:239], v135 offset:55296
	ds_read_b128 v[240:243], v135 offset:56320
	s_nop 0
	global_load_lds_dwordx4 v131, s[4:5]
	s_mov_b32 m0, s56
	s_nop 0
	global_load_lds_dwordx4 v133, s[4:5]
	s_add_u32 s4, s22, 0x80080
	s_addc_u32 s5, s23, 0
	s_mov_b32 m0, s57
	s_nop 0
	global_load_lds_dwordx4 v131, s[4:5]
	s_mov_b32 m0, s69
	s_nop 0
	global_load_lds_dwordx4 v133, s[4:5]
	s_mov_b32 m0, s48
	s_nop 0
	global_load_lds_dwordx4 v130, s[34:35]
	s_mov_b32 m0, s49
	s_nop 0
	global_load_lds_dwordx4 v132, s[34:35]
	s_waitcnt vmcnt(8)
	s_waitcnt lgkmcnt(0)
	s_barrier
	s_setprio 1
	s_waitcnt lgkmcnt(0)
	v_mfma_f32_16x16x32_bf16 v[20:23], v[12:15], v[48:51], v[136:139]
	v_mfma_f32_16x16x32_bf16 v[92:95], v[16:19], v[56:59], v[20:23]
	v_mfma_f32_16x16x32_bf16 v[20:23], v[164:167], v[48:51], v[140:143]
	v_mfma_f32_16x16x32_bf16 v[84:87], v[188:191], v[56:59], v[20:23]
	v_mfma_f32_16x16x32_bf16 v[20:23], v[12:15], v[168:171], v[144:147]
	v_mfma_f32_16x16x32_bf16 v[60:63], v[16:19], v[172:175], v[20:23]
	v_mfma_f32_16x16x32_bf16 v[20:23], v[164:167], v[168:171], v[148:151]
	v_mfma_f32_16x16x32_bf16 v[52:55], v[188:191], v[172:175], v[20:23]
	v_mfma_f32_16x16x32_bf16 v[20:23], v[12:15], v[204:207], v[152:155]
	v_mfma_f32_16x16x32_bf16 v[0:3], v[12:15], v[236:239], v[0:3]
	v_mfma_f32_16x16x32_bf16 v[28:31], v[16:19], v[232:235], v[20:23]
	v_mfma_f32_16x16x32_bf16 v[20:23], v[164:167], v[204:207], v[156:159]
	v_mfma_f32_16x16x32_bf16 v[12:15], v[16:19], v[240:243], v[0:3]
	v_mfma_f32_16x16x32_bf16 v[0:3], v[164:167], v[236:239], v[4:7]
	v_mfma_f32_16x16x32_bf16 v[20:23], v[188:191], v[232:235], v[20:23]
	v_mfma_f32_16x16x32_bf16 v[4:7], v[188:191], v[240:243], v[0:3]
	s_setprio 0
	s_setprio 1
	v_mfma_f32_16x16x32_bf16 v[0:3], v[192:195], v[48:51], v[8:11]
	v_mfma_f32_16x16x32_bf16 v[88:91], v[220:223], v[56:59], v[0:3]
	v_mfma_f32_16x16x32_bf16 v[0:3], v[224:227], v[48:51], v[200:203]
	v_mfma_f32_16x16x32_bf16 v[80:83], v[228:231], v[56:59], v[0:3]
	v_mfma_f32_16x16x32_bf16 v[0:3], v[192:195], v[168:171], v[24:27]
	v_mfma_f32_16x16x32_bf16 v[56:59], v[220:223], v[172:175], v[0:3]
	v_mfma_f32_16x16x32_bf16 v[0:3], v[224:227], v[168:171], v[176:179]
	v_mfma_f32_16x16x32_bf16 v[48:51], v[228:231], v[172:175], v[0:3]
	v_mfma_f32_16x16x32_bf16 v[0:3], v[192:195], v[204:207], v[208:211]
	v_mfma_f32_16x16x32_bf16 v[24:27], v[220:223], v[232:235], v[0:3]
	v_mfma_f32_16x16x32_bf16 v[0:3], v[224:227], v[204:207], v[180:183]
	v_mfma_f32_16x16x32_bf16 v[16:19], v[228:231], v[232:235], v[0:3]
	v_mfma_f32_16x16x32_bf16 v[0:3], v[192:195], v[236:239], v[184:187]
	v_mfma_f32_16x16x32_bf16 v[8:11], v[220:223], v[240:243], v[0:3]
	v_mfma_f32_16x16x32_bf16 v[0:3], v[224:227], v[236:239], v[160:163]
	v_mfma_f32_16x16x32_bf16 v[0:3], v[228:231], v[240:243], v[0:3]
	s_setprio 0
	s_barrier
	s_andn2_b64 vcc, exec, s[60:61]
	s_cbranch_vccnz .LBB0_300
	s_barrier

.LBB0_313:
	s_ashr_i32 s15, s14, 31
	s_lshl_b64 s[4:5], s[14:15], 17
	s_add_u32 s20, s2, s4
	s_addc_u32 s21, s19, s5
	s_and_b64 s[4:5], s[16:17], exec
	s_cselect_b32 s39, s21, s31
	s_cselect_b32 s38, s20, s30
	s_ashr_i32 s11, s10, 31
	s_lshl_b64 s[4:5], s[10:11], 9
	s_add_u32 s11, s44, s4
	s_addc_u32 s15, s46, s5
	s_ashr_i32 s13, s12, 31
	s_lshl_b64 s[4:5], s[12:13], 20
	s_add_u32 s22, s11, s4
	s_addc_u32 s23, s15, s5
	s_and_b64 s[4:5], s[16:17], exec
	s_cselect_b32 s35, s23, s37
	s_cselect_b32 s34, s22, s36
	s_add_u32 s56, s30, 0x100
	s_addc_u32 s57, s31, 0
	s_add_u32 s82, s36, 0x100
	s_addc_u32 s83, s37, 0
	s_add_u32 s80, s30, 0x180
	s_addc_u32 s81, s31, 0
	s_add_i32 s4, 0, 0x10000
	s_add_i32 s13, 0, 0x14000
	v_add_u32_e32 v128, s4, v134
	v_add_u32_e32 v129, s13, v134
	ds_read_b128 v[0:3], v128
	ds_read_b128 v[4:7], v128 offset:1024
	ds_read_b128 v[8:11], v128 offset:2048
	ds_read_b128 v[12:15], v128 offset:3072
	ds_read_b128 v[16:19], v129
	ds_read_b128 v[20:23], v129 offset:1024
	ds_read_b128 v[24:27], v129 offset:2048
	ds_read_b128 v[28:31], v129 offset:3072
	s_add_u32 s70, s30, 0x10080
	s_addc_u32 s71, s31, 0
	s_add_i32 s5, s25, 0xc000
	s_mov_b32 m0, s5
	s_add_i32 s11, s25, 0xe000
	ds_read_b128 v[32:35], v135
	ds_read_b128 v[36:39], v135 offset:1024
	ds_read_b128 v[40:43], v135 offset:2048
	ds_read_b128 v[44:47], v135 offset:3072
	ds_read_b128 v[48:51], v135 offset:4096
	ds_read_b128 v[52:55], v135 offset:5120
	ds_read_b128 v[56:59], v135 offset:6144
	ds_read_b128 v[60:63], v135 offset:7168
	s_nop 0
	global_load_lds_dwordx4 v133, s[70:71]
	s_mov_b32 m0, s11
	s_nop 0
	global_load_lds_dwordx4 v131, s[70:71]
	s_waitcnt vmcnt(8)
	s_waitcnt lgkmcnt(0)
	s_barrier
	s_setprio 1
	s_waitcnt lgkmcnt(0)
	v_mfma_f32_16x16x32_bf16 v[64:67], v[0:3], v[32:35], 0
	v_mfma_f32_16x16x32_bf16 v[68:71], v[8:11], v[32:35], 0
	v_mfma_f32_16x16x32_bf16 v[72:75], v[0:3], v[40:43], 0
	v_mfma_f32_16x16x32_bf16 v[76:79], v[8:11], v[40:43], 0
	v_mfma_f32_16x16x32_bf16 v[80:83], v[0:3], v[48:51], 0
	v_mfma_f32_16x16x32_bf16 v[84:87], v[8:11], v[48:51], 0
	v_mfma_f32_16x16x32_bf16 v[88:91], v[0:3], v[56:59], 0
	v_mfma_f32_16x16x32_bf16 v[92:95], v[8:11], v[56:59], 0
	v_mfma_f32_16x16x32_bf16 v[64:67], v[4:7], v[36:39], v[64:67]
	v_mfma_f32_16x16x32_bf16 v[68:71], v[12:15], v[36:39], v[68:71]
	v_mfma_f32_16x16x32_bf16 v[72:75], v[4:7], v[44:47], v[72:75]
	v_mfma_f32_16x16x32_bf16 v[76:79], v[12:15], v[44:47], v[76:79]
	v_mfma_f32_16x16x32_bf16 v[80:83], v[4:7], v[52:55], v[80:83]
	v_mfma_f32_16x16x32_bf16 v[84:87], v[12:15], v[52:55], v[84:87]
	v_mfma_f32_16x16x32_bf16 v[88:91], v[4:7], v[60:63], v[88:91]
	v_mfma_f32_16x16x32_bf16 v[92:95], v[12:15], v[60:63], v[92:95]
	s_setprio 0
	s_setprio 1
	v_mfma_f32_16x16x32_bf16 v[96:99], v[16:19], v[32:35], 0
	v_mfma_f32_16x16x32_bf16 v[32:35], v[24:27], v[32:35], 0
	v_mfma_f32_16x16x32_bf16 v[96:99], v[20:23], v[36:39], v[96:99]
	v_mfma_f32_16x16x32_bf16 v[32:35], v[28:31], v[36:39], v[32:35]
	v_mfma_f32_16x16x32_bf16 v[36:39], v[16:19], v[40:43], 0
	v_mfma_f32_16x16x32_bf16 v[40:43], v[24:27], v[40:43], 0
	v_mfma_f32_16x16x32_bf16 v[36:39], v[20:23], v[44:47], v[36:39]
	v_mfma_f32_16x16x32_bf16 v[40:43], v[28:31], v[44:47], v[40:43]
	v_mfma_f32_16x16x32_bf16 v[44:47], v[16:19], v[48:51], 0
	v_mfma_f32_16x16x32_bf16 v[48:51], v[24:27], v[48:51], 0
	v_mfma_f32_16x16x32_bf16 v[44:47], v[20:23], v[52:55], v[44:47]
	v_mfma_f32_16x16x32_bf16 v[48:51], v[28:31], v[52:55], v[48:51]
	v_mfma_f32_16x16x32_bf16 v[52:55], v[16:19], v[56:59], 0
	v_mfma_f32_16x16x32_bf16 v[56:59], v[24:27], v[56:59], 0
	v_mfma_f32_16x16x32_bf16 v[52:55], v[20:23], v[60:63], v[52:55]
	v_mfma_f32_16x16x32_bf16 v[56:59], v[28:31], v[60:63], v[56:59]
	s_setprio 0
	s_barrier
	s_add_i32 s70, s4, s97
	s_add_i32 s4, s70, 0x2000
	s_mov_b32 m0, s70
	s_add_u32 s74, s36, 0x80100
	ds_read_b128 v[60:63], v135 offset:16384
	ds_read_b128 v[100:103], v135 offset:17408
	ds_read_b128 v[104:107], v135 offset:18432
	ds_read_b128 v[108:111], v135 offset:19456
	ds_read_b128 v[112:115], v135 offset:20480
	ds_read_b128 v[116:119], v135 offset:21504
	ds_read_b128 v[120:123], v135 offset:22528
	ds_read_b128 v[124:127], v135 offset:23552
	s_addc_u32 s75, s37, 0
	global_load_lds_dwordx4 v132, s[82:83]
	s_mov_b32 m0, s4
	s_add_i32 s13, s13, s97
	s_add_i32 s15, s13, 0x2000
	global_load_lds_dwordx4 v130, s[82:83]
	s_mov_b32 m0, s13
	s_nop 0
	global_load_lds_dwordx4 v132, s[74:75]
	s_mov_b32 m0, s15
	s_nop 0
	global_load_lds_dwordx4 v130, s[74:75]
	s_mov_b32 m0, s25
	s_nop 0
	global_load_lds_dwordx4 v133, s[56:57]
	s_mov_b32 m0, s27
	s_nop 0
	global_load_lds_dwordx4 v131, s[56:57]
	s_waitcnt vmcnt(8)
	s_waitcnt lgkmcnt(0)
	s_barrier
	s_setprio 1
	s_waitcnt lgkmcnt(0)
	v_mfma_f32_16x16x32_bf16 v[136:139], v[0:3], v[60:63], 0
	v_mfma_f32_16x16x32_bf16 v[144:147], v[0:3], v[104:107], 0
	v_mfma_f32_16x16x32_bf16 v[152:155], v[0:3], v[112:115], 0
	v_mfma_f32_16x16x32_bf16 v[0:3], v[0:3], v[120:123], 0
	v_mfma_f32_16x16x32_bf16 v[136:139], v[4:7], v[100:103], v[136:139]
	v_mfma_f32_16x16x32_bf16 v[144:147], v[4:7], v[108:111], v[144:147]
	v_mfma_f32_16x16x32_bf16 v[152:155], v[4:7], v[116:119], v[152:155]
	v_mfma_f32_16x16x32_bf16 v[0:3], v[4:7], v[124:127], v[0:3]
	v_mfma_f32_16x16x32_bf16 v[4:7], v[8:11], v[120:123], 0
	v_mfma_f32_16x16x32_bf16 v[140:143], v[8:11], v[60:63], 0
	v_mfma_f32_16x16x32_bf16 v[148:151], v[8:11], v[104:107], 0
	v_mfma_f32_16x16x32_bf16 v[156:159], v[8:11], v[112:115], 0
	v_mfma_f32_16x16x32_bf16 v[4:7], v[12:15], v[124:127], v[4:7]
	v_mfma_f32_16x16x32_bf16 v[140:143], v[12:15], v[100:103], v[140:143]
	v_mfma_f32_16x16x32_bf16 v[148:151], v[12:15], v[108:111], v[148:151]
	v_mfma_f32_16x16x32_bf16 v[156:159], v[12:15], v[116:119], v[156:159]
	s_setprio 0
	s_setprio 1
	v_mfma_f32_16x16x32_bf16 v[8:11], v[16:19], v[60:63], 0
	v_mfma_f32_16x16x32_bf16 v[12:15], v[24:27], v[60:63], 0
	v_mfma_f32_16x16x32_bf16 v[8:11], v[20:23], v[100:103], v[8:11]
	v_mfma_f32_16x16x32_bf16 v[12:15], v[28:31], v[100:103], v[12:15]
	v_mfma_f32_16x16x32_bf16 v[60:63], v[16:19], v[104:107], 0
	v_mfma_f32_16x16x32_bf16 v[100:103], v[24:27], v[104:107], 0
	v_mfma_f32_16x16x32_bf16 v[104:107], v[16:19], v[112:115], 0
	v_mfma_f32_16x16x32_bf16 v[16:19], v[16:19], v[120:123], 0
	v_mfma_f32_16x16x32_bf16 v[60:63], v[20:23], v[108:111], v[60:63]
	v_mfma_f32_16x16x32_bf16 v[100:103], v[28:31], v[108:111], v[100:103]
	v_mfma_f32_16x16x32_bf16 v[104:107], v[20:23], v[116:119], v[104:107]
	v_mfma_f32_16x16x32_bf16 v[108:111], v[24:27], v[112:115], 0
	v_mfma_f32_16x16x32_bf16 v[16:19], v[20:23], v[124:127], v[16:19]
	v_mfma_f32_16x16x32_bf16 v[20:23], v[24:27], v[120:123], 0
	v_mfma_f32_16x16x32_bf16 v[108:111], v[28:31], v[116:119], v[108:111]
	v_mfma_f32_16x16x32_bf16 v[20:23], v[28:31], v[124:127], v[20:23]
	s_setprio 0
	s_barrier
	s_add_i32 s71, 0, 0x18000
	s_add_i32 s69, 0, 0x1c000
	v_add_u32_e32 v196, s71, v134
	v_add_u32_e32 v198, s69, v134
	ds_read_b128 v[24:27], v196
	ds_read_b128 v[28:31], v196 offset:1024
	ds_read_b128 v[112:115], v196 offset:2048
	ds_read_b128 v[116:119], v196 offset:3072
	ds_read_b128 v[120:123], v198
	ds_read_b128 v[124:127], v198 offset:1024
	ds_read_b128 v[160:163], v198 offset:2048
	ds_read_b128 v[164:167], v198 offset:3072
	s_add_u32 s56, s30, 0x10100
	s_addc_u32 s57, s31, 0
	s_mov_b32 m0, s29
	ds_read_b128 v[168:171], v135 offset:32768
	ds_read_b128 v[172:175], v135 offset:33792
	ds_read_b128 v[176:179], v135 offset:34816
	ds_read_b128 v[180:183], v135 offset:35840
	ds_read_b128 v[184:187], v135 offset:36864
	ds_read_b128 v[188:191], v135 offset:37888
	ds_read_b128 v[192:195], v135 offset:38912
	ds_read_b128 v[200:203], v135 offset:39936
	s_nop 0
	global_load_lds_dwordx4 v133, s[56:57]
	s_mov_b32 m0, s47
	s_nop 0
	global_load_lds_dwordx4 v131, s[56:57]
	s_waitcnt vmcnt(8)
	s_waitcnt lgkmcnt(0)
	s_barrier
	s_setprio 1
	s_waitcnt lgkmcnt(0)
	v_mfma_f32_16x16x32_bf16 v[64:67], v[24:27], v[168:171], v[64:67]
	v_mfma_f32_16x16x32_bf16 v[64:67], v[28:31], v[172:175], v[64:67]
	v_mfma_f32_16x16x32_bf16 v[68:71], v[112:115], v[168:171], v[68:71]
	v_mfma_f32_16x16x32_bf16 v[68:71], v[116:119], v[172:175], v[68:71]
	v_mfma_f32_16x16x32_bf16 v[72:75], v[24:27], v[176:179], v[72:75]
	v_mfma_f32_16x16x32_bf16 v[72:75], v[28:31], v[180:183], v[72:75]
	v_mfma_f32_16x16x32_bf16 v[76:79], v[112:115], v[176:179], v[76:79]
	v_mfma_f32_16x16x32_bf16 v[76:79], v[116:119], v[180:183], v[76:79]
	v_mfma_f32_16x16x32_bf16 v[80:83], v[24:27], v[184:187], v[80:83]
	v_mfma_f32_16x16x32_bf16 v[80:83], v[28:31], v[188:191], v[80:83]
	v_mfma_f32_16x16x32_bf16 v[84:87], v[112:115], v[184:187], v[84:87]
	v_mfma_f32_16x16x32_bf16 v[84:87], v[116:119], v[188:191], v[84:87]
	v_mfma_f32_16x16x32_bf16 v[88:91], v[24:27], v[192:195], v[88:91]
	v_mfma_f32_16x16x32_bf16 v[88:91], v[28:31], v[200:203], v[88:91]
	v_mfma_f32_16x16x32_bf16 v[92:95], v[112:115], v[192:195], v[92:95]
	v_mfma_f32_16x16x32_bf16 v[92:95], v[116:119], v[200:203], v[92:95]
	s_setprio 0
	s_setprio 1
	v_mfma_f32_16x16x32_bf16 v[96:99], v[120:123], v[168:171], v[96:99]
	v_mfma_f32_16x16x32_bf16 v[96:99], v[124:127], v[172:175], v[96:99]
	v_mfma_f32_16x16x32_bf16 v[32:35], v[160:163], v[168:171], v[32:35]
	v_mfma_f32_16x16x32_bf16 v[32:35], v[164:167], v[172:175], v[32:35]
	v_mfma_f32_16x16x32_bf16 v[36:39], v[120:123], v[176:179], v[36:39]
	v_mfma_f32_16x16x32_bf16 v[36:39], v[124:127], v[180:183], v[36:39]
	v_mfma_f32_16x16x32_bf16 v[40:43], v[160:163], v[176:179], v[40:43]
	v_mfma_f32_16x16x32_bf16 v[40:43], v[164:167], v[180:183], v[40:43]
	v_mfma_f32_16x16x32_bf16 v[44:47], v[120:123], v[184:187], v[44:47]
	v_mfma_f32_16x16x32_bf16 v[44:47], v[124:127], v[188:191], v[44:47]
	v_mfma_f32_16x16x32_bf16 v[48:51], v[160:163], v[184:187], v[48:51]
	v_mfma_f32_16x16x32_bf16 v[48:51], v[164:167], v[188:191], v[48:51]
	v_mfma_f32_16x16x32_bf16 v[52:55], v[120:123], v[192:195], v[52:55]
	v_mfma_f32_16x16x32_bf16 v[52:55], v[124:127], v[200:203], v[52:55]
	v_mfma_f32_16x16x32_bf16 v[56:59], v[160:163], v[192:195], v[56:59]
	v_mfma_f32_16x16x32_bf16 v[56:59], v[164:167], v[200:203], v[56:59]
	s_setprio 0
	s_barrier
	s_add_u32 s74, s36, 0x180
	s_addc_u32 s75, s37, 0
	s_add_i32 s71, s71, s97
	s_add_i32 s56, s71, 0x2000
	s_mov_b32 m0, s71
	s_add_u32 s36, s36, 0x80180
	ds_read_b128 v[168:171], v135 offset:49152
	ds_read_b128 v[172:175], v135 offset:50176
	ds_read_b128 v[176:179], v135 offset:51200
	ds_read_b128 v[180:183], v135 offset:52224
	ds_read_b128 v[184:187], v135 offset:53248
	ds_read_b128 v[188:191], v135 offset:54272
	ds_read_b128 v[192:195], v135 offset:55296
	ds_read_b128 v[200:203], v135 offset:56320
	s_addc_u32 s37, s37, 0
	global_load_lds_dwordx4 v132, s[74:75]
	s_mov_b32 m0, s56
	s_add_i32 s57, s69, s97
	s_add_i32 s69, s57, 0x2000
	global_load_lds_dwordx4 v130, s[74:75]
	s_mov_b32 m0, s57
	s_nop 0
	global_load_lds_dwordx4 v132, s[36:37]
	s_mov_b32 m0, s69
	s_nop 0
	global_load_lds_dwordx4 v130, s[36:37]
	s_mov_b32 m0, s48
	s_nop 0
	global_load_lds_dwordx4 v133, s[80:81]
	s_mov_b32 m0, s49
	s_nop 0
	global_load_lds_dwordx4 v131, s[80:81]
	s_waitcnt vmcnt(8)
	s_waitcnt lgkmcnt(0)
	s_barrier
	s_setprio 1
	s_waitcnt lgkmcnt(0)
	v_mfma_f32_16x16x32_bf16 v[0:3], v[24:27], v[192:195], v[0:3]
	v_mfma_f32_16x16x32_bf16 v[0:3], v[28:31], v[200:203], v[0:3]
	v_mfma_f32_16x16x32_bf16 v[4:7], v[112:115], v[192:195], v[4:7]
	v_mfma_f32_16x16x32_bf16 v[4:7], v[116:119], v[200:203], v[4:7]
	v_mfma_f32_16x16x32_bf16 v[136:139], v[24:27], v[168:171], v[136:139]
	v_mfma_f32_16x16x32_bf16 v[136:139], v[28:31], v[172:175], v[136:139]
	v_mfma_f32_16x16x32_bf16 v[140:143], v[112:115], v[168:171], v[140:143]
	v_mfma_f32_16x16x32_bf16 v[140:143], v[116:119], v[172:175], v[140:143]
	v_mfma_f32_16x16x32_bf16 v[144:147], v[24:27], v[176:179], v[144:147]
	v_mfma_f32_16x16x32_bf16 v[144:147], v[28:31], v[180:183], v[144:147]
	v_mfma_f32_16x16x32_bf16 v[148:151], v[112:115], v[176:179], v[148:151]
	v_mfma_f32_16x16x32_bf16 v[148:151], v[116:119], v[180:183], v[148:151]
	v_mfma_f32_16x16x32_bf16 v[152:155], v[24:27], v[184:187], v[152:155]
	v_mfma_f32_16x16x32_bf16 v[152:155], v[28:31], v[188:191], v[152:155]
	v_mfma_f32_16x16x32_bf16 v[156:159], v[112:115], v[184:187], v[156:159]
	v_mfma_f32_16x16x32_bf16 v[156:159], v[116:119], v[188:191], v[156:159]
	s_setprio 0
	s_setprio 1
	v_mfma_f32_16x16x32_bf16 v[8:11], v[120:123], v[168:171], v[8:11]
	v_mfma_f32_16x16x32_bf16 v[12:15], v[160:163], v[168:171], v[12:15]
	v_mfma_f32_16x16x32_bf16 v[24:27], v[120:123], v[176:179], v[60:63]
	v_mfma_f32_16x16x32_bf16 v[28:31], v[160:163], v[176:179], v[100:103]
	v_mfma_f32_16x16x32_bf16 v[60:63], v[120:123], v[184:187], v[104:107]
	v_mfma_f32_16x16x32_bf16 v[100:103], v[160:163], v[184:187], v[108:111]
	v_mfma_f32_16x16x32_bf16 v[16:19], v[120:123], v[192:195], v[16:19]
	v_mfma_f32_16x16x32_bf16 v[20:23], v[160:163], v[192:195], v[20:23]
	v_mfma_f32_16x16x32_bf16 v[8:11], v[124:127], v[172:175], v[8:11]
	v_mfma_f32_16x16x32_bf16 v[12:15], v[164:167], v[172:175], v[12:15]
	v_mfma_f32_16x16x32_bf16 v[24:27], v[124:127], v[180:183], v[24:27]
	v_mfma_f32_16x16x32_bf16 v[28:31], v[164:167], v[180:183], v[28:31]
	v_mfma_f32_16x16x32_bf16 v[60:63], v[124:127], v[188:191], v[60:63]
	v_mfma_f32_16x16x32_bf16 v[100:103], v[164:167], v[188:191], v[100:103]
	v_mfma_f32_16x16x32_bf16 v[16:19], v[124:127], v[200:203], v[16:19]
	v_mfma_f32_16x16x32_bf16 v[20:23], v[164:167], v[200:203], v[20:23]
	s_setprio 0
	s_barrier
	ds_read_b128 v[104:107], v128
	ds_read_b128 v[108:111], v128 offset:1024
	ds_read_b128 v[112:115], v128 offset:2048
	ds_read_b128 v[116:119], v128 offset:3072
	ds_read_b128 v[120:123], v129
	ds_read_b128 v[124:127], v129 offset:1024
	ds_read_b128 v[160:163], v129 offset:2048
	ds_read_b128 v[164:167], v129 offset:3072
	s_add_u32 s36, s38, 0x80
	s_addc_u32 s37, s39, 0
	s_add_u32 s30, s30, 0x10180
	s_addc_u32 s31, s31, 0
	s_mov_b32 m0, s5
	ds_read_b128 v[168:171], v135
	ds_read_b128 v[172:175], v135 offset:1024
	ds_read_b128 v[176:179], v135 offset:2048
	ds_read_b128 v[180:183], v135 offset:3072
	ds_read_b128 v[184:187], v135 offset:4096
	ds_read_b128 v[188:191], v135 offset:5120
	ds_read_b128 v[192:195], v135 offset:6144
	ds_read_b128 v[200:203], v135 offset:7168
	s_nop 0
	global_load_lds_dwordx4 v133, s[30:31]
	s_mov_b32 m0, s11
	s_nop 0
	global_load_lds_dwordx4 v131, s[30:31]
	s_waitcnt vmcnt(8)
	s_waitcnt lgkmcnt(0)
	s_barrier
	s_setprio 1
	s_waitcnt lgkmcnt(0)
	v_mfma_f32_16x16x32_bf16 v[64:67], v[104:107], v[168:171], v[64:67]
	v_mfma_f32_16x16x32_bf16 v[64:67], v[108:111], v[172:175], v[64:67]
	v_mfma_f32_16x16x32_bf16 v[68:71], v[112:115], v[168:171], v[68:71]
	v_mfma_f32_16x16x32_bf16 v[68:71], v[116:119], v[172:175], v[68:71]
	v_mfma_f32_16x16x32_bf16 v[72:75], v[104:107], v[176:179], v[72:75]
	v_mfma_f32_16x16x32_bf16 v[72:75], v[108:111], v[180:183], v[72:75]
	v_mfma_f32_16x16x32_bf16 v[76:79], v[112:115], v[176:179], v[76:79]
	v_mfma_f32_16x16x32_bf16 v[76:79], v[116:119], v[180:183], v[76:79]
	v_mfma_f32_16x16x32_bf16 v[80:83], v[104:107], v[184:187], v[80:83]
	v_mfma_f32_16x16x32_bf16 v[80:83], v[108:111], v[188:191], v[80:83]
	v_mfma_f32_16x16x32_bf16 v[84:87], v[112:115], v[184:187], v[84:87]
	v_mfma_f32_16x16x32_bf16 v[84:87], v[116:119], v[188:191], v[84:87]
	v_mfma_f32_16x16x32_bf16 v[88:91], v[104:107], v[192:195], v[88:91]
	v_mfma_f32_16x16x32_bf16 v[88:91], v[108:111], v[200:203], v[88:91]
	v_mfma_f32_16x16x32_bf16 v[92:95], v[112:115], v[192:195], v[92:95]
	v_mfma_f32_16x16x32_bf16 v[92:95], v[116:119], v[200:203], v[92:95]
	s_setprio 0
	s_setprio 1
	v_mfma_f32_16x16x32_bf16 v[32:35], v[160:163], v[168:171], v[32:35]
	v_mfma_f32_16x16x32_bf16 v[96:99], v[120:123], v[168:171], v[96:99]
	v_mfma_f32_16x16x32_bf16 v[168:171], v[164:167], v[172:175], v[32:35]
	v_mfma_f32_16x16x32_bf16 v[32:35], v[120:123], v[176:179], v[36:39]
	v_mfma_f32_16x16x32_bf16 v[36:39], v[124:127], v[180:183], v[32:35]
	v_mfma_f32_16x16x32_bf16 v[32:35], v[160:163], v[176:179], v[40:43]
	v_mfma_f32_16x16x32_bf16 v[204:207], v[124:127], v[172:175], v[96:99]
	v_mfma_f32_16x16x32_bf16 v[172:175], v[164:167], v[180:183], v[32:35]
	v_mfma_f32_16x16x32_bf16 v[32:35], v[120:123], v[184:187], v[44:47]
	v_mfma_f32_16x16x32_bf16 v[44:47], v[124:127], v[188:191], v[32:35]
	v_mfma_f32_16x16x32_bf16 v[32:35], v[160:163], v[184:187], v[48:51]
	v_mfma_f32_16x16x32_bf16 v[48:51], v[164:167], v[188:191], v[32:35]
	v_mfma_f32_16x16x32_bf16 v[32:35], v[120:123], v[192:195], v[52:55]
	v_mfma_f32_16x16x32_bf16 v[52:55], v[124:127], v[200:203], v[32:35]
	v_mfma_f32_16x16x32_bf16 v[32:35], v[160:163], v[192:195], v[56:59]
	v_mfma_f32_16x16x32_bf16 v[56:59], v[164:167], v[200:203], v[32:35]
	s_setprio 0
	s_barrier
	s_mov_b32 m0, s70
	s_mov_b64 s[30:31], s[34:35]
	s_nop 2
	ds_read_b128 v[32:35], v135 offset:16384
	ds_read_b128 v[40:43], v135 offset:17408
	ds_read_b128 v[96:99], v135 offset:18432
	ds_read_b128 v[176:179], v135 offset:19456
	ds_read_b128 v[180:183], v135 offset:20480
	ds_read_b128 v[184:187], v135 offset:21504
	ds_read_b128 v[188:191], v135 offset:22528
	ds_read_b128 v[192:195], v135 offset:23552
	s_nop 0
	global_load_lds_dwordx4 v132, s[30:31]
	s_mov_b32 m0, s4
	s_add_u32 s4, s34, 0x80000
	s_addc_u32 s5, s35, 0
	global_load_lds_dwordx4 v130, s[30:31]
	s_mov_b32 m0, s13
	s_nop 0
	global_load_lds_dwordx4 v132, s[4:5]
	s_mov_b32 m0, s15
	s_nop 0
	global_load_lds_dwordx4 v130, s[4:5]
	s_mov_b64 s[4:5], s[38:39]
	s_mov_b32 m0, s25
	s_nop 0
	global_load_lds_dwordx4 v133, s[4:5]
	s_mov_b32 m0, s27
	s_nop 0
	global_load_lds_dwordx4 v131, s[4:5]
	s_waitcnt vmcnt(8)
	s_waitcnt lgkmcnt(0)
	s_barrier
	s_setprio 1
	s_waitcnt lgkmcnt(0)
	v_mfma_f32_16x16x32_bf16 v[0:3], v[104:107], v[188:191], v[0:3]
	v_mfma_f32_16x16x32_bf16 v[0:3], v[108:111], v[192:195], v[0:3]
	v_mfma_f32_16x16x32_bf16 v[4:7], v[112:115], v[188:191], v[4:7]
	v_mfma_f32_16x16x32_bf16 v[4:7], v[116:119], v[192:195], v[4:7]
	v_mfma_f32_16x16x32_bf16 v[136:139], v[104:107], v[32:35], v[136:139]
	v_mfma_f32_16x16x32_bf16 v[136:139], v[108:111], v[40:43], v[136:139]
	v_mfma_f32_16x16x32_bf16 v[140:143], v[112:115], v[32:35], v[140:143]
	v_mfma_f32_16x16x32_bf16 v[140:143], v[116:119], v[40:43], v[140:143]
	v_mfma_f32_16x16x32_bf16 v[144:147], v[104:107], v[96:99], v[144:147]
	v_mfma_f32_16x16x32_bf16 v[144:147], v[108:111], v[176:179], v[144:147]
	v_mfma_f32_16x16x32_bf16 v[148:151], v[112:115], v[96:99], v[148:151]
	v_mfma_f32_16x16x32_bf16 v[148:151], v[116:119], v[176:179], v[148:151]
	v_mfma_f32_16x16x32_bf16 v[152:155], v[104:107], v[180:183], v[152:155]
	v_mfma_f32_16x16x32_bf16 v[152:155], v[108:111], v[184:187], v[152:155]
	v_mfma_f32_16x16x32_bf16 v[156:159], v[112:115], v[180:183], v[156:159]
	v_mfma_f32_16x16x32_bf16 v[156:159], v[116:119], v[184:187], v[156:159]
	s_setprio 0
	s_setprio 1
	v_mfma_f32_16x16x32_bf16 v[12:15], v[160:163], v[32:35], v[12:15]
	v_mfma_f32_16x16x32_bf16 v[200:203], v[164:167], v[40:43], v[12:15]
	v_mfma_f32_16x16x32_bf16 v[12:15], v[120:123], v[96:99], v[24:27]
	v_mfma_f32_16x16x32_bf16 v[24:27], v[124:127], v[176:179], v[12:15]
	v_mfma_f32_16x16x32_bf16 v[12:15], v[160:163], v[96:99], v[28:31]
	v_mfma_f32_16x16x32_bf16 v[176:179], v[164:167], v[176:179], v[12:15]
	v_mfma_f32_16x16x32_bf16 v[12:15], v[120:123], v[180:183], v[60:63]
	v_mfma_f32_16x16x32_bf16 v[208:211], v[124:127], v[184:187], v[12:15]
	v_mfma_f32_16x16x32_bf16 v[12:15], v[160:163], v[180:183], v[100:103]
	v_mfma_f32_16x16x32_bf16 v[8:11], v[120:123], v[32:35], v[8:11]
	v_mfma_f32_16x16x32_bf16 v[180:183], v[164:167], v[184:187], v[12:15]
	v_mfma_f32_16x16x32_bf16 v[12:15], v[120:123], v[188:191], v[16:19]
	v_mfma_f32_16x16x32_bf16 v[8:11], v[124:127], v[40:43], v[8:11]
	v_mfma_f32_16x16x32_bf16 v[184:187], v[124:127], v[192:195], v[12:15]
	v_mfma_f32_16x16x32_bf16 v[12:15], v[160:163], v[188:191], v[20:23]
	v_mfma_f32_16x16x32_bf16 v[160:163], v[164:167], v[192:195], v[12:15]
	s_setprio 0
	s_barrier
	s_nop 4
	ds_read_b128 v[12:15], v196
	ds_read_b128 v[16:19], v196 offset:1024
	ds_read_b128 v[164:167], v196 offset:2048
	ds_read_b128 v[188:191], v196 offset:3072
	ds_read_b128 v[192:195], v198
	ds_read_b128 v[220:223], v198 offset:1024
	ds_read_b128 v[224:227], v198 offset:2048
	ds_read_b128 v[228:231], v198 offset:3072
	s_add_u32 s4, s38, 0x10000
	s_addc_u32 s5, s39, 0
	s_mov_b32 m0, s29
	ds_read_b128 v[20:23], v135 offset:32768
	ds_read_b128 v[28:31], v135 offset:33792
	ds_read_b128 v[60:63], v135 offset:34816
	ds_read_b128 v[100:103], v135 offset:35840
	ds_read_b128 v[232:235], v135 offset:36864
	ds_read_b128 v[236:239], v135 offset:37888
	ds_read_b128 v[240:243], v135 offset:38912
	ds_read_b128 v[244:247], v135 offset:39936
	s_nop 0
	global_load_lds_dwordx4 v133, s[4:5]
	s_mov_b32 m0, s47
	s_nop 0
	global_load_lds_dwordx4 v131, s[4:5]
	s_waitcnt vmcnt(8)
	s_waitcnt lgkmcnt(0)
	s_barrier
	s_setprio 1
	s_waitcnt lgkmcnt(0)
	v_mfma_f32_16x16x32_bf16 v[32:35], v[12:15], v[20:23], v[64:67]
	v_mfma_f32_16x16x32_bf16 v[120:123], v[16:19], v[28:31], v[32:35]
	v_mfma_f32_16x16x32_bf16 v[32:35], v[164:167], v[20:23], v[68:71]
	v_mfma_f32_16x16x32_bf16 v[112:115], v[188:191], v[28:31], v[32:35]
	v_mfma_f32_16x16x32_bf16 v[32:35], v[12:15], v[60:63], v[72:75]
	v_mfma_f32_16x16x32_bf16 v[104:107], v[16:19], v[100:103], v[32:35]
	v_mfma_f32_16x16x32_bf16 v[32:35], v[164:167], v[60:63], v[76:79]
	v_mfma_f32_16x16x32_bf16 v[96:99], v[188:191], v[100:103], v[32:35]
	v_mfma_f32_16x16x32_bf16 v[32:35], v[12:15], v[232:235], v[80:83]
	v_mfma_f32_16x16x32_bf16 v[72:75], v[16:19], v[236:239], v[32:35]
	v_mfma_f32_16x16x32_bf16 v[32:35], v[164:167], v[232:235], v[84:87]
	v_mfma_f32_16x16x32_bf16 v[64:67], v[188:191], v[236:239], v[32:35]
	v_mfma_f32_16x16x32_bf16 v[32:35], v[12:15], v[240:243], v[88:91]
	v_mfma_f32_16x16x32_bf16 v[40:43], v[16:19], v[244:247], v[32:35]
	v_mfma_f32_16x16x32_bf16 v[32:35], v[164:167], v[240:243], v[92:95]
	v_mfma_f32_16x16x32_bf16 v[32:35], v[188:191], v[244:247], v[32:35]
	s_setprio 0
	s_setprio 1
	v_mfma_f32_16x16x32_bf16 v[68:71], v[192:195], v[20:23], v[204:207]
	v_mfma_f32_16x16x32_bf16 v[20:23], v[224:227], v[20:23], v[168:171]
	v_mfma_f32_16x16x32_bf16 v[116:119], v[228:231], v[28:31], v[20:23]
	v_mfma_f32_16x16x32_bf16 v[20:23], v[192:195], v[60:63], v[36:39]
	v_mfma_f32_16x16x32_bf16 v[108:111], v[220:223], v[100:103], v[20:23]
	v_mfma_f32_16x16x32_bf16 v[20:23], v[224:227], v[60:63], v[172:175]
	v_mfma_f32_16x16x32_bf16 v[100:103], v[228:231], v[100:103], v[20:23]
	v_mfma_f32_16x16x32_bf16 v[20:23], v[192:195], v[232:235], v[44:47]
	v_mfma_f32_16x16x32_bf16 v[76:79], v[220:223], v[236:239], v[20:23]
	v_mfma_f32_16x16x32_bf16 v[20:23], v[224:227], v[232:235], v[48:51]
	v_mfma_f32_16x16x32_bf16 v[124:127], v[220:223], v[28:31], v[68:71]
	v_mfma_f32_16x16x32_bf16 v[68:71], v[228:231], v[236:239], v[20:23]
	v_mfma_f32_16x16x32_bf16 v[20:23], v[192:195], v[240:243], v[52:55]
	v_mfma_f32_16x16x32_bf16 v[44:47], v[220:223], v[244:247], v[20:23]
	v_mfma_f32_16x16x32_bf16 v[20:23], v[224:227], v[240:243], v[56:59]
	v_mfma_f32_16x16x32_bf16 v[36:39], v[228:231], v[244:247], v[20:23]
	s_setprio 0
	s_barrier
	s_add_u32 s4, s34, 0x80
	s_mov_b32 m0, s71
	s_addc_u32 s5, s35, 0
	ds_read_b128 v[48:51], v135 offset:49152
	ds_read_b128 v[56:59], v135 offset:50176
	ds_read_b128 v[168:171], v135 offset:51200
	ds_read_b128 v[172:175], v135 offset:52224
	ds_read_b128 v[204:207], v135 offset:53248
	ds_read_b128 v[232:235], v135 offset:54272
	ds_read_b128 v[236:239], v135 offset:55296
	ds_read_b128 v[240:243], v135 offset:56320
	s_nop 0
	global_load_lds_dwordx4 v132, s[4:5]
	s_mov_b32 m0, s56
	s_nop 0
	global_load_lds_dwordx4 v130, s[4:5]
	s_add_u32 s4, s34, 0x80080
	s_addc_u32 s5, s35, 0
	s_mov_b32 m0, s57
	s_nop 0
	global_load_lds_dwordx4 v132, s[4:5]
	s_mov_b32 m0, s69
	s_nop 0
	global_load_lds_dwordx4 v130, s[4:5]
	s_mov_b32 m0, s48
	s_nop 0
	global_load_lds_dwordx4 v133, s[36:37]
	s_mov_b32 m0, s49
	s_nop 0
	global_load_lds_dwordx4 v131, s[36:37]
	s_waitcnt vmcnt(8)
	s_waitcnt lgkmcnt(0)
	s_barrier
	s_setprio 1
	s_waitcnt lgkmcnt(0)
	v_mfma_f32_16x16x32_bf16 v[20:23], v[12:15], v[48:51], v[136:139]
	v_mfma_f32_16x16x32_bf16 v[92:95], v[16:19], v[56:59], v[20:23]
	v_mfma_f32_16x16x32_bf16 v[20:23], v[164:167], v[48:51], v[140:143]
	v_mfma_f32_16x16x32_bf16 v[84:87], v[188:191], v[56:59], v[20:23]
	v_mfma_f32_16x16x32_bf16 v[20:23], v[12:15], v[168:171], v[144:147]
	v_mfma_f32_16x16x32_bf16 v[60:63], v[16:19], v[172:175], v[20:23]
	v_mfma_f32_16x16x32_bf16 v[20:23], v[164:167], v[168:171], v[148:151]
	v_mfma_f32_16x16x32_bf16 v[52:55], v[188:191], v[172:175], v[20:23]
	v_mfma_f32_16x16x32_bf16 v[20:23], v[12:15], v[204:207], v[152:155]
	v_mfma_f32_16x16x32_bf16 v[0:3], v[12:15], v[236:239], v[0:3]
	v_mfma_f32_16x16x32_bf16 v[28:31], v[16:19], v[232:235], v[20:23]
	v_mfma_f32_16x16x32_bf16 v[20:23], v[164:167], v[204:207], v[156:159]
	v_mfma_f32_16x16x32_bf16 v[12:15], v[16:19], v[240:243], v[0:3]
	v_mfma_f32_16x16x32_bf16 v[0:3], v[164:167], v[236:239], v[4:7]
	v_mfma_f32_16x16x32_bf16 v[20:23], v[188:191], v[232:235], v[20:23]
	v_mfma_f32_16x16x32_bf16 v[4:7], v[188:191], v[240:243], v[0:3]
	s_setprio 0
	s_setprio 1
	v_mfma_f32_16x16x32_bf16 v[0:3], v[192:195], v[48:51], v[8:11]
	v_mfma_f32_16x16x32_bf16 v[88:91], v[220:223], v[56:59], v[0:3]
	v_mfma_f32_16x16x32_bf16 v[0:3], v[224:227], v[48:51], v[200:203]
	v_mfma_f32_16x16x32_bf16 v[80:83], v[228:231], v[56:59], v[0:3]
	v_mfma_f32_16x16x32_bf16 v[0:3], v[192:195], v[168:171], v[24:27]
	v_mfma_f32_16x16x32_bf16 v[56:59], v[220:223], v[172:175], v[0:3]
	v_mfma_f32_16x16x32_bf16 v[0:3], v[224:227], v[168:171], v[176:179]
	v_mfma_f32_16x16x32_bf16 v[48:51], v[228:231], v[172:175], v[0:3]
	v_mfma_f32_16x16x32_bf16 v[0:3], v[192:195], v[204:207], v[208:211]
	v_mfma_f32_16x16x32_bf16 v[24:27], v[220:223], v[232:235], v[0:3]
	v_mfma_f32_16x16x32_bf16 v[0:3], v[224:227], v[204:207], v[180:183]
	v_mfma_f32_16x16x32_bf16 v[16:19], v[228:231], v[232:235], v[0:3]
	v_mfma_f32_16x16x32_bf16 v[0:3], v[192:195], v[236:239], v[184:187]
	v_mfma_f32_16x16x32_bf16 v[8:11], v[220:223], v[240:243], v[0:3]
	v_mfma_f32_16x16x32_bf16 v[0:3], v[224:227], v[236:239], v[160:163]
	v_mfma_f32_16x16x32_bf16 v[0:3], v[228:231], v[240:243], v[0:3]
	s_setprio 0
	s_barrier
	s_andn2_b64 vcc, exec, s[60:61]
	s_cbranch_vccnz .LBB0_315
	s_barrier

.LBB0_380:
	s_cmp_eq_u32 s15, 28
	s_cselect_b32 s36, s20, s4
	s_cselect_b32 s37, s21, s5
	s_cselect_b32 s34, s26, s11
	s_cselect_b32 s35, s27, s13
	s_add_u32 s30, s36, 0x80
	s_addc_u32 s31, s37, 0
	s_add_i32 s17, 0, 0x10000
	v_add_u32_e32 v128, s17, v134
	s_add_i32 s69, 0, 0x14000
	ds_read_b128 v[136:139], v128
	ds_read_b128 v[140:143], v128 offset:1024
	ds_read_b128 v[144:147], v128 offset:2048
	ds_read_b128 v[148:151], v128 offset:3072
	v_add_u32_e32 v128, s69, v134
	ds_read_b128 v[152:155], v128
	ds_read_b128 v[156:159], v128 offset:1024
	ds_read_b128 v[160:163], v128 offset:2048
	ds_read_b128 v[164:167], v128 offset:3072
	s_mov_b64 s[70:71], s[28:29]
	s_add_i32 m0, s23, 0xc000
	ds_read_b128 v[168:171], v135
	ds_read_b128 v[172:175], v135 offset:1024
	ds_read_b128 v[176:179], v135 offset:2048
	ds_read_b128 v[180:183], v135 offset:3072
	ds_read_b128 v[184:187], v135 offset:4096
	ds_read_b128 v[188:191], v135 offset:5120
	ds_read_b128 v[192:195], v135 offset:6144
	ds_read_b128 v[200:203], v135 offset:7168
	s_nop 0
	global_load_lds_dwordx4 v133, s[70:71]
	s_add_i32 m0, s23, 0xe000
	s_nop 0
	global_load_lds_dwordx4 v131, s[70:71]
	s_waitcnt vmcnt(8)
	s_waitcnt lgkmcnt(0)
	s_barrier
	s_setprio 1
	s_waitcnt lgkmcnt(0)
	v_mfma_f32_16x16x32_bf16 v[124:127], v[136:139], v[168:171], v[124:127]
	v_mfma_f32_16x16x32_bf16 v[124:127], v[140:143], v[172:175], v[124:127]
	v_mfma_f32_16x16x32_bf16 v[120:123], v[144:147], v[168:171], v[120:123]
	v_mfma_f32_16x16x32_bf16 v[120:123], v[148:151], v[172:175], v[120:123]
	v_mfma_f32_16x16x32_bf16 v[116:119], v[136:139], v[176:179], v[116:119]
	v_mfma_f32_16x16x32_bf16 v[116:119], v[140:143], v[180:183], v[116:119]
	v_mfma_f32_16x16x32_bf16 v[108:111], v[144:147], v[176:179], v[108:111]
	v_mfma_f32_16x16x32_bf16 v[108:111], v[148:151], v[180:183], v[108:111]
	v_mfma_f32_16x16x32_bf16 v[100:103], v[136:139], v[184:187], v[100:103]
	v_mfma_f32_16x16x32_bf16 v[100:103], v[140:143], v[188:191], v[100:103]
	v_mfma_f32_16x16x32_bf16 v[92:95], v[144:147], v[184:187], v[92:95]
	v_mfma_f32_16x16x32_bf16 v[92:95], v[148:151], v[188:191], v[92:95]
	v_mfma_f32_16x16x32_bf16 v[84:87], v[136:139], v[192:195], v[84:87]
	v_mfma_f32_16x16x32_bf16 v[84:87], v[140:143], v[200:203], v[84:87]
	v_mfma_f32_16x16x32_bf16 v[76:79], v[144:147], v[192:195], v[76:79]
	v_mfma_f32_16x16x32_bf16 v[76:79], v[148:151], v[200:203], v[76:79]
	s_setprio 0
	s_setprio 1
	v_mfma_f32_16x16x32_bf16 v[112:115], v[152:155], v[168:171], v[112:115]
	v_mfma_f32_16x16x32_bf16 v[112:115], v[156:159], v[172:175], v[112:115]
	v_mfma_f32_16x16x32_bf16 v[104:107], v[160:163], v[168:171], v[104:107]
	v_mfma_f32_16x16x32_bf16 v[104:107], v[164:167], v[172:175], v[104:107]
	v_mfma_f32_16x16x32_bf16 v[96:99], v[152:155], v[176:179], v[96:99]
	v_mfma_f32_16x16x32_bf16 v[96:99], v[156:159], v[180:183], v[96:99]
	v_mfma_f32_16x16x32_bf16 v[88:91], v[160:163], v[176:179], v[88:91]
	v_mfma_f32_16x16x32_bf16 v[88:91], v[164:167], v[180:183], v[88:91]
	v_mfma_f32_16x16x32_bf16 v[80:83], v[152:155], v[184:187], v[80:83]
	v_mfma_f32_16x16x32_bf16 v[80:83], v[156:159], v[188:191], v[80:83]
	v_mfma_f32_16x16x32_bf16 v[72:75], v[160:163], v[184:187], v[72:75]
	v_mfma_f32_16x16x32_bf16 v[72:75], v[164:167], v[188:191], v[72:75]
	v_mfma_f32_16x16x32_bf16 v[68:71], v[152:155], v[192:195], v[68:71]
	v_mfma_f32_16x16x32_bf16 v[68:71], v[156:159], v[200:203], v[68:71]
	v_mfma_f32_16x16x32_bf16 v[64:67], v[160:163], v[192:195], v[64:67]
	v_mfma_f32_16x16x32_bf16 v[64:67], v[164:167], v[200:203], v[64:67]
	s_setprio 0
	s_barrier
	s_add_i32 s17, s17, s97
	s_mov_b64 s[70:71], s[34:35]
	s_mov_b32 m0, s17
	ds_read_b128 v[168:171], v135 offset:16384
	ds_read_b128 v[172:175], v135 offset:17408
	ds_read_b128 v[176:179], v135 offset:18432
	ds_read_b128 v[180:183], v135 offset:19456
	ds_read_b128 v[184:187], v135 offset:20480
	ds_read_b128 v[188:191], v135 offset:21504
	ds_read_b128 v[192:195], v135 offset:22528
	ds_read_b128 v[200:203], v135 offset:23552
	s_nop 0
	global_load_lds_dwordx4 v132, s[70:71]
	s_add_i32 m0, s17, 0x2000
	s_nop 0
	global_load_lds_dwordx4 v130, s[70:71]
	s_add_u32 s70, s34, 0x200000
	s_addc_u32 s71, s35, 0
	s_add_i32 s17, s69, s97
	s_mov_b32 m0, s17
	s_nop 0
	global_load_lds_dwordx4 v132, s[70:71]
	s_add_i32 m0, s17, 0x2000
	s_nop 0
	global_load_lds_dwordx4 v130, s[70:71]
	s_mov_b64 s[70:71], s[36:37]
	s_mov_b32 m0, s23
	s_nop 0
	global_load_lds_dwordx4 v133, s[70:71]
	s_mov_b32 m0, s25
	s_nop 0
	global_load_lds_dwordx4 v131, s[70:71]
	s_waitcnt vmcnt(8)
	s_waitcnt lgkmcnt(0)
	s_barrier
	s_setprio 1
	s_waitcnt lgkmcnt(0)
	v_mfma_f32_16x16x32_bf16 v[60:63], v[136:139], v[168:171], v[60:63]
	v_mfma_f32_16x16x32_bf16 v[60:63], v[140:143], v[172:175], v[60:63]
	v_mfma_f32_16x16x32_bf16 v[56:59], v[144:147], v[168:171], v[56:59]
	v_mfma_f32_16x16x32_bf16 v[56:59], v[148:151], v[172:175], v[56:59]
	v_mfma_f32_16x16x32_bf16 v[52:55], v[136:139], v[176:179], v[52:55]
	v_mfma_f32_16x16x32_bf16 v[52:55], v[140:143], v[180:183], v[52:55]
	v_mfma_f32_16x16x32_bf16 v[44:47], v[144:147], v[176:179], v[44:47]
	v_mfma_f32_16x16x32_bf16 v[44:47], v[148:151], v[180:183], v[44:47]
	v_mfma_f32_16x16x32_bf16 v[36:39], v[136:139], v[184:187], v[36:39]
	v_mfma_f32_16x16x32_bf16 v[36:39], v[140:143], v[188:191], v[36:39]
	v_mfma_f32_16x16x32_bf16 v[28:31], v[144:147], v[184:187], v[28:31]
	v_mfma_f32_16x16x32_bf16 v[28:31], v[148:151], v[188:191], v[28:31]
	v_mfma_f32_16x16x32_bf16 v[20:23], v[136:139], v[192:195], v[20:23]
	v_mfma_f32_16x16x32_bf16 v[20:23], v[140:143], v[200:203], v[20:23]
	v_mfma_f32_16x16x32_bf16 v[12:15], v[144:147], v[192:195], v[12:15]
	v_mfma_f32_16x16x32_bf16 v[12:15], v[148:151], v[200:203], v[12:15]
	s_setprio 0
	s_setprio 1
	v_mfma_f32_16x16x32_bf16 v[48:51], v[152:155], v[168:171], v[48:51]
	v_mfma_f32_16x16x32_bf16 v[48:51], v[156:159], v[172:175], v[48:51]
	v_mfma_f32_16x16x32_bf16 v[40:43], v[160:163], v[168:171], v[40:43]
	v_mfma_f32_16x16x32_bf16 v[40:43], v[164:167], v[172:175], v[40:43]
	v_mfma_f32_16x16x32_bf16 v[32:35], v[152:155], v[176:179], v[32:35]
	v_mfma_f32_16x16x32_bf16 v[32:35], v[156:159], v[180:183], v[32:35]
	v_mfma_f32_16x16x32_bf16 v[24:27], v[160:163], v[176:179], v[24:27]
	v_mfma_f32_16x16x32_bf16 v[24:27], v[164:167], v[180:183], v[24:27]
	v_mfma_f32_16x16x32_bf16 v[16:19], v[152:155], v[184:187], v[16:19]
	v_mfma_f32_16x16x32_bf16 v[16:19], v[156:159], v[188:191], v[16:19]
	v_mfma_f32_16x16x32_bf16 v[8:11], v[160:163], v[184:187], v[8:11]
	v_mfma_f32_16x16x32_bf16 v[8:11], v[164:167], v[188:191], v[8:11]
	v_mfma_f32_16x16x32_bf16 v[4:7], v[152:155], v[192:195], v[4:7]
	v_mfma_f32_16x16x32_bf16 v[4:7], v[156:159], v[200:203], v[4:7]
	v_mfma_f32_16x16x32_bf16 v[0:3], v[160:163], v[192:195], v[0:3]
	v_mfma_f32_16x16x32_bf16 v[0:3], v[164:167], v[200:203], v[0:3]
	s_setprio 0
	s_barrier
	s_add_i32 s17, 0, 0x18000
	v_add_u32_e32 v128, s17, v134
	s_add_i32 s69, 0, 0x1c000
	ds_read_b128 v[136:139], v128
	ds_read_b128 v[140:143], v128 offset:1024
	ds_read_b128 v[144:147], v128 offset:2048
	ds_read_b128 v[148:151], v128 offset:3072
	v_add_u32_e32 v128, s69, v134
	ds_read_b128 v[152:155], v128
	ds_read_b128 v[156:159], v128 offset:1024
	ds_read_b128 v[160:163], v128 offset:2048
	ds_read_b128 v[164:167], v128 offset:3072
	s_add_u32 s36, s36, 0x80000
	s_addc_u32 s37, s37, 0
	s_mov_b32 m0, s46
	ds_read_b128 v[168:171], v135 offset:32768
	ds_read_b128 v[172:175], v135 offset:33792
	ds_read_b128 v[176:179], v135 offset:34816
	ds_read_b128 v[180:183], v135 offset:35840
	ds_read_b128 v[184:187], v135 offset:36864
	ds_read_b128 v[188:191], v135 offset:37888
	ds_read_b128 v[192:195], v135 offset:38912
	ds_read_b128 v[200:203], v135 offset:39936
	s_nop 0
	global_load_lds_dwordx4 v133, s[36:37]
	s_mov_b32 m0, s47
	s_nop 0
	global_load_lds_dwordx4 v131, s[36:37]
	s_waitcnt vmcnt(8)
	s_waitcnt lgkmcnt(0)
	s_barrier
	s_setprio 1
	s_waitcnt lgkmcnt(0)
	v_mfma_f32_16x16x32_bf16 v[124:127], v[136:139], v[168:171], v[124:127]
	v_mfma_f32_16x16x32_bf16 v[124:127], v[140:143], v[172:175], v[124:127]
	v_mfma_f32_16x16x32_bf16 v[120:123], v[144:147], v[168:171], v[120:123]
	v_mfma_f32_16x16x32_bf16 v[120:123], v[148:151], v[172:175], v[120:123]
	v_mfma_f32_16x16x32_bf16 v[116:119], v[136:139], v[176:179], v[116:119]
	v_mfma_f32_16x16x32_bf16 v[116:119], v[140:143], v[180:183], v[116:119]
	v_mfma_f32_16x16x32_bf16 v[108:111], v[144:147], v[176:179], v[108:111]
	v_mfma_f32_16x16x32_bf16 v[108:111], v[148:151], v[180:183], v[108:111]
	v_mfma_f32_16x16x32_bf16 v[100:103], v[136:139], v[184:187], v[100:103]
	v_mfma_f32_16x16x32_bf16 v[100:103], v[140:143], v[188:191], v[100:103]
	v_mfma_f32_16x16x32_bf16 v[92:95], v[144:147], v[184:187], v[92:95]
	v_mfma_f32_16x16x32_bf16 v[92:95], v[148:151], v[188:191], v[92:95]
	v_mfma_f32_16x16x32_bf16 v[84:87], v[136:139], v[192:195], v[84:87]
	v_mfma_f32_16x16x32_bf16 v[84:87], v[140:143], v[200:203], v[84:87]
	v_mfma_f32_16x16x32_bf16 v[76:79], v[144:147], v[192:195], v[76:79]
	v_mfma_f32_16x16x32_bf16 v[76:79], v[148:151], v[200:203], v[76:79]
	s_setprio 0
	s_setprio 1
	v_mfma_f32_16x16x32_bf16 v[112:115], v[152:155], v[168:171], v[112:115]
	v_mfma_f32_16x16x32_bf16 v[112:115], v[156:159], v[172:175], v[112:115]
	v_mfma_f32_16x16x32_bf16 v[104:107], v[160:163], v[168:171], v[104:107]
	v_mfma_f32_16x16x32_bf16 v[104:107], v[164:167], v[172:175], v[104:107]
	v_mfma_f32_16x16x32_bf16 v[96:99], v[152:155], v[176:179], v[96:99]
	v_mfma_f32_16x16x32_bf16 v[96:99], v[156:159], v[180:183], v[96:99]
	v_mfma_f32_16x16x32_bf16 v[88:91], v[160:163], v[176:179], v[88:91]
	v_mfma_f32_16x16x32_bf16 v[88:91], v[164:167], v[180:183], v[88:91]
	v_mfma_f32_16x16x32_bf16 v[80:83], v[152:155], v[184:187], v[80:83]
	v_mfma_f32_16x16x32_bf16 v[80:83], v[156:159], v[188:191], v[80:83]
	v_mfma_f32_16x16x32_bf16 v[72:75], v[160:163], v[184:187], v[72:75]
	v_mfma_f32_16x16x32_bf16 v[72:75], v[164:167], v[188:191], v[72:75]
	v_mfma_f32_16x16x32_bf16 v[68:71], v[152:155], v[192:195], v[68:71]
	v_mfma_f32_16x16x32_bf16 v[68:71], v[156:159], v[200:203], v[68:71]
	v_mfma_f32_16x16x32_bf16 v[64:67], v[160:163], v[192:195], v[64:67]
	v_mfma_f32_16x16x32_bf16 v[64:67], v[164:167], v[200:203], v[64:67]
	s_setprio 0
	s_barrier
	s_add_u32 s36, s34, 0x80
	s_addc_u32 s37, s35, 0
	s_add_i32 s17, s17, s97
	s_mov_b32 m0, s17
	ds_read_b128 v[168:171], v135 offset:49152
	ds_read_b128 v[172:175], v135 offset:50176
	ds_read_b128 v[176:179], v135 offset:51200
	ds_read_b128 v[180:183], v135 offset:52224
	ds_read_b128 v[184:187], v135 offset:53248
	ds_read_b128 v[188:191], v135 offset:54272
	ds_read_b128 v[192:195], v135 offset:55296
	ds_read_b128 v[200:203], v135 offset:56320
	s_nop 0
	global_load_lds_dwordx4 v132, s[36:37]
	s_add_i32 m0, s17, 0x2000
	s_add_u32 s34, s34, 0x200080
	s_addc_u32 s35, s35, 0
	s_add_i32 s17, s69, s97
	s_nop 0
	global_load_lds_dwordx4 v130, s[36:37]
	s_mov_b32 m0, s17
	s_nop 0
	global_load_lds_dwordx4 v132, s[34:35]
	s_add_i32 m0, s17, 0x2000
	s_nop 0
	global_load_lds_dwordx4 v130, s[34:35]
	s_mov_b32 m0, s56
	s_nop 0
	global_load_lds_dwordx4 v133, s[30:31]
	s_mov_b32 m0, s57
	s_nop 0
	global_load_lds_dwordx4 v131, s[30:31]
	s_waitcnt vmcnt(8)
	s_waitcnt lgkmcnt(0)
	s_barrier
	s_setprio 1
	s_waitcnt lgkmcnt(0)
	v_mfma_f32_16x16x32_bf16 v[60:63], v[136:139], v[168:171], v[60:63]
	v_mfma_f32_16x16x32_bf16 v[60:63], v[140:143], v[172:175], v[60:63]
	v_mfma_f32_16x16x32_bf16 v[56:59], v[144:147], v[168:171], v[56:59]
	v_mfma_f32_16x16x32_bf16 v[56:59], v[148:151], v[172:175], v[56:59]
	v_mfma_f32_16x16x32_bf16 v[52:55], v[136:139], v[176:179], v[52:55]
	v_mfma_f32_16x16x32_bf16 v[52:55], v[140:143], v[180:183], v[52:55]
	v_mfma_f32_16x16x32_bf16 v[44:47], v[144:147], v[176:179], v[44:47]
	v_mfma_f32_16x16x32_bf16 v[44:47], v[148:151], v[180:183], v[44:47]
	v_mfma_f32_16x16x32_bf16 v[36:39], v[136:139], v[184:187], v[36:39]
	v_mfma_f32_16x16x32_bf16 v[36:39], v[140:143], v[188:191], v[36:39]
	v_mfma_f32_16x16x32_bf16 v[28:31], v[144:147], v[184:187], v[28:31]
	v_mfma_f32_16x16x32_bf16 v[28:31], v[148:151], v[188:191], v[28:31]
	v_mfma_f32_16x16x32_bf16 v[20:23], v[136:139], v[192:195], v[20:23]
	v_mfma_f32_16x16x32_bf16 v[20:23], v[140:143], v[200:203], v[20:23]
	v_mfma_f32_16x16x32_bf16 v[12:15], v[144:147], v[192:195], v[12:15]
	v_mfma_f32_16x16x32_bf16 v[12:15], v[148:151], v[200:203], v[12:15]
	s_setprio 0
	s_setprio 1
	v_mfma_f32_16x16x32_bf16 v[48:51], v[152:155], v[168:171], v[48:51]
	v_mfma_f32_16x16x32_bf16 v[48:51], v[156:159], v[172:175], v[48:51]
	v_mfma_f32_16x16x32_bf16 v[40:43], v[160:163], v[168:171], v[40:43]
	v_mfma_f32_16x16x32_bf16 v[40:43], v[164:167], v[172:175], v[40:43]
	v_mfma_f32_16x16x32_bf16 v[32:35], v[152:155], v[176:179], v[32:35]
	v_mfma_f32_16x16x32_bf16 v[32:35], v[156:159], v[180:183], v[32:35]
	v_mfma_f32_16x16x32_bf16 v[24:27], v[160:163], v[176:179], v[24:27]
	v_mfma_f32_16x16x32_bf16 v[24:27], v[164:167], v[180:183], v[24:27]
	v_mfma_f32_16x16x32_bf16 v[16:19], v[152:155], v[184:187], v[16:19]
	v_mfma_f32_16x16x32_bf16 v[16:19], v[156:159], v[188:191], v[16:19]
	v_mfma_f32_16x16x32_bf16 v[8:11], v[160:163], v[184:187], v[8:11]
	v_mfma_f32_16x16x32_bf16 v[8:11], v[164:167], v[188:191], v[8:11]
	v_mfma_f32_16x16x32_bf16 v[4:7], v[152:155], v[192:195], v[4:7]
	v_mfma_f32_16x16x32_bf16 v[4:7], v[156:159], v[200:203], v[4:7]
	v_mfma_f32_16x16x32_bf16 v[0:3], v[160:163], v[192:195], v[0:3]
	v_mfma_f32_16x16x32_bf16 v[0:3], v[164:167], v[200:203], v[0:3]
	s_setprio 0
	s_barrier
	s_add_i32 s15, s15, 2
	s_add_u32 s4, s4, 0x100
	s_addc_u32 s5, s5, 0
	s_add_u32 s11, s11, 0x100
	s_addc_u32 s13, s13, 0
	s_add_u32 s28, s28, 0x100
	s_addc_u32 s29, s29, 0
	s_cmp_gt_u32 s15, 29
	s_cbranch_scc0 .LBB0_380
	s_and_b64 vcc, exec, s[60:61]
	s_cbranch_vccz .LBB0_383
	s_barrier

.LBB0_397:
	s_cmp_eq_u32 s69, 4
	s_cselect_b32 s34, s15, s49
	s_cselect_b32 s35, s5, s56
	s_cselect_b32 s30, s48, s57
	s_cselect_b32 s31, s13, s65
	s_add_u32 s28, s34, 0x80
	s_addc_u32 s29, s35, 0
	s_add_i32 s72, 0, 0x10000
	v_add_u32_e32 v128, s72, v134
	s_add_i32 s74, 0, 0x14000
	ds_read_b128 v[136:139], v128
	ds_read_b128 v[140:143], v128 offset:1024
	ds_read_b128 v[144:147], v128 offset:2048
	ds_read_b128 v[148:151], v128 offset:3072
	v_add_u32_e32 v128, s74, v134
	ds_read_b128 v[152:155], v128
	ds_read_b128 v[156:159], v128 offset:1024
	ds_read_b128 v[160:163], v128 offset:2048
	ds_read_b128 v[164:167], v128 offset:3072
	s_mov_b64 s[70:71], s[26:27]
	s_add_i32 m0, s25, 0xc000
	ds_read_b128 v[168:171], v135
	ds_read_b128 v[172:175], v135 offset:1024
	ds_read_b128 v[176:179], v135 offset:2048
	ds_read_b128 v[180:183], v135 offset:3072
	ds_read_b128 v[184:187], v135 offset:4096
	ds_read_b128 v[188:191], v135 offset:5120
	ds_read_b128 v[192:195], v135 offset:6144
	ds_read_b128 v[200:203], v135 offset:7168
	s_nop 0
	global_load_lds_dwordx4 v133, s[70:71]
	s_add_i32 m0, s25, 0xe000
	s_nop 0
	global_load_lds_dwordx4 v131, s[70:71]
	s_waitcnt vmcnt(8)
	s_waitcnt lgkmcnt(0)
	s_barrier
	s_setprio 1
	s_waitcnt lgkmcnt(0)
	v_mfma_f32_16x16x32_bf16 v[124:127], v[136:139], v[168:171], v[124:127]
	v_mfma_f32_16x16x32_bf16 v[124:127], v[140:143], v[172:175], v[124:127]
	v_mfma_f32_16x16x32_bf16 v[120:123], v[144:147], v[168:171], v[120:123]
	v_mfma_f32_16x16x32_bf16 v[120:123], v[148:151], v[172:175], v[120:123]
	v_mfma_f32_16x16x32_bf16 v[116:119], v[136:139], v[176:179], v[116:119]
	v_mfma_f32_16x16x32_bf16 v[116:119], v[140:143], v[180:183], v[116:119]
	v_mfma_f32_16x16x32_bf16 v[108:111], v[144:147], v[176:179], v[108:111]
	v_mfma_f32_16x16x32_bf16 v[108:111], v[148:151], v[180:183], v[108:111]
	v_mfma_f32_16x16x32_bf16 v[100:103], v[136:139], v[184:187], v[100:103]
	v_mfma_f32_16x16x32_bf16 v[100:103], v[140:143], v[188:191], v[100:103]
	v_mfma_f32_16x16x32_bf16 v[92:95], v[144:147], v[184:187], v[92:95]
	v_mfma_f32_16x16x32_bf16 v[92:95], v[148:151], v[188:191], v[92:95]
	v_mfma_f32_16x16x32_bf16 v[84:87], v[136:139], v[192:195], v[84:87]
	v_mfma_f32_16x16x32_bf16 v[84:87], v[140:143], v[200:203], v[84:87]
	v_mfma_f32_16x16x32_bf16 v[76:79], v[144:147], v[192:195], v[76:79]
	v_mfma_f32_16x16x32_bf16 v[76:79], v[148:151], v[200:203], v[76:79]
	s_setprio 0
	s_setprio 1
	v_mfma_f32_16x16x32_bf16 v[112:115], v[152:155], v[168:171], v[112:115]
	v_mfma_f32_16x16x32_bf16 v[112:115], v[156:159], v[172:175], v[112:115]
	v_mfma_f32_16x16x32_bf16 v[104:107], v[160:163], v[168:171], v[104:107]
	v_mfma_f32_16x16x32_bf16 v[104:107], v[164:167], v[172:175], v[104:107]
	v_mfma_f32_16x16x32_bf16 v[96:99], v[152:155], v[176:179], v[96:99]
	v_mfma_f32_16x16x32_bf16 v[96:99], v[156:159], v[180:183], v[96:99]
	v_mfma_f32_16x16x32_bf16 v[88:91], v[160:163], v[176:179], v[88:91]
	v_mfma_f32_16x16x32_bf16 v[88:91], v[164:167], v[180:183], v[88:91]
	v_mfma_f32_16x16x32_bf16 v[80:83], v[152:155], v[184:187], v[80:83]
	v_mfma_f32_16x16x32_bf16 v[80:83], v[156:159], v[188:191], v[80:83]
	v_mfma_f32_16x16x32_bf16 v[72:75], v[160:163], v[184:187], v[72:75]
	v_mfma_f32_16x16x32_bf16 v[72:75], v[164:167], v[188:191], v[72:75]
	v_mfma_f32_16x16x32_bf16 v[68:71], v[152:155], v[192:195], v[68:71]
	v_mfma_f32_16x16x32_bf16 v[68:71], v[156:159], v[200:203], v[68:71]
	v_mfma_f32_16x16x32_bf16 v[64:67], v[160:163], v[192:195], v[64:67]
	v_mfma_f32_16x16x32_bf16 v[64:67], v[164:167], v[200:203], v[64:67]
	s_setprio 0
	s_barrier
	s_add_i32 s72, s72, s97
	s_mov_b64 s[70:71], s[30:31]
	s_mov_b32 m0, s72
	ds_read_b128 v[168:171], v135 offset:16384
	ds_read_b128 v[172:175], v135 offset:17408
	ds_read_b128 v[176:179], v135 offset:18432
	ds_read_b128 v[180:183], v135 offset:19456
	ds_read_b128 v[184:187], v135 offset:20480
	ds_read_b128 v[188:191], v135 offset:21504
	ds_read_b128 v[192:195], v135 offset:22528
	ds_read_b128 v[200:203], v135 offset:23552
	s_nop 0
	global_load_lds_dwordx4 v132, s[70:71]
	s_add_i32 m0, s72, 0x2000
	s_nop 0
	global_load_lds_dwordx4 v130, s[70:71]
	s_add_u32 s70, s30, 0x20000
	s_addc_u32 s71, s31, 0
	s_add_i32 s72, s74, s97
	s_mov_b32 m0, s72
	s_nop 0
	global_load_lds_dwordx4 v132, s[70:71]
	s_add_i32 m0, s72, 0x2000
	s_nop 0
	global_load_lds_dwordx4 v130, s[70:71]
	s_mov_b64 s[70:71], s[34:35]
	s_mov_b32 m0, s25
	s_nop 0
	global_load_lds_dwordx4 v133, s[70:71]
	s_mov_b32 m0, s37
	s_nop 0
	global_load_lds_dwordx4 v131, s[70:71]
	s_waitcnt vmcnt(8)
	s_waitcnt lgkmcnt(0)
	s_barrier
	s_setprio 1
	s_waitcnt lgkmcnt(0)
	v_mfma_f32_16x16x32_bf16 v[60:63], v[136:139], v[168:171], v[60:63]
	v_mfma_f32_16x16x32_bf16 v[60:63], v[140:143], v[172:175], v[60:63]
	v_mfma_f32_16x16x32_bf16 v[56:59], v[144:147], v[168:171], v[56:59]
	v_mfma_f32_16x16x32_bf16 v[56:59], v[148:151], v[172:175], v[56:59]
	v_mfma_f32_16x16x32_bf16 v[52:55], v[136:139], v[176:179], v[52:55]
	v_mfma_f32_16x16x32_bf16 v[52:55], v[140:143], v[180:183], v[52:55]
	v_mfma_f32_16x16x32_bf16 v[44:47], v[144:147], v[176:179], v[44:47]
	v_mfma_f32_16x16x32_bf16 v[44:47], v[148:151], v[180:183], v[44:47]
	v_mfma_f32_16x16x32_bf16 v[36:39], v[136:139], v[184:187], v[36:39]
	v_mfma_f32_16x16x32_bf16 v[36:39], v[140:143], v[188:191], v[36:39]
	v_mfma_f32_16x16x32_bf16 v[28:31], v[144:147], v[184:187], v[28:31]
	v_mfma_f32_16x16x32_bf16 v[28:31], v[148:151], v[188:191], v[28:31]
	v_mfma_f32_16x16x32_bf16 v[20:23], v[136:139], v[192:195], v[20:23]
	v_mfma_f32_16x16x32_bf16 v[20:23], v[140:143], v[200:203], v[20:23]
	v_mfma_f32_16x16x32_bf16 v[12:15], v[144:147], v[192:195], v[12:15]
	v_mfma_f32_16x16x32_bf16 v[12:15], v[148:151], v[200:203], v[12:15]
	s_setprio 0
	s_setprio 1
	v_mfma_f32_16x16x32_bf16 v[48:51], v[152:155], v[168:171], v[48:51]
	v_mfma_f32_16x16x32_bf16 v[48:51], v[156:159], v[172:175], v[48:51]
	v_mfma_f32_16x16x32_bf16 v[40:43], v[160:163], v[168:171], v[40:43]
	v_mfma_f32_16x16x32_bf16 v[40:43], v[164:167], v[172:175], v[40:43]
	v_mfma_f32_16x16x32_bf16 v[32:35], v[152:155], v[176:179], v[32:35]
	v_mfma_f32_16x16x32_bf16 v[32:35], v[156:159], v[180:183], v[32:35]
	v_mfma_f32_16x16x32_bf16 v[24:27], v[160:163], v[176:179], v[24:27]
	v_mfma_f32_16x16x32_bf16 v[24:27], v[164:167], v[180:183], v[24:27]
	v_mfma_f32_16x16x32_bf16 v[16:19], v[152:155], v[184:187], v[16:19]
	v_mfma_f32_16x16x32_bf16 v[16:19], v[156:159], v[188:191], v[16:19]
	v_mfma_f32_16x16x32_bf16 v[8:11], v[160:163], v[184:187], v[8:11]
	v_mfma_f32_16x16x32_bf16 v[8:11], v[164:167], v[188:191], v[8:11]
	v_mfma_f32_16x16x32_bf16 v[4:7], v[152:155], v[192:195], v[4:7]
	v_mfma_f32_16x16x32_bf16 v[4:7], v[156:159], v[200:203], v[4:7]
	v_mfma_f32_16x16x32_bf16 v[0:3], v[160:163], v[192:195], v[0:3]
	v_mfma_f32_16x16x32_bf16 v[0:3], v[164:167], v[200:203], v[0:3]
	s_setprio 0
	s_barrier
	s_add_i32 s70, 0, 0x18000
	v_add_u32_e32 v128, s70, v134
	s_add_i32 s71, 0, 0x1c000
	ds_read_b128 v[136:139], v128
	ds_read_b128 v[140:143], v128 offset:1024
	ds_read_b128 v[144:147], v128 offset:2048
	ds_read_b128 v[148:151], v128 offset:3072
	v_add_u32_e32 v128, s71, v134
	ds_read_b128 v[152:155], v128
	ds_read_b128 v[156:159], v128 offset:1024
	ds_read_b128 v[160:163], v128 offset:2048
	ds_read_b128 v[164:167], v128 offset:3072
	s_add_u32 s34, s34, 0x20000
	s_addc_u32 s35, s35, 0
	s_mov_b32 m0, s38
	ds_read_b128 v[168:171], v135 offset:32768
	ds_read_b128 v[172:175], v135 offset:33792
	ds_read_b128 v[176:179], v135 offset:34816
	ds_read_b128 v[180:183], v135 offset:35840
	ds_read_b128 v[184:187], v135 offset:36864
	ds_read_b128 v[188:191], v135 offset:37888
	ds_read_b128 v[192:195], v135 offset:38912
	ds_read_b128 v[200:203], v135 offset:39936
	s_nop 0
	global_load_lds_dwordx4 v133, s[34:35]
	s_mov_b32 m0, s39
	s_nop 0
	global_load_lds_dwordx4 v131, s[34:35]
	s_waitcnt vmcnt(8)
	s_waitcnt lgkmcnt(0)
	s_barrier
	s_setprio 1
	s_waitcnt lgkmcnt(0)
	v_mfma_f32_16x16x32_bf16 v[124:127], v[136:139], v[168:171], v[124:127]
	v_mfma_f32_16x16x32_bf16 v[124:127], v[140:143], v[172:175], v[124:127]
	v_mfma_f32_16x16x32_bf16 v[120:123], v[144:147], v[168:171], v[120:123]
	v_mfma_f32_16x16x32_bf16 v[120:123], v[148:151], v[172:175], v[120:123]
	v_mfma_f32_16x16x32_bf16 v[116:119], v[136:139], v[176:179], v[116:119]
	v_mfma_f32_16x16x32_bf16 v[116:119], v[140:143], v[180:183], v[116:119]
	v_mfma_f32_16x16x32_bf16 v[108:111], v[144:147], v[176:179], v[108:111]
	v_mfma_f32_16x16x32_bf16 v[108:111], v[148:151], v[180:183], v[108:111]
	v_mfma_f32_16x16x32_bf16 v[100:103], v[136:139], v[184:187], v[100:103]
	v_mfma_f32_16x16x32_bf16 v[100:103], v[140:143], v[188:191], v[100:103]
	v_mfma_f32_16x16x32_bf16 v[92:95], v[144:147], v[184:187], v[92:95]
	v_mfma_f32_16x16x32_bf16 v[92:95], v[148:151], v[188:191], v[92:95]
	v_mfma_f32_16x16x32_bf16 v[84:87], v[136:139], v[192:195], v[84:87]
	v_mfma_f32_16x16x32_bf16 v[84:87], v[140:143], v[200:203], v[84:87]
	v_mfma_f32_16x16x32_bf16 v[76:79], v[144:147], v[192:195], v[76:79]
	v_mfma_f32_16x16x32_bf16 v[76:79], v[148:151], v[200:203], v[76:79]
	s_setprio 0
	s_setprio 1
	v_mfma_f32_16x16x32_bf16 v[112:115], v[152:155], v[168:171], v[112:115]
	v_mfma_f32_16x16x32_bf16 v[112:115], v[156:159], v[172:175], v[112:115]
	v_mfma_f32_16x16x32_bf16 v[104:107], v[160:163], v[168:171], v[104:107]
	v_mfma_f32_16x16x32_bf16 v[104:107], v[164:167], v[172:175], v[104:107]
	v_mfma_f32_16x16x32_bf16 v[96:99], v[152:155], v[176:179], v[96:99]
	v_mfma_f32_16x16x32_bf16 v[96:99], v[156:159], v[180:183], v[96:99]
	v_mfma_f32_16x16x32_bf16 v[88:91], v[160:163], v[176:179], v[88:91]
	v_mfma_f32_16x16x32_bf16 v[88:91], v[164:167], v[180:183], v[88:91]
	v_mfma_f32_16x16x32_bf16 v[80:83], v[152:155], v[184:187], v[80:83]
	v_mfma_f32_16x16x32_bf16 v[80:83], v[156:159], v[188:191], v[80:83]
	v_mfma_f32_16x16x32_bf16 v[72:75], v[160:163], v[184:187], v[72:75]
	v_mfma_f32_16x16x32_bf16 v[72:75], v[164:167], v[188:191], v[72:75]
	v_mfma_f32_16x16x32_bf16 v[68:71], v[152:155], v[192:195], v[68:71]
	v_mfma_f32_16x16x32_bf16 v[68:71], v[156:159], v[200:203], v[68:71]
	v_mfma_f32_16x16x32_bf16 v[64:67], v[160:163], v[192:195], v[64:67]
	v_mfma_f32_16x16x32_bf16 v[64:67], v[164:167], v[200:203], v[64:67]
	s_setprio 0
	s_barrier
	s_add_u32 s34, s30, 0x80
	s_addc_u32 s35, s31, 0
	s_add_i32 s70, s70, s97
	s_mov_b32 m0, s70
	ds_read_b128 v[168:171], v135 offset:49152
	ds_read_b128 v[172:175], v135 offset:50176
	ds_read_b128 v[176:179], v135 offset:51200
	ds_read_b128 v[180:183], v135 offset:52224
	ds_read_b128 v[184:187], v135 offset:53248
	ds_read_b128 v[188:191], v135 offset:54272
	ds_read_b128 v[192:195], v135 offset:55296
	ds_read_b128 v[200:203], v135 offset:56320
	s_nop 0
	global_load_lds_dwordx4 v132, s[34:35]
	s_add_i32 m0, s70, 0x2000
	s_add_u32 s30, s30, 0x20080
	s_addc_u32 s31, s31, 0
	global_load_lds_dwordx4 v130, s[34:35]
	s_add_i32 s34, s71, s97
	s_mov_b32 m0, s34
	s_nop 0
	global_load_lds_dwordx4 v132, s[30:31]
	s_add_i32 m0, s34, 0x2000
	s_nop 0
	global_load_lds_dwordx4 v130, s[30:31]
	s_mov_b32 m0, s44
	s_nop 0
	global_load_lds_dwordx4 v133, s[28:29]
	s_mov_b32 m0, s46
	s_nop 0
	global_load_lds_dwordx4 v131, s[28:29]
	s_waitcnt vmcnt(8)
	s_waitcnt lgkmcnt(0)
	s_barrier
	s_setprio 1
	s_waitcnt lgkmcnt(0)
	v_mfma_f32_16x16x32_bf16 v[60:63], v[136:139], v[168:171], v[60:63]
	v_mfma_f32_16x16x32_bf16 v[60:63], v[140:143], v[172:175], v[60:63]
	v_mfma_f32_16x16x32_bf16 v[56:59], v[144:147], v[168:171], v[56:59]
	v_mfma_f32_16x16x32_bf16 v[56:59], v[148:151], v[172:175], v[56:59]
	v_mfma_f32_16x16x32_bf16 v[52:55], v[136:139], v[176:179], v[52:55]
	v_mfma_f32_16x16x32_bf16 v[52:55], v[140:143], v[180:183], v[52:55]
	v_mfma_f32_16x16x32_bf16 v[44:47], v[144:147], v[176:179], v[44:47]
	v_mfma_f32_16x16x32_bf16 v[44:47], v[148:151], v[180:183], v[44:47]
	v_mfma_f32_16x16x32_bf16 v[36:39], v[136:139], v[184:187], v[36:39]
	v_mfma_f32_16x16x32_bf16 v[36:39], v[140:143], v[188:191], v[36:39]
	v_mfma_f32_16x16x32_bf16 v[28:31], v[144:147], v[184:187], v[28:31]
	v_mfma_f32_16x16x32_bf16 v[28:31], v[148:151], v[188:191], v[28:31]
	v_mfma_f32_16x16x32_bf16 v[20:23], v[136:139], v[192:195], v[20:23]
	v_mfma_f32_16x16x32_bf16 v[20:23], v[140:143], v[200:203], v[20:23]
	v_mfma_f32_16x16x32_bf16 v[12:15], v[144:147], v[192:195], v[12:15]
	v_mfma_f32_16x16x32_bf16 v[12:15], v[148:151], v[200:203], v[12:15]
	s_setprio 0
	s_setprio 1
	v_mfma_f32_16x16x32_bf16 v[48:51], v[152:155], v[168:171], v[48:51]
	v_mfma_f32_16x16x32_bf16 v[48:51], v[156:159], v[172:175], v[48:51]
	v_mfma_f32_16x16x32_bf16 v[40:43], v[160:163], v[168:171], v[40:43]
	v_mfma_f32_16x16x32_bf16 v[40:43], v[164:167], v[172:175], v[40:43]
	v_mfma_f32_16x16x32_bf16 v[32:35], v[152:155], v[176:179], v[32:35]
	v_mfma_f32_16x16x32_bf16 v[32:35], v[156:159], v[180:183], v[32:35]
	v_mfma_f32_16x16x32_bf16 v[24:27], v[160:163], v[176:179], v[24:27]
	v_mfma_f32_16x16x32_bf16 v[24:27], v[164:167], v[180:183], v[24:27]
	v_mfma_f32_16x16x32_bf16 v[16:19], v[152:155], v[184:187], v[16:19]
	v_mfma_f32_16x16x32_bf16 v[16:19], v[156:159], v[188:191], v[16:19]
	v_mfma_f32_16x16x32_bf16 v[8:11], v[160:163], v[184:187], v[8:11]
	v_mfma_f32_16x16x32_bf16 v[8:11], v[164:167], v[188:191], v[8:11]
	v_mfma_f32_16x16x32_bf16 v[4:7], v[152:155], v[192:195], v[4:7]
	v_mfma_f32_16x16x32_bf16 v[4:7], v[156:159], v[200:203], v[4:7]
	v_mfma_f32_16x16x32_bf16 v[0:3], v[160:163], v[192:195], v[0:3]
	v_mfma_f32_16x16x32_bf16 v[0:3], v[164:167], v[200:203], v[0:3]
	s_setprio 0
	s_barrier
	s_add_i32 s69, s69, 2
	s_add_u32 s49, s49, 0x100
	s_addc_u32 s56, s56, 0
	s_add_u32 s57, s57, 0x100
	s_addc_u32 s65, s65, 0
	s_add_u32 s26, s26, 0x100
	s_addc_u32 s27, s27, 0
	s_cmp_gt_u32 s69, 5
	s_cbranch_scc0 .LBB0_397
	s_and_b64 vcc, exec, s[60:61]
	s_cbranch_vccz .LBB0_400
	s_barrier

.LBB0_527:
	s_cmp_eq_u32 s85, 28
	s_cselect_b32 s56, s5, s39
	s_cselect_b32 s57, s4, s69
	s_cselect_b32 s86, s37, s72
	s_cselect_b32 s87, s11, s74
	s_add_u32 s12, s56, 0x80
	s_addc_u32 s13, s57, 0
	s_add_i32 vcc_lo, 0, 0x10000
	s_add_i32 vcc_hi, 0, 0x14000
	v_add_u32_e32 v136, vcc_lo, v184
	v_add_u32_e32 v156, vcc_hi, v184
	ds_read_b128 v[104:107], v136
	ds_read_b128 v[108:111], v136 offset:1024
	ds_read_b128 v[132:135], v136 offset:2048
	ds_read_b128 v[136:139], v136 offset:3072
	ds_read_b128 v[144:147], v156
	ds_read_b128 v[148:151], v156 offset:1024
	ds_read_b128 v[152:155], v156 offset:2048
	ds_read_b128 v[156:159], v156 offset:3072
	s_mov_b64 s[8:9], s[16:17]
	s_add_i32 m0, s89, 0xc000
	ds_read_b128 v[160:163], v185
	ds_read_b128 v[164:167], v185 offset:1024
	ds_read_b128 v[168:171], v185 offset:2048
	ds_read_b128 v[172:175], v185 offset:3072
	ds_read_b128 v[186:189], v185 offset:4096
	ds_read_b128 v[190:193], v185 offset:5120
	ds_read_b128 v[200:203], v185 offset:6144
	ds_read_b128 v[204:207], v185 offset:7168
	s_nop 0
	global_load_lds_dwordx4 v179, s[8:9]
	s_add_i32 m0, s89, 0xe000
	s_nop 0
	global_load_lds_dwordx4 v182, s[8:9]
	s_waitcnt vmcnt(8)
	s_waitcnt lgkmcnt(0)
	s_barrier
	s_setprio 1
	s_waitcnt lgkmcnt(0)
	v_mfma_f32_16x16x32_bf16 v[140:143], v[104:107], v[160:163], v[140:143]
	v_mfma_f32_16x16x32_bf16 v[140:143], v[108:111], v[164:167], v[140:143]
	v_mfma_f32_16x16x32_bf16 v[128:131], v[132:135], v[160:163], v[128:131]
	v_mfma_f32_16x16x32_bf16 v[128:131], v[136:139], v[164:167], v[128:131]
	v_mfma_f32_16x16x32_bf16 v[124:127], v[104:107], v[168:171], v[124:127]
	v_mfma_f32_16x16x32_bf16 v[124:127], v[108:111], v[172:175], v[124:127]
	v_mfma_f32_16x16x32_bf16 v[112:115], v[132:135], v[168:171], v[112:115]
	v_mfma_f32_16x16x32_bf16 v[112:115], v[136:139], v[172:175], v[112:115]
	v_mfma_f32_16x16x32_bf16 v[96:99], v[104:107], v[186:189], v[96:99]
	v_mfma_f32_16x16x32_bf16 v[96:99], v[108:111], v[190:193], v[96:99]
	v_mfma_f32_16x16x32_bf16 v[88:91], v[132:135], v[186:189], v[88:91]
	v_mfma_f32_16x16x32_bf16 v[88:91], v[136:139], v[190:193], v[88:91]
	v_mfma_f32_16x16x32_bf16 v[84:87], v[104:107], v[200:203], v[84:87]
	v_mfma_f32_16x16x32_bf16 v[84:87], v[108:111], v[204:207], v[84:87]
	v_mfma_f32_16x16x32_bf16 v[72:75], v[132:135], v[200:203], v[72:75]
	v_mfma_f32_16x16x32_bf16 v[72:75], v[136:139], v[204:207], v[72:75]
	s_setprio 0
	s_setprio 1
	v_mfma_f32_16x16x32_bf16 v[120:123], v[144:147], v[160:163], v[120:123]
	v_mfma_f32_16x16x32_bf16 v[120:123], v[148:151], v[164:167], v[120:123]
	v_mfma_f32_16x16x32_bf16 v[116:119], v[152:155], v[160:163], v[116:119]
	v_mfma_f32_16x16x32_bf16 v[116:119], v[156:159], v[164:167], v[116:119]
	v_mfma_f32_16x16x32_bf16 v[100:103], v[144:147], v[168:171], v[100:103]
	v_mfma_f32_16x16x32_bf16 v[100:103], v[148:151], v[172:175], v[100:103]
	v_mfma_f32_16x16x32_bf16 v[92:95], v[152:155], v[168:171], v[92:95]
	v_mfma_f32_16x16x32_bf16 v[92:95], v[156:159], v[172:175], v[92:95]
	v_mfma_f32_16x16x32_bf16 v[80:83], v[144:147], v[186:189], v[80:83]
	v_mfma_f32_16x16x32_bf16 v[80:83], v[148:151], v[190:193], v[80:83]
	v_mfma_f32_16x16x32_bf16 v[76:79], v[152:155], v[186:189], v[76:79]
	v_mfma_f32_16x16x32_bf16 v[76:79], v[156:159], v[190:193], v[76:79]
	v_mfma_f32_16x16x32_bf16 v[68:71], v[144:147], v[200:203], v[68:71]
	v_mfma_f32_16x16x32_bf16 v[68:71], v[148:151], v[204:207], v[68:71]
	v_mfma_f32_16x16x32_bf16 v[64:67], v[152:155], v[200:203], v[64:67]
	v_mfma_f32_16x16x32_bf16 v[64:67], v[156:159], v[204:207], v[64:67]
	s_setprio 0
	s_barrier
	s_add_i32 vcc_lo, vcc_lo, s97
	s_mov_b64 s[8:9], s[86:87]
	s_mov_b32 m0, vcc_lo
	ds_read_b128 v[160:163], v185 offset:16384
	ds_read_b128 v[164:167], v185 offset:17408
	ds_read_b128 v[168:171], v185 offset:18432
	ds_read_b128 v[172:175], v185 offset:19456
	ds_read_b128 v[186:189], v185 offset:20480
	ds_read_b128 v[190:193], v185 offset:21504
	ds_read_b128 v[200:203], v185 offset:22528
	ds_read_b128 v[204:207], v185 offset:23552
	s_nop 0
	global_load_lds_dwordx4 v181, s[8:9]
	s_add_i32 m0, vcc_lo, 0x2000
	s_nop 0
	global_load_lds_dwordx4 v183, s[8:9]
	s_add_u32 s8, s86, 0x80000
	s_addc_u32 s9, s87, 0
	s_add_i32 vcc_lo, vcc_hi, s97
	s_mov_b32 m0, vcc_lo
	s_nop 0
	global_load_lds_dwordx4 v181, s[8:9]
	s_add_i32 m0, vcc_lo, 0x2000
	s_nop 0
	global_load_lds_dwordx4 v183, s[8:9]
	s_mov_b64 s[8:9], s[56:57]
	s_mov_b32 m0, s89
	s_nop 0
	global_load_lds_dwordx4 v179, s[8:9]
	s_mov_b32 m0, s92
	s_nop 0
	global_load_lds_dwordx4 v182, s[8:9]
	s_waitcnt vmcnt(8)
	s_waitcnt lgkmcnt(0)
	s_barrier
	s_setprio 1
	s_waitcnt lgkmcnt(0)
	v_mfma_f32_16x16x32_bf16 v[60:63], v[104:107], v[160:163], v[60:63]
	v_mfma_f32_16x16x32_bf16 v[60:63], v[108:111], v[164:167], v[60:63]
	v_mfma_f32_16x16x32_bf16 v[56:59], v[132:135], v[160:163], v[56:59]
	v_mfma_f32_16x16x32_bf16 v[56:59], v[136:139], v[164:167], v[56:59]
	v_mfma_f32_16x16x32_bf16 v[48:51], v[104:107], v[168:171], v[48:51]
	v_mfma_f32_16x16x32_bf16 v[48:51], v[108:111], v[172:175], v[48:51]
	v_mfma_f32_16x16x32_bf16 v[40:43], v[132:135], v[168:171], v[40:43]
	v_mfma_f32_16x16x32_bf16 v[40:43], v[136:139], v[172:175], v[40:43]
	v_mfma_f32_16x16x32_bf16 v[32:35], v[104:107], v[186:189], v[32:35]
	v_mfma_f32_16x16x32_bf16 v[32:35], v[108:111], v[190:193], v[32:35]
	v_mfma_f32_16x16x32_bf16 v[24:27], v[132:135], v[186:189], v[24:27]
	v_mfma_f32_16x16x32_bf16 v[24:27], v[136:139], v[190:193], v[24:27]
	v_mfma_f32_16x16x32_bf16 v[16:19], v[104:107], v[200:203], v[16:19]
	v_mfma_f32_16x16x32_bf16 v[16:19], v[108:111], v[204:207], v[16:19]
	v_mfma_f32_16x16x32_bf16 v[8:11], v[132:135], v[200:203], v[8:11]
	v_mfma_f32_16x16x32_bf16 v[8:11], v[136:139], v[204:207], v[8:11]
	s_setprio 0
	s_setprio 1
	v_mfma_f32_16x16x32_bf16 v[52:55], v[144:147], v[160:163], v[52:55]
	v_mfma_f32_16x16x32_bf16 v[52:55], v[148:151], v[164:167], v[52:55]
	v_mfma_f32_16x16x32_bf16 v[44:47], v[152:155], v[160:163], v[44:47]
	v_mfma_f32_16x16x32_bf16 v[44:47], v[156:159], v[164:167], v[44:47]
	v_mfma_f32_16x16x32_bf16 v[36:39], v[144:147], v[168:171], v[36:39]
	v_mfma_f32_16x16x32_bf16 v[36:39], v[148:151], v[172:175], v[36:39]
	v_mfma_f32_16x16x32_bf16 v[28:31], v[152:155], v[168:171], v[28:31]
	v_mfma_f32_16x16x32_bf16 v[28:31], v[156:159], v[172:175], v[28:31]
	v_mfma_f32_16x16x32_bf16 v[20:23], v[144:147], v[186:189], v[20:23]
	v_mfma_f32_16x16x32_bf16 v[20:23], v[148:151], v[190:193], v[20:23]
	v_mfma_f32_16x16x32_bf16 v[12:15], v[152:155], v[186:189], v[12:15]
	v_mfma_f32_16x16x32_bf16 v[12:15], v[156:159], v[190:193], v[12:15]
	v_mfma_f32_16x16x32_bf16 v[4:7], v[144:147], v[200:203], v[4:7]
	v_mfma_f32_16x16x32_bf16 v[4:7], v[148:151], v[204:207], v[4:7]
	v_mfma_f32_16x16x32_bf16 v[0:3], v[152:155], v[200:203], v[0:3]
	v_mfma_f32_16x16x32_bf16 v[0:3], v[156:159], v[204:207], v[0:3]
	s_setprio 0
	s_barrier
	s_add_i32 vcc_lo, 0, 0x18000
	s_add_i32 vcc_hi, 0, 0x1c000
	v_add_u32_e32 v136, vcc_lo, v184
	v_add_u32_e32 v156, vcc_hi, v184
	ds_read_b128 v[104:107], v136
	ds_read_b128 v[108:111], v136 offset:1024
	ds_read_b128 v[132:135], v136 offset:2048
	ds_read_b128 v[136:139], v136 offset:3072
	ds_read_b128 v[144:147], v156
	ds_read_b128 v[148:151], v156 offset:1024
	ds_read_b128 v[152:155], v156 offset:2048
	ds_read_b128 v[156:159], v156 offset:3072
	s_add_u32 s8, s56, 0x80000
	s_addc_u32 s9, s57, 0
	s_mov_b32 m0, s93
	ds_read_b128 v[160:163], v185 offset:32768
	ds_read_b128 v[164:167], v185 offset:33792
	ds_read_b128 v[168:171], v185 offset:34816
	ds_read_b128 v[172:175], v185 offset:35840
	ds_read_b128 v[186:189], v185 offset:36864
	ds_read_b128 v[190:193], v185 offset:37888
	ds_read_b128 v[200:203], v185 offset:38912
	ds_read_b128 v[204:207], v185 offset:39936
	s_nop 0
	global_load_lds_dwordx4 v179, s[8:9]
	s_mov_b32 m0, s48
	s_nop 0
	global_load_lds_dwordx4 v182, s[8:9]
	s_waitcnt vmcnt(8)
	s_waitcnt lgkmcnt(0)
	s_barrier
	s_setprio 1
	s_waitcnt lgkmcnt(0)
	v_mfma_f32_16x16x32_bf16 v[140:143], v[104:107], v[160:163], v[140:143]
	v_mfma_f32_16x16x32_bf16 v[140:143], v[108:111], v[164:167], v[140:143]
	v_mfma_f32_16x16x32_bf16 v[128:131], v[132:135], v[160:163], v[128:131]
	v_mfma_f32_16x16x32_bf16 v[128:131], v[136:139], v[164:167], v[128:131]
	v_mfma_f32_16x16x32_bf16 v[124:127], v[104:107], v[168:171], v[124:127]
	v_mfma_f32_16x16x32_bf16 v[124:127], v[108:111], v[172:175], v[124:127]
	v_mfma_f32_16x16x32_bf16 v[112:115], v[132:135], v[168:171], v[112:115]
	v_mfma_f32_16x16x32_bf16 v[112:115], v[136:139], v[172:175], v[112:115]
	v_mfma_f32_16x16x32_bf16 v[96:99], v[104:107], v[186:189], v[96:99]
	v_mfma_f32_16x16x32_bf16 v[96:99], v[108:111], v[190:193], v[96:99]
	v_mfma_f32_16x16x32_bf16 v[88:91], v[132:135], v[186:189], v[88:91]
	v_mfma_f32_16x16x32_bf16 v[88:91], v[136:139], v[190:193], v[88:91]
	v_mfma_f32_16x16x32_bf16 v[84:87], v[104:107], v[200:203], v[84:87]
	v_mfma_f32_16x16x32_bf16 v[84:87], v[108:111], v[204:207], v[84:87]
	v_mfma_f32_16x16x32_bf16 v[72:75], v[132:135], v[200:203], v[72:75]
	v_mfma_f32_16x16x32_bf16 v[72:75], v[136:139], v[204:207], v[72:75]
	s_setprio 0
	s_setprio 1
	v_mfma_f32_16x16x32_bf16 v[120:123], v[144:147], v[160:163], v[120:123]
	v_mfma_f32_16x16x32_bf16 v[120:123], v[148:151], v[164:167], v[120:123]
	v_mfma_f32_16x16x32_bf16 v[116:119], v[152:155], v[160:163], v[116:119]
	v_mfma_f32_16x16x32_bf16 v[116:119], v[156:159], v[164:167], v[116:119]
	v_mfma_f32_16x16x32_bf16 v[100:103], v[144:147], v[168:171], v[100:103]
	v_mfma_f32_16x16x32_bf16 v[100:103], v[148:151], v[172:175], v[100:103]
	v_mfma_f32_16x16x32_bf16 v[92:95], v[152:155], v[168:171], v[92:95]
	v_mfma_f32_16x16x32_bf16 v[92:95], v[156:159], v[172:175], v[92:95]
	v_mfma_f32_16x16x32_bf16 v[80:83], v[144:147], v[186:189], v[80:83]
	v_mfma_f32_16x16x32_bf16 v[80:83], v[148:151], v[190:193], v[80:83]
	v_mfma_f32_16x16x32_bf16 v[76:79], v[152:155], v[186:189], v[76:79]
	v_mfma_f32_16x16x32_bf16 v[76:79], v[156:159], v[190:193], v[76:79]
	v_mfma_f32_16x16x32_bf16 v[68:71], v[144:147], v[200:203], v[68:71]
	v_mfma_f32_16x16x32_bf16 v[68:71], v[148:151], v[204:207], v[68:71]
	v_mfma_f32_16x16x32_bf16 v[64:67], v[152:155], v[200:203], v[64:67]
	v_mfma_f32_16x16x32_bf16 v[64:67], v[156:159], v[204:207], v[64:67]
	s_setprio 0
	s_barrier
	s_add_u32 s8, s86, 0x80
	s_addc_u32 s9, s87, 0
	s_add_i32 s56, vcc_lo, s97
	s_mov_b32 m0, s56
	ds_read_b128 v[160:163], v185 offset:49152
	ds_read_b128 v[164:167], v185 offset:50176
	ds_read_b128 v[168:171], v185 offset:51200
	ds_read_b128 v[172:175], v185 offset:52224
	ds_read_b128 v[186:189], v185 offset:53248
	ds_read_b128 v[190:193], v185 offset:54272
	ds_read_b128 v[200:203], v185 offset:55296
	ds_read_b128 v[204:207], v185 offset:56320
	s_nop 0
	global_load_lds_dwordx4 v181, s[8:9]
	s_add_i32 m0, s56, 0x2000
	s_nop 0
	global_load_lds_dwordx4 v183, s[8:9]
	s_add_u32 s8, s86, 0x80080
	s_addc_u32 s9, s87, 0
	s_add_i32 s56, vcc_hi, s97
	s_mov_b32 m0, s56
	s_nop 0
	global_load_lds_dwordx4 v181, s[8:9]
	s_add_i32 m0, s56, 0x2000
	s_nop 0
	global_load_lds_dwordx4 v183, s[8:9]
	s_mov_b32 m0, s46
	s_nop 0
	global_load_lds_dwordx4 v179, s[12:13]
	s_mov_b32 m0, s70
	s_nop 0
	global_load_lds_dwordx4 v182, s[12:13]
	s_waitcnt vmcnt(8)
	s_waitcnt lgkmcnt(0)
	s_barrier
	s_setprio 1
	s_waitcnt lgkmcnt(0)
	v_mfma_f32_16x16x32_bf16 v[60:63], v[104:107], v[160:163], v[60:63]
	v_mfma_f32_16x16x32_bf16 v[60:63], v[108:111], v[164:167], v[60:63]
	v_mfma_f32_16x16x32_bf16 v[56:59], v[132:135], v[160:163], v[56:59]
	v_mfma_f32_16x16x32_bf16 v[56:59], v[136:139], v[164:167], v[56:59]
	v_mfma_f32_16x16x32_bf16 v[48:51], v[104:107], v[168:171], v[48:51]
	v_mfma_f32_16x16x32_bf16 v[48:51], v[108:111], v[172:175], v[48:51]
	v_mfma_f32_16x16x32_bf16 v[40:43], v[132:135], v[168:171], v[40:43]
	v_mfma_f32_16x16x32_bf16 v[40:43], v[136:139], v[172:175], v[40:43]
	v_mfma_f32_16x16x32_bf16 v[32:35], v[104:107], v[186:189], v[32:35]
	v_mfma_f32_16x16x32_bf16 v[32:35], v[108:111], v[190:193], v[32:35]
	v_mfma_f32_16x16x32_bf16 v[24:27], v[132:135], v[186:189], v[24:27]
	v_mfma_f32_16x16x32_bf16 v[24:27], v[136:139], v[190:193], v[24:27]
	v_mfma_f32_16x16x32_bf16 v[16:19], v[104:107], v[200:203], v[16:19]
	v_mfma_f32_16x16x32_bf16 v[16:19], v[108:111], v[204:207], v[16:19]
	v_mfma_f32_16x16x32_bf16 v[8:11], v[132:135], v[200:203], v[8:11]
	v_mfma_f32_16x16x32_bf16 v[8:11], v[136:139], v[204:207], v[8:11]
	s_setprio 0
	s_setprio 1
	v_mfma_f32_16x16x32_bf16 v[52:55], v[144:147], v[160:163], v[52:55]
	v_mfma_f32_16x16x32_bf16 v[52:55], v[148:151], v[164:167], v[52:55]
	v_mfma_f32_16x16x32_bf16 v[44:47], v[152:155], v[160:163], v[44:47]
	v_mfma_f32_16x16x32_bf16 v[44:47], v[156:159], v[164:167], v[44:47]
	v_mfma_f32_16x16x32_bf16 v[36:39], v[144:147], v[168:171], v[36:39]
	v_mfma_f32_16x16x32_bf16 v[36:39], v[148:151], v[172:175], v[36:39]
	v_mfma_f32_16x16x32_bf16 v[28:31], v[152:155], v[168:171], v[28:31]
	v_mfma_f32_16x16x32_bf16 v[28:31], v[156:159], v[172:175], v[28:31]
	v_mfma_f32_16x16x32_bf16 v[20:23], v[144:147], v[186:189], v[20:23]
	v_mfma_f32_16x16x32_bf16 v[20:23], v[148:151], v[190:193], v[20:23]
	v_mfma_f32_16x16x32_bf16 v[12:15], v[152:155], v[186:189], v[12:15]
	v_mfma_f32_16x16x32_bf16 v[12:15], v[156:159], v[190:193], v[12:15]
	v_mfma_f32_16x16x32_bf16 v[4:7], v[144:147], v[200:203], v[4:7]
	v_mfma_f32_16x16x32_bf16 v[4:7], v[148:151], v[204:207], v[4:7]
	v_mfma_f32_16x16x32_bf16 v[0:3], v[152:155], v[200:203], v[0:3]
	v_mfma_f32_16x16x32_bf16 v[0:3], v[156:159], v[204:207], v[0:3]
	s_setprio 0
	s_barrier
	s_add_i32 s85, s85, 2
	s_add_u32 s39, s39, 0x100
	s_addc_u32 s69, s69, 0
	s_add_u32 s72, s72, 0x100
	s_addc_u32 s74, s74, 0
	s_add_u32 s16, s16, 0x100
	s_addc_u32 s17, s17, 0
	s_cmp_gt_u32 s85, 29
	s_cbranch_scc0 .LBB0_527
	s_and_b64 vcc, exec, s[60:61]
	s_cbranch_vccz .LBB0_530
	s_barrier

.LBB0_604:
	s_cmp_eq_u32 s21, 4
	s_cselect_b32 s38, s22, s4
	s_cselect_b32 s39, s23, s5
	s_cselect_b32 s36, s24, s15
	s_cselect_b32 s37, s25, s17
	s_add_u32 s34, s38, 0x80
	s_addc_u32 s35, s39, 0
	s_add_i32 s65, 0, 0x10000
	s_add_i32 s69, 0, 0x14000
	v_add_u32_e32 v132, s65, v154
	v_add_u32_e32 v148, s69, v154
	ds_read_b128 v[112:115], v132
	ds_read_b128 v[120:123], v132 offset:1024
	ds_read_b128 v[128:131], v132 offset:2048
	ds_read_b128 v[132:135], v132 offset:3072
	ds_read_b128 v[144:147], v148
	ds_read_b128 v[156:159], v148 offset:1024
	ds_read_b128 v[160:163], v148 offset:2048
	ds_read_b128 v[164:167], v148 offset:3072
	s_add_u32 s70, s4, 0x7ff80
	s_addc_u32 s71, s5, 0
	s_add_i32 m0, s27, 0xc000
	ds_read_b128 v[168:171], v155
	ds_read_b128 v[172:175], v155 offset:1024
	ds_read_b128 v[176:179], v155 offset:2048
	ds_read_b128 v[180:183], v155 offset:3072
	ds_read_b128 v[184:187], v155 offset:4096
	ds_read_b128 v[188:191], v155 offset:5120
	ds_read_b128 v[192:195], v155 offset:6144
	ds_read_b128 v[200:203], v155 offset:7168
	s_nop 0
	global_load_lds_dwordx4 v151, s[70:71]
	s_add_i32 m0, s27, 0xe000
	s_nop 0
	global_load_lds_dwordx4 v150, s[70:71]
	s_waitcnt vmcnt(8)
	s_waitcnt lgkmcnt(0)
	s_barrier
	s_setprio 1
	s_waitcnt lgkmcnt(0)
	v_mfma_f32_16x16x32_bf16 v[140:143], v[112:115], v[168:171], v[140:143]
	v_mfma_f32_16x16x32_bf16 v[140:143], v[120:123], v[172:175], v[140:143]
	v_mfma_f32_16x16x32_bf16 v[136:139], v[128:131], v[168:171], v[136:139]
	v_mfma_f32_16x16x32_bf16 v[136:139], v[132:135], v[172:175], v[136:139]
	v_mfma_f32_16x16x32_bf16 v[108:111], v[112:115], v[176:179], v[108:111]
	v_mfma_f32_16x16x32_bf16 v[108:111], v[120:123], v[180:183], v[108:111]
	v_mfma_f32_16x16x32_bf16 v[104:107], v[128:131], v[176:179], v[104:107]
	v_mfma_f32_16x16x32_bf16 v[104:107], v[132:135], v[180:183], v[104:107]
	v_mfma_f32_16x16x32_bf16 v[92:95], v[112:115], v[184:187], v[92:95]
	v_mfma_f32_16x16x32_bf16 v[92:95], v[120:123], v[188:191], v[92:95]
	v_mfma_f32_16x16x32_bf16 v[88:91], v[128:131], v[184:187], v[88:91]
	v_mfma_f32_16x16x32_bf16 v[88:91], v[132:135], v[188:191], v[88:91]
	v_mfma_f32_16x16x32_bf16 v[76:79], v[112:115], v[192:195], v[76:79]
	v_mfma_f32_16x16x32_bf16 v[76:79], v[120:123], v[200:203], v[76:79]
	v_mfma_f32_16x16x32_bf16 v[72:75], v[128:131], v[192:195], v[72:75]
	v_mfma_f32_16x16x32_bf16 v[72:75], v[132:135], v[200:203], v[72:75]
	s_setprio 0
	s_setprio 1
	v_mfma_f32_16x16x32_bf16 v[124:127], v[144:147], v[168:171], v[124:127]
	v_mfma_f32_16x16x32_bf16 v[124:127], v[156:159], v[172:175], v[124:127]
	v_mfma_f32_16x16x32_bf16 v[116:119], v[160:163], v[168:171], v[116:119]
	v_mfma_f32_16x16x32_bf16 v[116:119], v[164:167], v[172:175], v[116:119]
	v_mfma_f32_16x16x32_bf16 v[100:103], v[144:147], v[176:179], v[100:103]
	v_mfma_f32_16x16x32_bf16 v[100:103], v[156:159], v[180:183], v[100:103]
	v_mfma_f32_16x16x32_bf16 v[96:99], v[160:163], v[176:179], v[96:99]
	v_mfma_f32_16x16x32_bf16 v[96:99], v[164:167], v[180:183], v[96:99]
	v_mfma_f32_16x16x32_bf16 v[84:87], v[144:147], v[184:187], v[84:87]
	v_mfma_f32_16x16x32_bf16 v[84:87], v[156:159], v[188:191], v[84:87]
	v_mfma_f32_16x16x32_bf16 v[80:83], v[160:163], v[184:187], v[80:83]
	v_mfma_f32_16x16x32_bf16 v[80:83], v[164:167], v[188:191], v[80:83]
	v_mfma_f32_16x16x32_bf16 v[68:71], v[144:147], v[192:195], v[68:71]
	v_mfma_f32_16x16x32_bf16 v[68:71], v[156:159], v[200:203], v[68:71]
	v_mfma_f32_16x16x32_bf16 v[64:67], v[160:163], v[192:195], v[64:67]
	v_mfma_f32_16x16x32_bf16 v[64:67], v[164:167], v[200:203], v[64:67]
	s_setprio 0
	s_barrier
	s_add_i32 s65, s65, s97
	s_mov_b64 s[70:71], s[36:37]
	s_mov_b32 m0, s65
	ds_read_b128 v[168:171], v155 offset:16384
	ds_read_b128 v[172:175], v155 offset:17408
	ds_read_b128 v[176:179], v155 offset:18432
	ds_read_b128 v[180:183], v155 offset:19456
	ds_read_b128 v[184:187], v155 offset:20480
	ds_read_b128 v[188:191], v155 offset:21504
	ds_read_b128 v[192:195], v155 offset:22528
	ds_read_b128 v[200:203], v155 offset:23552
	s_nop 0
	global_load_lds_dwordx4 v152, s[70:71]
	s_add_i32 m0, s65, 0x2000
	s_nop 0
	global_load_lds_dwordx4 v153, s[70:71]
	s_add_u32 s70, s36, 0x80000
	s_addc_u32 s71, s37, 0
	s_add_i32 s65, s69, s97
	s_mov_b32 m0, s65
	s_nop 0
	global_load_lds_dwordx4 v152, s[70:71]
	s_add_i32 m0, s65, 0x2000
	s_nop 0
	global_load_lds_dwordx4 v153, s[70:71]
	s_mov_b64 s[70:71], s[38:39]
	s_mov_b32 m0, s27
	s_nop 0
	global_load_lds_dwordx4 v151, s[70:71]
	s_mov_b32 m0, s29
	s_nop 0
	global_load_lds_dwordx4 v150, s[70:71]
	s_waitcnt vmcnt(8)
	s_waitcnt lgkmcnt(0)
	s_barrier
	s_setprio 1
	s_waitcnt lgkmcnt(0)
	v_mfma_f32_16x16x32_bf16 v[60:63], v[112:115], v[168:171], v[60:63]
	v_mfma_f32_16x16x32_bf16 v[60:63], v[120:123], v[172:175], v[60:63]
	v_mfma_f32_16x16x32_bf16 v[56:59], v[128:131], v[168:171], v[56:59]
	v_mfma_f32_16x16x32_bf16 v[56:59], v[132:135], v[172:175], v[56:59]
	v_mfma_f32_16x16x32_bf16 v[52:55], v[112:115], v[176:179], v[52:55]
	v_mfma_f32_16x16x32_bf16 v[52:55], v[120:123], v[180:183], v[52:55]
	v_mfma_f32_16x16x32_bf16 v[44:47], v[128:131], v[176:179], v[44:47]
	v_mfma_f32_16x16x32_bf16 v[44:47], v[132:135], v[180:183], v[44:47]
	v_mfma_f32_16x16x32_bf16 v[36:39], v[112:115], v[184:187], v[36:39]
	v_mfma_f32_16x16x32_bf16 v[36:39], v[120:123], v[188:191], v[36:39]
	v_mfma_f32_16x16x32_bf16 v[28:31], v[128:131], v[184:187], v[28:31]
	v_mfma_f32_16x16x32_bf16 v[28:31], v[132:135], v[188:191], v[28:31]
	v_mfma_f32_16x16x32_bf16 v[20:23], v[112:115], v[192:195], v[20:23]
	v_mfma_f32_16x16x32_bf16 v[20:23], v[120:123], v[200:203], v[20:23]
	v_mfma_f32_16x16x32_bf16 v[8:11], v[128:131], v[192:195], v[8:11]
	v_mfma_f32_16x16x32_bf16 v[8:11], v[132:135], v[200:203], v[8:11]
	s_setprio 0
	s_setprio 1
	v_mfma_f32_16x16x32_bf16 v[48:51], v[144:147], v[168:171], v[48:51]
	v_mfma_f32_16x16x32_bf16 v[48:51], v[156:159], v[172:175], v[48:51]
	v_mfma_f32_16x16x32_bf16 v[40:43], v[160:163], v[168:171], v[40:43]
	v_mfma_f32_16x16x32_bf16 v[40:43], v[164:167], v[172:175], v[40:43]
	v_mfma_f32_16x16x32_bf16 v[32:35], v[144:147], v[176:179], v[32:35]
	v_mfma_f32_16x16x32_bf16 v[32:35], v[156:159], v[180:183], v[32:35]
	v_mfma_f32_16x16x32_bf16 v[24:27], v[160:163], v[176:179], v[24:27]
	v_mfma_f32_16x16x32_bf16 v[24:27], v[164:167], v[180:183], v[24:27]
	v_mfma_f32_16x16x32_bf16 v[16:19], v[144:147], v[184:187], v[16:19]
	v_mfma_f32_16x16x32_bf16 v[16:19], v[156:159], v[188:191], v[16:19]
	v_mfma_f32_16x16x32_bf16 v[12:15], v[160:163], v[184:187], v[12:15]
	v_mfma_f32_16x16x32_bf16 v[12:15], v[164:167], v[188:191], v[12:15]
	v_mfma_f32_16x16x32_bf16 v[4:7], v[144:147], v[192:195], v[4:7]
	v_mfma_f32_16x16x32_bf16 v[4:7], v[156:159], v[200:203], v[4:7]
	v_mfma_f32_16x16x32_bf16 v[0:3], v[160:163], v[192:195], v[0:3]
	v_mfma_f32_16x16x32_bf16 v[0:3], v[164:167], v[200:203], v[0:3]
	s_setprio 0
	s_barrier
	s_add_i32 s65, 0, 0x18000
	s_add_i32 s69, 0, 0x1c000
	v_add_u32_e32 v132, s65, v154
	v_add_u32_e32 v148, s69, v154
	ds_read_b128 v[112:115], v132
	ds_read_b128 v[120:123], v132 offset:1024
	ds_read_b128 v[128:131], v132 offset:2048
	ds_read_b128 v[132:135], v132 offset:3072
	ds_read_b128 v[144:147], v148
	ds_read_b128 v[156:159], v148 offset:1024
	ds_read_b128 v[160:163], v148 offset:2048
	ds_read_b128 v[164:167], v148 offset:3072
	s_add_u32 s38, s38, 0x80000
	s_addc_u32 s39, s39, 0
	s_mov_b32 m0, s31
	ds_read_b128 v[168:171], v155 offset:32768
	ds_read_b128 v[172:175], v155 offset:33792
	ds_read_b128 v[176:179], v155 offset:34816
	ds_read_b128 v[180:183], v155 offset:35840
	ds_read_b128 v[184:187], v155 offset:36864
	ds_read_b128 v[188:191], v155 offset:37888
	ds_read_b128 v[192:195], v155 offset:38912
	ds_read_b128 v[200:203], v155 offset:39936
	s_nop 0
	global_load_lds_dwordx4 v151, s[38:39]
	s_mov_b32 m0, s48
	s_nop 0
	global_load_lds_dwordx4 v150, s[38:39]
	s_waitcnt vmcnt(8)
	s_waitcnt lgkmcnt(0)
	s_barrier
	s_setprio 1
	s_waitcnt lgkmcnt(0)
	v_mfma_f32_16x16x32_bf16 v[140:143], v[112:115], v[168:171], v[140:143]
	v_mfma_f32_16x16x32_bf16 v[140:143], v[120:123], v[172:175], v[140:143]
	v_mfma_f32_16x16x32_bf16 v[136:139], v[128:131], v[168:171], v[136:139]
	v_mfma_f32_16x16x32_bf16 v[136:139], v[132:135], v[172:175], v[136:139]
	v_mfma_f32_16x16x32_bf16 v[108:111], v[112:115], v[176:179], v[108:111]
	v_mfma_f32_16x16x32_bf16 v[108:111], v[120:123], v[180:183], v[108:111]
	v_mfma_f32_16x16x32_bf16 v[104:107], v[128:131], v[176:179], v[104:107]
	v_mfma_f32_16x16x32_bf16 v[104:107], v[132:135], v[180:183], v[104:107]
	v_mfma_f32_16x16x32_bf16 v[92:95], v[112:115], v[184:187], v[92:95]
	v_mfma_f32_16x16x32_bf16 v[92:95], v[120:123], v[188:191], v[92:95]
	v_mfma_f32_16x16x32_bf16 v[88:91], v[128:131], v[184:187], v[88:91]
	v_mfma_f32_16x16x32_bf16 v[88:91], v[132:135], v[188:191], v[88:91]
	v_mfma_f32_16x16x32_bf16 v[76:79], v[112:115], v[192:195], v[76:79]
	v_mfma_f32_16x16x32_bf16 v[76:79], v[120:123], v[200:203], v[76:79]
	v_mfma_f32_16x16x32_bf16 v[72:75], v[128:131], v[192:195], v[72:75]
	v_mfma_f32_16x16x32_bf16 v[72:75], v[132:135], v[200:203], v[72:75]
	s_setprio 0
	s_setprio 1
	v_mfma_f32_16x16x32_bf16 v[124:127], v[144:147], v[168:171], v[124:127]
	v_mfma_f32_16x16x32_bf16 v[124:127], v[156:159], v[172:175], v[124:127]
	v_mfma_f32_16x16x32_bf16 v[116:119], v[160:163], v[168:171], v[116:119]
	v_mfma_f32_16x16x32_bf16 v[116:119], v[164:167], v[172:175], v[116:119]
	v_mfma_f32_16x16x32_bf16 v[100:103], v[144:147], v[176:179], v[100:103]
	v_mfma_f32_16x16x32_bf16 v[100:103], v[156:159], v[180:183], v[100:103]
	v_mfma_f32_16x16x32_bf16 v[96:99], v[160:163], v[176:179], v[96:99]
	v_mfma_f32_16x16x32_bf16 v[96:99], v[164:167], v[180:183], v[96:99]
	v_mfma_f32_16x16x32_bf16 v[84:87], v[144:147], v[184:187], v[84:87]
	v_mfma_f32_16x16x32_bf16 v[84:87], v[156:159], v[188:191], v[84:87]
	v_mfma_f32_16x16x32_bf16 v[80:83], v[160:163], v[184:187], v[80:83]
	v_mfma_f32_16x16x32_bf16 v[80:83], v[164:167], v[188:191], v[80:83]
	v_mfma_f32_16x16x32_bf16 v[68:71], v[144:147], v[192:195], v[68:71]
	v_mfma_f32_16x16x32_bf16 v[68:71], v[156:159], v[200:203], v[68:71]
	v_mfma_f32_16x16x32_bf16 v[64:67], v[160:163], v[192:195], v[64:67]
	v_mfma_f32_16x16x32_bf16 v[64:67], v[164:167], v[200:203], v[64:67]
	s_setprio 0
	s_barrier
	s_add_u32 s38, s36, 0x80
	s_addc_u32 s39, s37, 0
	s_add_i32 s65, s65, s97
	s_mov_b32 m0, s65
	ds_read_b128 v[168:171], v155 offset:49152
	ds_read_b128 v[172:175], v155 offset:50176
	ds_read_b128 v[176:179], v155 offset:51200
	ds_read_b128 v[180:183], v155 offset:52224
	ds_read_b128 v[184:187], v155 offset:53248
	ds_read_b128 v[188:191], v155 offset:54272
	ds_read_b128 v[192:195], v155 offset:55296
	ds_read_b128 v[200:203], v155 offset:56320
	s_nop 0
	global_load_lds_dwordx4 v152, s[38:39]
	s_add_i32 m0, s65, 0x2000
	s_add_u32 s36, s36, 0x80080
	s_addc_u32 s37, s37, 0
	global_load_lds_dwordx4 v153, s[38:39]
	s_add_i32 s38, s69, s97
	s_mov_b32 m0, s38
	s_nop 0
	global_load_lds_dwordx4 v152, s[36:37]
	s_add_i32 m0, s38, 0x2000
	s_nop 0
	global_load_lds_dwordx4 v153, s[36:37]
	s_mov_b32 m0, s49
	s_nop 0
	global_load_lds_dwordx4 v151, s[34:35]
	s_mov_b32 m0, s56
	s_nop 0
	global_load_lds_dwordx4 v150, s[34:35]
	s_waitcnt vmcnt(8)
	s_waitcnt lgkmcnt(0)
	s_barrier
	s_setprio 1
	s_waitcnt lgkmcnt(0)
	v_mfma_f32_16x16x32_bf16 v[60:63], v[112:115], v[168:171], v[60:63]
	v_mfma_f32_16x16x32_bf16 v[60:63], v[120:123], v[172:175], v[60:63]
	v_mfma_f32_16x16x32_bf16 v[56:59], v[128:131], v[168:171], v[56:59]
	v_mfma_f32_16x16x32_bf16 v[56:59], v[132:135], v[172:175], v[56:59]
	v_mfma_f32_16x16x32_bf16 v[52:55], v[112:115], v[176:179], v[52:55]
	v_mfma_f32_16x16x32_bf16 v[52:55], v[120:123], v[180:183], v[52:55]
	v_mfma_f32_16x16x32_bf16 v[44:47], v[128:131], v[176:179], v[44:47]
	v_mfma_f32_16x16x32_bf16 v[44:47], v[132:135], v[180:183], v[44:47]
	v_mfma_f32_16x16x32_bf16 v[36:39], v[112:115], v[184:187], v[36:39]
	v_mfma_f32_16x16x32_bf16 v[36:39], v[120:123], v[188:191], v[36:39]
	v_mfma_f32_16x16x32_bf16 v[28:31], v[128:131], v[184:187], v[28:31]
	v_mfma_f32_16x16x32_bf16 v[28:31], v[132:135], v[188:191], v[28:31]
	v_mfma_f32_16x16x32_bf16 v[20:23], v[112:115], v[192:195], v[20:23]
	v_mfma_f32_16x16x32_bf16 v[20:23], v[120:123], v[200:203], v[20:23]
	v_mfma_f32_16x16x32_bf16 v[8:11], v[128:131], v[192:195], v[8:11]
	v_mfma_f32_16x16x32_bf16 v[8:11], v[132:135], v[200:203], v[8:11]
	s_setprio 0
	s_setprio 1
	v_mfma_f32_16x16x32_bf16 v[48:51], v[144:147], v[168:171], v[48:51]
	v_mfma_f32_16x16x32_bf16 v[48:51], v[156:159], v[172:175], v[48:51]
	v_mfma_f32_16x16x32_bf16 v[40:43], v[160:163], v[168:171], v[40:43]
	v_mfma_f32_16x16x32_bf16 v[40:43], v[164:167], v[172:175], v[40:43]
	v_mfma_f32_16x16x32_bf16 v[32:35], v[144:147], v[176:179], v[32:35]
	v_mfma_f32_16x16x32_bf16 v[32:35], v[156:159], v[180:183], v[32:35]
	v_mfma_f32_16x16x32_bf16 v[24:27], v[160:163], v[176:179], v[24:27]
	v_mfma_f32_16x16x32_bf16 v[24:27], v[164:167], v[180:183], v[24:27]
	v_mfma_f32_16x16x32_bf16 v[16:19], v[144:147], v[184:187], v[16:19]
	v_mfma_f32_16x16x32_bf16 v[16:19], v[156:159], v[188:191], v[16:19]
	v_mfma_f32_16x16x32_bf16 v[12:15], v[160:163], v[184:187], v[12:15]
	v_mfma_f32_16x16x32_bf16 v[12:15], v[164:167], v[188:191], v[12:15]
	v_mfma_f32_16x16x32_bf16 v[4:7], v[144:147], v[192:195], v[4:7]
	v_mfma_f32_16x16x32_bf16 v[4:7], v[156:159], v[200:203], v[4:7]
	v_mfma_f32_16x16x32_bf16 v[0:3], v[160:163], v[192:195], v[0:3]
	v_mfma_f32_16x16x32_bf16 v[0:3], v[164:167], v[200:203], v[0:3]
	s_setprio 0
	s_barrier
	s_add_i32 s21, s21, 2
	s_add_u32 s4, s4, 0x100
	s_addc_u32 s5, s5, 0
	s_add_u32 s15, s15, 0x100
	s_addc_u32 s17, s17, 0
	s_cmp_gt_u32 s21, 5
	s_cbranch_scc0 .LBB0_604
	s_and_b64 vcc, exec, s[60:61]
	s_cbranch_vccz .LBB0_607
	s_barrier

.LBB0_676:
	s_add_u32 s30, s28, 0x100
	s_addc_u32 s31, s29, 0
	s_cmp_eq_u32 s69, 28
	s_cselect_b32 s38, s5, s30
	s_cselect_b32 s39, s4, s31
	s_cselect_b32 s36, s17, s21
	s_cselect_b32 s37, s13, s27
	s_add_u32 s34, s38, 0x80
	s_addc_u32 s35, s39, 0
	s_add_i32 s74, 0, 0x10000
	s_add_i32 s84, 0, 0x14000
	v_add_u32_e32 v140, s74, v150
	v_add_u32_e32 v144, s84, v150
	ds_read_b128 v[128:131], v140
	ds_read_b128 v[132:135], v140 offset:1024
	ds_read_b128 v[136:139], v140 offset:2048
	ds_read_b128 v[140:143], v140 offset:3072
	ds_read_b128 v[152:155], v144
	ds_read_b128 v[156:159], v144 offset:1024
	ds_read_b128 v[160:163], v144 offset:2048
	ds_read_b128 v[164:167], v144 offset:3072
	s_add_u32 s28, s28, 0x80080
	s_addc_u32 s29, s29, 0
	s_add_i32 m0, s48, 0xc000
	ds_read_b128 v[168:171], v151
	ds_read_b128 v[172:175], v151 offset:1024
	ds_read_b128 v[176:179], v151 offset:2048
	ds_read_b128 v[180:183], v151 offset:3072
	ds_read_b128 v[184:187], v151 offset:4096
	ds_read_b128 v[188:191], v151 offset:5120
	ds_read_b128 v[192:195], v151 offset:6144
	ds_read_b128 v[200:203], v151 offset:7168
	s_nop 0
	global_load_lds_dwordx4 v146, s[28:29]
	s_add_i32 m0, s48, 0xe000
	s_nop 0
	global_load_lds_dwordx4 v148, s[28:29]
	s_waitcnt vmcnt(8)
	s_waitcnt lgkmcnt(0)
	s_barrier
	s_setprio 1
	s_waitcnt lgkmcnt(0)
	v_mfma_f32_16x16x32_bf16 v[124:127], v[128:131], v[168:171], v[124:127]
	v_mfma_f32_16x16x32_bf16 v[124:127], v[132:135], v[172:175], v[124:127]
	v_mfma_f32_16x16x32_bf16 v[120:123], v[136:139], v[168:171], v[120:123]
	v_mfma_f32_16x16x32_bf16 v[120:123], v[140:143], v[172:175], v[120:123]
	v_mfma_f32_16x16x32_bf16 v[108:111], v[128:131], v[176:179], v[108:111]
	v_mfma_f32_16x16x32_bf16 v[108:111], v[132:135], v[180:183], v[108:111]
	v_mfma_f32_16x16x32_bf16 v[104:107], v[136:139], v[176:179], v[104:107]
	v_mfma_f32_16x16x32_bf16 v[104:107], v[140:143], v[180:183], v[104:107]
	v_mfma_f32_16x16x32_bf16 v[96:99], v[128:131], v[184:187], v[96:99]
	v_mfma_f32_16x16x32_bf16 v[96:99], v[132:135], v[188:191], v[96:99]
	v_mfma_f32_16x16x32_bf16 v[88:91], v[136:139], v[184:187], v[88:91]
	v_mfma_f32_16x16x32_bf16 v[88:91], v[140:143], v[188:191], v[88:91]
	v_mfma_f32_16x16x32_bf16 v[80:83], v[128:131], v[192:195], v[80:83]
	v_mfma_f32_16x16x32_bf16 v[80:83], v[132:135], v[200:203], v[80:83]
	v_mfma_f32_16x16x32_bf16 v[72:75], v[136:139], v[192:195], v[72:75]
	v_mfma_f32_16x16x32_bf16 v[72:75], v[140:143], v[200:203], v[72:75]
	s_setprio 0
	s_setprio 1
	v_mfma_f32_16x16x32_bf16 v[116:119], v[152:155], v[168:171], v[116:119]
	v_mfma_f32_16x16x32_bf16 v[116:119], v[156:159], v[172:175], v[116:119]
	v_mfma_f32_16x16x32_bf16 v[112:115], v[160:163], v[168:171], v[112:115]
	v_mfma_f32_16x16x32_bf16 v[112:115], v[164:167], v[172:175], v[112:115]
	v_mfma_f32_16x16x32_bf16 v[100:103], v[152:155], v[176:179], v[100:103]
	v_mfma_f32_16x16x32_bf16 v[100:103], v[156:159], v[180:183], v[100:103]
	v_mfma_f32_16x16x32_bf16 v[92:95], v[160:163], v[176:179], v[92:95]
	v_mfma_f32_16x16x32_bf16 v[92:95], v[164:167], v[180:183], v[92:95]
	v_mfma_f32_16x16x32_bf16 v[84:87], v[152:155], v[184:187], v[84:87]
	v_mfma_f32_16x16x32_bf16 v[84:87], v[156:159], v[188:191], v[84:87]
	v_mfma_f32_16x16x32_bf16 v[76:79], v[160:163], v[184:187], v[76:79]
	v_mfma_f32_16x16x32_bf16 v[76:79], v[164:167], v[188:191], v[76:79]
	v_mfma_f32_16x16x32_bf16 v[68:71], v[152:155], v[192:195], v[68:71]
	v_mfma_f32_16x16x32_bf16 v[68:71], v[156:159], v[200:203], v[68:71]
	v_mfma_f32_16x16x32_bf16 v[64:67], v[160:163], v[192:195], v[64:67]
	v_mfma_f32_16x16x32_bf16 v[64:67], v[164:167], v[200:203], v[64:67]
	s_setprio 0
	s_barrier
	s_add_i32 s74, s74, s97
	s_mov_b64 s[28:29], s[36:37]
	s_mov_b32 m0, s74
	ds_read_b128 v[168:171], v151 offset:16384
	ds_read_b128 v[172:175], v151 offset:17408
	ds_read_b128 v[176:179], v151 offset:18432
	ds_read_b128 v[180:183], v151 offset:19456
	ds_read_b128 v[184:187], v151 offset:20480
	ds_read_b128 v[188:191], v151 offset:21504
	ds_read_b128 v[192:195], v151 offset:22528
	ds_read_b128 v[200:203], v151 offset:23552
	s_nop 0
	global_load_lds_dwordx4 v147, s[28:29]
	s_add_i32 m0, s74, 0x2000
	s_nop 0
	global_load_lds_dwordx4 v149, s[28:29]
	s_add_u32 s28, s36, 0x80000
	s_addc_u32 s29, s37, 0
	s_add_i32 s74, s84, s97
	s_mov_b32 m0, s74
	s_nop 0
	global_load_lds_dwordx4 v147, s[28:29]
	s_add_i32 m0, s74, 0x2000
	s_nop 0
	global_load_lds_dwordx4 v149, s[28:29]
	s_mov_b64 s[28:29], s[38:39]
	s_mov_b32 m0, s48
	s_nop 0
	global_load_lds_dwordx4 v146, s[28:29]
	s_mov_b32 m0, s49
	s_nop 0
	global_load_lds_dwordx4 v148, s[28:29]
	s_waitcnt vmcnt(8)
	s_waitcnt lgkmcnt(0)
	s_barrier
	s_setprio 1
	s_waitcnt lgkmcnt(0)
	v_mfma_f32_16x16x32_bf16 v[60:63], v[128:131], v[168:171], v[60:63]
	v_mfma_f32_16x16x32_bf16 v[60:63], v[132:135], v[172:175], v[60:63]
	v_mfma_f32_16x16x32_bf16 v[56:59], v[136:139], v[168:171], v[56:59]
	v_mfma_f32_16x16x32_bf16 v[56:59], v[140:143], v[172:175], v[56:59]
	v_mfma_f32_16x16x32_bf16 v[48:51], v[128:131], v[176:179], v[48:51]
	v_mfma_f32_16x16x32_bf16 v[48:51], v[132:135], v[180:183], v[48:51]
	v_mfma_f32_16x16x32_bf16 v[40:43], v[136:139], v[176:179], v[40:43]
	v_mfma_f32_16x16x32_bf16 v[40:43], v[140:143], v[180:183], v[40:43]
	v_mfma_f32_16x16x32_bf16 v[32:35], v[128:131], v[184:187], v[32:35]
	v_mfma_f32_16x16x32_bf16 v[32:35], v[132:135], v[188:191], v[32:35]
	v_mfma_f32_16x16x32_bf16 v[24:27], v[136:139], v[184:187], v[24:27]
	v_mfma_f32_16x16x32_bf16 v[24:27], v[140:143], v[188:191], v[24:27]
	v_mfma_f32_16x16x32_bf16 v[16:19], v[128:131], v[192:195], v[16:19]
	v_mfma_f32_16x16x32_bf16 v[16:19], v[132:135], v[200:203], v[16:19]
	v_mfma_f32_16x16x32_bf16 v[8:11], v[136:139], v[192:195], v[8:11]
	v_mfma_f32_16x16x32_bf16 v[8:11], v[140:143], v[200:203], v[8:11]
	s_setprio 0
	s_setprio 1
	v_mfma_f32_16x16x32_bf16 v[52:55], v[152:155], v[168:171], v[52:55]
	v_mfma_f32_16x16x32_bf16 v[52:55], v[156:159], v[172:175], v[52:55]
	v_mfma_f32_16x16x32_bf16 v[44:47], v[160:163], v[168:171], v[44:47]
	v_mfma_f32_16x16x32_bf16 v[44:47], v[164:167], v[172:175], v[44:47]
	v_mfma_f32_16x16x32_bf16 v[36:39], v[152:155], v[176:179], v[36:39]
	v_mfma_f32_16x16x32_bf16 v[36:39], v[156:159], v[180:183], v[36:39]
	v_mfma_f32_16x16x32_bf16 v[28:31], v[160:163], v[176:179], v[28:31]
	v_mfma_f32_16x16x32_bf16 v[28:31], v[164:167], v[180:183], v[28:31]
	v_mfma_f32_16x16x32_bf16 v[20:23], v[152:155], v[184:187], v[20:23]
	v_mfma_f32_16x16x32_bf16 v[20:23], v[156:159], v[188:191], v[20:23]
	v_mfma_f32_16x16x32_bf16 v[12:15], v[160:163], v[184:187], v[12:15]
	v_mfma_f32_16x16x32_bf16 v[12:15], v[164:167], v[188:191], v[12:15]
	v_mfma_f32_16x16x32_bf16 v[4:7], v[152:155], v[192:195], v[4:7]
	v_mfma_f32_16x16x32_bf16 v[4:7], v[156:159], v[200:203], v[4:7]
	v_mfma_f32_16x16x32_bf16 v[0:3], v[160:163], v[192:195], v[0:3]
	v_mfma_f32_16x16x32_bf16 v[0:3], v[164:167], v[200:203], v[0:3]
	s_setprio 0
	s_barrier
	s_add_i32 s74, 0, 0x18000
	s_add_i32 s84, 0, 0x1c000
	v_add_u32_e32 v140, s74, v150
	v_add_u32_e32 v144, s84, v150
	ds_read_b128 v[128:131], v140
	ds_read_b128 v[132:135], v140 offset:1024
	ds_read_b128 v[136:139], v140 offset:2048
	ds_read_b128 v[140:143], v140 offset:3072
	ds_read_b128 v[152:155], v144
	ds_read_b128 v[156:159], v144 offset:1024
	ds_read_b128 v[160:163], v144 offset:2048
	ds_read_b128 v[164:167], v144 offset:3072
	s_add_u32 s28, s38, 0x80000
	s_addc_u32 s29, s39, 0
	s_mov_b32 m0, s56
	ds_read_b128 v[168:171], v151 offset:32768
	ds_read_b128 v[172:175], v151 offset:33792
	ds_read_b128 v[176:179], v151 offset:34816
	ds_read_b128 v[180:183], v151 offset:35840
	ds_read_b128 v[184:187], v151 offset:36864
	ds_read_b128 v[188:191], v151 offset:37888
	ds_read_b128 v[192:195], v151 offset:38912
	ds_read_b128 v[200:203], v151 offset:39936
	s_nop 0
	global_load_lds_dwordx4 v146, s[28:29]
	s_mov_b32 m0, s57
	s_nop 0
	global_load_lds_dwordx4 v148, s[28:29]
	s_waitcnt vmcnt(8)
	s_waitcnt lgkmcnt(0)
	s_barrier
	s_setprio 1
	s_waitcnt lgkmcnt(0)
	v_mfma_f32_16x16x32_bf16 v[124:127], v[128:131], v[168:171], v[124:127]
	v_mfma_f32_16x16x32_bf16 v[124:127], v[132:135], v[172:175], v[124:127]
	v_mfma_f32_16x16x32_bf16 v[120:123], v[136:139], v[168:171], v[120:123]
	v_mfma_f32_16x16x32_bf16 v[120:123], v[140:143], v[172:175], v[120:123]
	v_mfma_f32_16x16x32_bf16 v[108:111], v[128:131], v[176:179], v[108:111]
	v_mfma_f32_16x16x32_bf16 v[108:111], v[132:135], v[180:183], v[108:111]
	v_mfma_f32_16x16x32_bf16 v[104:107], v[136:139], v[176:179], v[104:107]
	v_mfma_f32_16x16x32_bf16 v[104:107], v[140:143], v[180:183], v[104:107]
	v_mfma_f32_16x16x32_bf16 v[96:99], v[128:131], v[184:187], v[96:99]
	v_mfma_f32_16x16x32_bf16 v[96:99], v[132:135], v[188:191], v[96:99]
	v_mfma_f32_16x16x32_bf16 v[88:91], v[136:139], v[184:187], v[88:91]
	v_mfma_f32_16x16x32_bf16 v[88:91], v[140:143], v[188:191], v[88:91]
	v_mfma_f32_16x16x32_bf16 v[80:83], v[128:131], v[192:195], v[80:83]
	v_mfma_f32_16x16x32_bf16 v[80:83], v[132:135], v[200:203], v[80:83]
	v_mfma_f32_16x16x32_bf16 v[72:75], v[136:139], v[192:195], v[72:75]
	v_mfma_f32_16x16x32_bf16 v[72:75], v[140:143], v[200:203], v[72:75]
	s_setprio 0
	s_setprio 1
	v_mfma_f32_16x16x32_bf16 v[116:119], v[152:155], v[168:171], v[116:119]
	v_mfma_f32_16x16x32_bf16 v[116:119], v[156:159], v[172:175], v[116:119]
	v_mfma_f32_16x16x32_bf16 v[112:115], v[160:163], v[168:171], v[112:115]
	v_mfma_f32_16x16x32_bf16 v[112:115], v[164:167], v[172:175], v[112:115]
	v_mfma_f32_16x16x32_bf16 v[100:103], v[152:155], v[176:179], v[100:103]
	v_mfma_f32_16x16x32_bf16 v[100:103], v[156:159], v[180:183], v[100:103]
	v_mfma_f32_16x16x32_bf16 v[92:95], v[160:163], v[176:179], v[92:95]
	v_mfma_f32_16x16x32_bf16 v[92:95], v[164:167], v[180:183], v[92:95]
	v_mfma_f32_16x16x32_bf16 v[84:87], v[152:155], v[184:187], v[84:87]
	v_mfma_f32_16x16x32_bf16 v[84:87], v[156:159], v[188:191], v[84:87]
	v_mfma_f32_16x16x32_bf16 v[76:79], v[160:163], v[184:187], v[76:79]
	v_mfma_f32_16x16x32_bf16 v[76:79], v[164:167], v[188:191], v[76:79]
	v_mfma_f32_16x16x32_bf16 v[68:71], v[152:155], v[192:195], v[68:71]
	v_mfma_f32_16x16x32_bf16 v[68:71], v[156:159], v[200:203], v[68:71]
	v_mfma_f32_16x16x32_bf16 v[64:67], v[160:163], v[192:195], v[64:67]
	v_mfma_f32_16x16x32_bf16 v[64:67], v[164:167], v[200:203], v[64:67]
	s_setprio 0
	s_barrier
	s_add_u32 s28, s36, 0x80
	s_addc_u32 s29, s37, 0
	s_add_i32 s38, s74, s97
	s_mov_b32 m0, s38
	ds_read_b128 v[168:171], v151 offset:49152
	ds_read_b128 v[172:175], v151 offset:50176
	ds_read_b128 v[176:179], v151 offset:51200
	ds_read_b128 v[180:183], v151 offset:52224
	ds_read_b128 v[184:187], v151 offset:53248
	ds_read_b128 v[188:191], v151 offset:54272
	ds_read_b128 v[192:195], v151 offset:55296
	ds_read_b128 v[200:203], v151 offset:56320
	s_nop 0
	global_load_lds_dwordx4 v147, s[28:29]
	s_add_i32 m0, s38, 0x2000
	s_nop 0
	global_load_lds_dwordx4 v149, s[28:29]
	s_add_u32 s28, s36, 0x80080
	s_addc_u32 s29, s37, 0
	s_add_i32 s36, s84, s97
	s_mov_b32 m0, s36
	s_nop 0
	global_load_lds_dwordx4 v147, s[28:29]
	s_add_i32 m0, s36, 0x2000
	s_nop 0
	global_load_lds_dwordx4 v149, s[28:29]
	s_mov_b32 m0, s82
	s_nop 0
	global_load_lds_dwordx4 v146, s[34:35]
	s_mov_b32 m0, s83
	s_nop 0
	global_load_lds_dwordx4 v148, s[34:35]
	s_waitcnt vmcnt(8)
	s_waitcnt lgkmcnt(0)
	s_barrier
	s_setprio 1
	s_waitcnt lgkmcnt(0)
	v_mfma_f32_16x16x32_bf16 v[60:63], v[128:131], v[168:171], v[60:63]
	v_mfma_f32_16x16x32_bf16 v[60:63], v[132:135], v[172:175], v[60:63]
	v_mfma_f32_16x16x32_bf16 v[56:59], v[136:139], v[168:171], v[56:59]
	v_mfma_f32_16x16x32_bf16 v[56:59], v[140:143], v[172:175], v[56:59]
	v_mfma_f32_16x16x32_bf16 v[48:51], v[128:131], v[176:179], v[48:51]
	v_mfma_f32_16x16x32_bf16 v[48:51], v[132:135], v[180:183], v[48:51]
	v_mfma_f32_16x16x32_bf16 v[40:43], v[136:139], v[176:179], v[40:43]
	v_mfma_f32_16x16x32_bf16 v[40:43], v[140:143], v[180:183], v[40:43]
	v_mfma_f32_16x16x32_bf16 v[32:35], v[128:131], v[184:187], v[32:35]
	v_mfma_f32_16x16x32_bf16 v[32:35], v[132:135], v[188:191], v[32:35]
	v_mfma_f32_16x16x32_bf16 v[24:27], v[136:139], v[184:187], v[24:27]
	v_mfma_f32_16x16x32_bf16 v[24:27], v[140:143], v[188:191], v[24:27]
	v_mfma_f32_16x16x32_bf16 v[16:19], v[128:131], v[192:195], v[16:19]
	v_mfma_f32_16x16x32_bf16 v[16:19], v[132:135], v[200:203], v[16:19]
	v_mfma_f32_16x16x32_bf16 v[8:11], v[136:139], v[192:195], v[8:11]
	v_mfma_f32_16x16x32_bf16 v[8:11], v[140:143], v[200:203], v[8:11]
	s_setprio 0
	s_setprio 1
	v_mfma_f32_16x16x32_bf16 v[52:55], v[152:155], v[168:171], v[52:55]
	v_mfma_f32_16x16x32_bf16 v[52:55], v[156:159], v[172:175], v[52:55]
	v_mfma_f32_16x16x32_bf16 v[44:47], v[160:163], v[168:171], v[44:47]
	v_mfma_f32_16x16x32_bf16 v[44:47], v[164:167], v[172:175], v[44:47]
	v_mfma_f32_16x16x32_bf16 v[36:39], v[152:155], v[176:179], v[36:39]
	v_mfma_f32_16x16x32_bf16 v[36:39], v[156:159], v[180:183], v[36:39]
	v_mfma_f32_16x16x32_bf16 v[28:31], v[160:163], v[176:179], v[28:31]
	v_mfma_f32_16x16x32_bf16 v[28:31], v[164:167], v[180:183], v[28:31]
	v_mfma_f32_16x16x32_bf16 v[20:23], v[152:155], v[184:187], v[20:23]
	v_mfma_f32_16x16x32_bf16 v[20:23], v[156:159], v[188:191], v[20:23]
	v_mfma_f32_16x16x32_bf16 v[12:15], v[160:163], v[184:187], v[12:15]
	v_mfma_f32_16x16x32_bf16 v[12:15], v[164:167], v[188:191], v[12:15]
	v_mfma_f32_16x16x32_bf16 v[4:7], v[152:155], v[192:195], v[4:7]
	v_mfma_f32_16x16x32_bf16 v[4:7], v[156:159], v[200:203], v[4:7]
	v_mfma_f32_16x16x32_bf16 v[0:3], v[160:163], v[192:195], v[0:3]
	v_mfma_f32_16x16x32_bf16 v[0:3], v[164:167], v[200:203], v[0:3]
	s_setprio 0
	s_barrier
	s_add_i32 s69, s69, 2
	s_add_u32 s21, s21, 0x100
	s_addc_u32 s27, s27, 0
	s_cmp_gt_u32 s69, 29
	s_mov_b64 s[28:29], s[30:31]
	s_cbranch_scc0 .LBB0_676
	s_and_b64 vcc, exec, s[60:61]
	s_cbranch_vccz .LBB0_679
	s_barrier

.LBB0_788:
	s_add_u32 s30, s28, 0x100
	s_addc_u32 s31, s29, 0
	s_cmp_eq_u32 s17, 4
	s_cselect_b32 s38, s20, s30
	s_cselect_b32 s39, s21, s31
	s_cselect_b32 s36, s22, s5
	s_cselect_b32 s37, s23, s15
	s_add_u32 s34, s38, 0x80
	s_addc_u32 s35, s39, 0
	s_add_i32 s83, 0, 0x10000
	s_add_i32 s84, 0, 0x14000
	v_add_u32_e32 v146, s83, v136
	v_add_u32_e32 v162, s84, v136
	ds_read_b128 v[128:131], v146
	ds_read_b128 v[138:141], v146 offset:1024
	ds_read_b128 v[142:145], v146 offset:2048
	ds_read_b128 v[146:149], v146 offset:3072
	ds_read_b128 v[150:153], v162
	ds_read_b128 v[154:157], v162 offset:1024
	ds_read_b128 v[158:161], v162 offset:2048
	ds_read_b128 v[162:165], v162 offset:3072
	s_add_u32 s28, s28, 0x20080
	s_addc_u32 s29, s29, 0
	s_add_i32 m0, s27, 0xc000
	ds_read_b128 v[166:169], v137
	ds_read_b128 v[170:173], v137 offset:1024
	ds_read_b128 v[174:177], v137 offset:2048
	ds_read_b128 v[178:181], v137 offset:3072
	ds_read_b128 v[182:185], v137 offset:4096
	ds_read_b128 v[186:189], v137 offset:5120
	ds_read_b128 v[190:193], v137 offset:6144
	ds_read_b128 v[200:203], v137 offset:7168
	s_nop 0
	global_load_lds_dwordx4 v132, s[28:29]
	s_add_i32 m0, s27, 0xe000
	s_nop 0
	global_load_lds_dwordx4 v134, s[28:29]
	s_waitcnt vmcnt(8)
	s_waitcnt lgkmcnt(0)
	s_barrier
	s_setprio 1
	s_waitcnt lgkmcnt(0)
	v_mfma_f32_16x16x32_bf16 v[124:127], v[128:131], v[166:169], v[124:127]
	v_mfma_f32_16x16x32_bf16 v[124:127], v[138:141], v[170:173], v[124:127]
	v_mfma_f32_16x16x32_bf16 v[120:123], v[142:145], v[166:169], v[120:123]
	v_mfma_f32_16x16x32_bf16 v[120:123], v[146:149], v[170:173], v[120:123]
	v_mfma_f32_16x16x32_bf16 v[108:111], v[128:131], v[174:177], v[108:111]
	v_mfma_f32_16x16x32_bf16 v[108:111], v[138:141], v[178:181], v[108:111]
	v_mfma_f32_16x16x32_bf16 v[104:107], v[142:145], v[174:177], v[104:107]
	v_mfma_f32_16x16x32_bf16 v[104:107], v[146:149], v[178:181], v[104:107]
	v_mfma_f32_16x16x32_bf16 v[92:95], v[128:131], v[182:185], v[92:95]
	v_mfma_f32_16x16x32_bf16 v[92:95], v[138:141], v[186:189], v[92:95]
	v_mfma_f32_16x16x32_bf16 v[88:91], v[142:145], v[182:185], v[88:91]
	v_mfma_f32_16x16x32_bf16 v[88:91], v[146:149], v[186:189], v[88:91]
	v_mfma_f32_16x16x32_bf16 v[76:79], v[128:131], v[190:193], v[76:79]
	v_mfma_f32_16x16x32_bf16 v[76:79], v[138:141], v[200:203], v[76:79]
	v_mfma_f32_16x16x32_bf16 v[72:75], v[142:145], v[190:193], v[72:75]
	v_mfma_f32_16x16x32_bf16 v[72:75], v[146:149], v[200:203], v[72:75]
	s_setprio 0
	s_setprio 1
	v_mfma_f32_16x16x32_bf16 v[116:119], v[150:153], v[166:169], v[116:119]
	v_mfma_f32_16x16x32_bf16 v[116:119], v[154:157], v[170:173], v[116:119]
	v_mfma_f32_16x16x32_bf16 v[112:115], v[158:161], v[166:169], v[112:115]
	v_mfma_f32_16x16x32_bf16 v[112:115], v[162:165], v[170:173], v[112:115]
	v_mfma_f32_16x16x32_bf16 v[100:103], v[150:153], v[174:177], v[100:103]
	v_mfma_f32_16x16x32_bf16 v[100:103], v[154:157], v[178:181], v[100:103]
	v_mfma_f32_16x16x32_bf16 v[96:99], v[158:161], v[174:177], v[96:99]
	v_mfma_f32_16x16x32_bf16 v[96:99], v[162:165], v[178:181], v[96:99]
	v_mfma_f32_16x16x32_bf16 v[84:87], v[150:153], v[182:185], v[84:87]
	v_mfma_f32_16x16x32_bf16 v[84:87], v[154:157], v[186:189], v[84:87]
	v_mfma_f32_16x16x32_bf16 v[80:83], v[158:161], v[182:185], v[80:83]
	v_mfma_f32_16x16x32_bf16 v[80:83], v[162:165], v[186:189], v[80:83]
	v_mfma_f32_16x16x32_bf16 v[68:71], v[150:153], v[190:193], v[68:71]
	v_mfma_f32_16x16x32_bf16 v[68:71], v[154:157], v[200:203], v[68:71]
	v_mfma_f32_16x16x32_bf16 v[64:67], v[158:161], v[190:193], v[64:67]
	v_mfma_f32_16x16x32_bf16 v[64:67], v[162:165], v[200:203], v[64:67]
	s_setprio 0
	s_barrier
	s_add_i32 s83, s83, s97
	s_mov_b64 s[28:29], s[36:37]
	s_mov_b32 m0, s83
	ds_read_b128 v[166:169], v137 offset:16384
	ds_read_b128 v[170:173], v137 offset:17408
	ds_read_b128 v[174:177], v137 offset:18432
	ds_read_b128 v[178:181], v137 offset:19456
	ds_read_b128 v[182:185], v137 offset:20480
	ds_read_b128 v[186:189], v137 offset:21504
	ds_read_b128 v[190:193], v137 offset:22528
	ds_read_b128 v[200:203], v137 offset:23552
	s_nop 0
	global_load_lds_dwordx4 v133, s[28:29]
	s_add_i32 m0, s83, 0x2000
	s_nop 0
	global_load_lds_dwordx4 v135, s[28:29]
	s_add_u32 s28, s36, 0x20000
	s_addc_u32 s29, s37, 0
	s_add_i32 s83, s84, s97
	s_mov_b32 m0, s83
	s_nop 0
	global_load_lds_dwordx4 v133, s[28:29]
	s_add_i32 m0, s83, 0x2000
	s_nop 0
	global_load_lds_dwordx4 v135, s[28:29]
	s_mov_b64 s[28:29], s[38:39]
	s_mov_b32 m0, s27
	s_nop 0
	global_load_lds_dwordx4 v132, s[28:29]
	s_mov_b32 m0, s69
	s_nop 0
	global_load_lds_dwordx4 v134, s[28:29]
	s_waitcnt vmcnt(8)
	s_waitcnt lgkmcnt(0)
	s_barrier
	s_setprio 1
	s_waitcnt lgkmcnt(0)
	v_mfma_f32_16x16x32_bf16 v[60:63], v[128:131], v[166:169], v[60:63]
	v_mfma_f32_16x16x32_bf16 v[60:63], v[138:141], v[170:173], v[60:63]
	v_mfma_f32_16x16x32_bf16 v[56:59], v[142:145], v[166:169], v[56:59]
	v_mfma_f32_16x16x32_bf16 v[56:59], v[146:149], v[170:173], v[56:59]
	v_mfma_f32_16x16x32_bf16 v[44:47], v[128:131], v[174:177], v[44:47]
	v_mfma_f32_16x16x32_bf16 v[44:47], v[138:141], v[178:181], v[44:47]
	v_mfma_f32_16x16x32_bf16 v[40:43], v[142:145], v[174:177], v[40:43]
	v_mfma_f32_16x16x32_bf16 v[40:43], v[146:149], v[178:181], v[40:43]
	v_mfma_f32_16x16x32_bf16 v[28:31], v[128:131], v[182:185], v[28:31]
	v_mfma_f32_16x16x32_bf16 v[28:31], v[138:141], v[186:189], v[28:31]
	v_mfma_f32_16x16x32_bf16 v[24:27], v[142:145], v[182:185], v[24:27]
	v_mfma_f32_16x16x32_bf16 v[24:27], v[146:149], v[186:189], v[24:27]
	v_mfma_f32_16x16x32_bf16 v[12:15], v[128:131], v[190:193], v[12:15]
	v_mfma_f32_16x16x32_bf16 v[12:15], v[138:141], v[200:203], v[12:15]
	v_mfma_f32_16x16x32_bf16 v[8:11], v[142:145], v[190:193], v[8:11]
	v_mfma_f32_16x16x32_bf16 v[8:11], v[146:149], v[200:203], v[8:11]
	s_setprio 0
	s_setprio 1
	v_mfma_f32_16x16x32_bf16 v[52:55], v[150:153], v[166:169], v[52:55]
	v_mfma_f32_16x16x32_bf16 v[52:55], v[154:157], v[170:173], v[52:55]
	v_mfma_f32_16x16x32_bf16 v[48:51], v[158:161], v[166:169], v[48:51]
	v_mfma_f32_16x16x32_bf16 v[48:51], v[162:165], v[170:173], v[48:51]
	v_mfma_f32_16x16x32_bf16 v[36:39], v[150:153], v[174:177], v[36:39]
	v_mfma_f32_16x16x32_bf16 v[36:39], v[154:157], v[178:181], v[36:39]
	v_mfma_f32_16x16x32_bf16 v[32:35], v[158:161], v[174:177], v[32:35]
	v_mfma_f32_16x16x32_bf16 v[32:35], v[162:165], v[178:181], v[32:35]
	v_mfma_f32_16x16x32_bf16 v[20:23], v[150:153], v[182:185], v[20:23]
	v_mfma_f32_16x16x32_bf16 v[20:23], v[154:157], v[186:189], v[20:23]
	v_mfma_f32_16x16x32_bf16 v[16:19], v[158:161], v[182:185], v[16:19]
	v_mfma_f32_16x16x32_bf16 v[16:19], v[162:165], v[186:189], v[16:19]
	v_mfma_f32_16x16x32_bf16 v[4:7], v[150:153], v[190:193], v[4:7]
	v_mfma_f32_16x16x32_bf16 v[4:7], v[154:157], v[200:203], v[4:7]
	v_mfma_f32_16x16x32_bf16 v[0:3], v[158:161], v[190:193], v[0:3]
	v_mfma_f32_16x16x32_bf16 v[0:3], v[162:165], v[200:203], v[0:3]
	s_setprio 0
	s_barrier
	s_add_i32 s83, 0, 0x18000
	s_add_i32 s84, 0, 0x1c000
	v_add_u32_e32 v146, s83, v136
	v_add_u32_e32 v162, s84, v136
	ds_read_b128 v[128:131], v146
	ds_read_b128 v[138:141], v146 offset:1024
	ds_read_b128 v[142:145], v146 offset:2048
	ds_read_b128 v[146:149], v146 offset:3072
	ds_read_b128 v[150:153], v162
	ds_read_b128 v[154:157], v162 offset:1024
	ds_read_b128 v[158:161], v162 offset:2048
	ds_read_b128 v[162:165], v162 offset:3072
	s_add_u32 s28, s38, 0x20000
	s_addc_u32 s29, s39, 0
	s_mov_b32 m0, s71
	ds_read_b128 v[166:169], v137 offset:32768
	ds_read_b128 v[170:173], v137 offset:33792
	ds_read_b128 v[174:177], v137 offset:34816
	ds_read_b128 v[178:181], v137 offset:35840
	ds_read_b128 v[182:185], v137 offset:36864
	ds_read_b128 v[186:189], v137 offset:37888
	ds_read_b128 v[190:193], v137 offset:38912
	ds_read_b128 v[200:203], v137 offset:39936
	s_nop 0
	global_load_lds_dwordx4 v132, s[28:29]
	s_mov_b32 m0, s72
	s_nop 0
	global_load_lds_dwordx4 v134, s[28:29]
	s_waitcnt vmcnt(8)
	s_waitcnt lgkmcnt(0)
	s_barrier
	s_setprio 1
	s_waitcnt lgkmcnt(0)
	v_mfma_f32_16x16x32_bf16 v[124:127], v[128:131], v[166:169], v[124:127]
	v_mfma_f32_16x16x32_bf16 v[124:127], v[138:141], v[170:173], v[124:127]
	v_mfma_f32_16x16x32_bf16 v[120:123], v[142:145], v[166:169], v[120:123]
	v_mfma_f32_16x16x32_bf16 v[120:123], v[146:149], v[170:173], v[120:123]
	v_mfma_f32_16x16x32_bf16 v[108:111], v[128:131], v[174:177], v[108:111]
	v_mfma_f32_16x16x32_bf16 v[108:111], v[138:141], v[178:181], v[108:111]
	v_mfma_f32_16x16x32_bf16 v[104:107], v[142:145], v[174:177], v[104:107]
	v_mfma_f32_16x16x32_bf16 v[104:107], v[146:149], v[178:181], v[104:107]
	v_mfma_f32_16x16x32_bf16 v[92:95], v[128:131], v[182:185], v[92:95]
	v_mfma_f32_16x16x32_bf16 v[92:95], v[138:141], v[186:189], v[92:95]
	v_mfma_f32_16x16x32_bf16 v[88:91], v[142:145], v[182:185], v[88:91]
	v_mfma_f32_16x16x32_bf16 v[88:91], v[146:149], v[186:189], v[88:91]
	v_mfma_f32_16x16x32_bf16 v[76:79], v[128:131], v[190:193], v[76:79]
	v_mfma_f32_16x16x32_bf16 v[76:79], v[138:141], v[200:203], v[76:79]
	v_mfma_f32_16x16x32_bf16 v[72:75], v[142:145], v[190:193], v[72:75]
	v_mfma_f32_16x16x32_bf16 v[72:75], v[146:149], v[200:203], v[72:75]
	s_setprio 0
	s_setprio 1
	v_mfma_f32_16x16x32_bf16 v[116:119], v[150:153], v[166:169], v[116:119]
	v_mfma_f32_16x16x32_bf16 v[116:119], v[154:157], v[170:173], v[116:119]
	v_mfma_f32_16x16x32_bf16 v[112:115], v[158:161], v[166:169], v[112:115]
	v_mfma_f32_16x16x32_bf16 v[112:115], v[162:165], v[170:173], v[112:115]
	v_mfma_f32_16x16x32_bf16 v[100:103], v[150:153], v[174:177], v[100:103]
	v_mfma_f32_16x16x32_bf16 v[100:103], v[154:157], v[178:181], v[100:103]
	v_mfma_f32_16x16x32_bf16 v[96:99], v[158:161], v[174:177], v[96:99]
	v_mfma_f32_16x16x32_bf16 v[96:99], v[162:165], v[178:181], v[96:99]
	v_mfma_f32_16x16x32_bf16 v[84:87], v[150:153], v[182:185], v[84:87]
	v_mfma_f32_16x16x32_bf16 v[84:87], v[154:157], v[186:189], v[84:87]
	v_mfma_f32_16x16x32_bf16 v[80:83], v[158:161], v[182:185], v[80:83]
	v_mfma_f32_16x16x32_bf16 v[80:83], v[162:165], v[186:189], v[80:83]
	v_mfma_f32_16x16x32_bf16 v[68:71], v[150:153], v[190:193], v[68:71]
	v_mfma_f32_16x16x32_bf16 v[68:71], v[154:157], v[200:203], v[68:71]
	v_mfma_f32_16x16x32_bf16 v[64:67], v[158:161], v[190:193], v[64:67]
	v_mfma_f32_16x16x32_bf16 v[64:67], v[162:165], v[200:203], v[64:67]
	s_setprio 0
	s_barrier
	s_add_u32 s28, s36, 0x80
	s_addc_u32 s29, s37, 0
	s_add_i32 s38, s83, s97
	s_mov_b32 m0, s38
	ds_read_b128 v[166:169], v137 offset:49152
	ds_read_b128 v[170:173], v137 offset:50176
	ds_read_b128 v[174:177], v137 offset:51200
	ds_read_b128 v[178:181], v137 offset:52224
	ds_read_b128 v[182:185], v137 offset:53248
	ds_read_b128 v[186:189], v137 offset:54272
	ds_read_b128 v[190:193], v137 offset:55296
	ds_read_b128 v[200:203], v137 offset:56320
	s_nop 0
	global_load_lds_dwordx4 v133, s[28:29]
	s_add_i32 m0, s38, 0x2000
	s_nop 0
	global_load_lds_dwordx4 v135, s[28:29]
	s_add_u32 s28, s36, 0x20080
	s_addc_u32 s29, s37, 0
	s_add_i32 s36, s84, s97
	s_mov_b32 m0, s36
	s_nop 0
	global_load_lds_dwordx4 v133, s[28:29]
	s_add_i32 m0, s36, 0x2000
	s_nop 0
	global_load_lds_dwordx4 v135, s[28:29]
	s_mov_b32 m0, s80
	s_nop 0
	global_load_lds_dwordx4 v132, s[34:35]
	s_mov_b32 m0, s81
	s_nop 0
	global_load_lds_dwordx4 v134, s[34:35]
	s_waitcnt vmcnt(8)
	s_waitcnt lgkmcnt(0)
	s_barrier
	s_setprio 1
	s_waitcnt lgkmcnt(0)
	v_mfma_f32_16x16x32_bf16 v[60:63], v[128:131], v[166:169], v[60:63]
	v_mfma_f32_16x16x32_bf16 v[60:63], v[138:141], v[170:173], v[60:63]
	v_mfma_f32_16x16x32_bf16 v[56:59], v[142:145], v[166:169], v[56:59]
	v_mfma_f32_16x16x32_bf16 v[56:59], v[146:149], v[170:173], v[56:59]
	v_mfma_f32_16x16x32_bf16 v[44:47], v[128:131], v[174:177], v[44:47]
	v_mfma_f32_16x16x32_bf16 v[44:47], v[138:141], v[178:181], v[44:47]
	v_mfma_f32_16x16x32_bf16 v[40:43], v[142:145], v[174:177], v[40:43]
	v_mfma_f32_16x16x32_bf16 v[40:43], v[146:149], v[178:181], v[40:43]
	v_mfma_f32_16x16x32_bf16 v[28:31], v[128:131], v[182:185], v[28:31]
	v_mfma_f32_16x16x32_bf16 v[28:31], v[138:141], v[186:189], v[28:31]
	v_mfma_f32_16x16x32_bf16 v[24:27], v[142:145], v[182:185], v[24:27]
	v_mfma_f32_16x16x32_bf16 v[24:27], v[146:149], v[186:189], v[24:27]
	v_mfma_f32_16x16x32_bf16 v[12:15], v[128:131], v[190:193], v[12:15]
	v_mfma_f32_16x16x32_bf16 v[12:15], v[138:141], v[200:203], v[12:15]
	v_mfma_f32_16x16x32_bf16 v[8:11], v[142:145], v[190:193], v[8:11]
	v_mfma_f32_16x16x32_bf16 v[8:11], v[146:149], v[200:203], v[8:11]
	s_setprio 0
	s_setprio 1
	v_mfma_f32_16x16x32_bf16 v[52:55], v[150:153], v[166:169], v[52:55]
	v_mfma_f32_16x16x32_bf16 v[52:55], v[154:157], v[170:173], v[52:55]
	v_mfma_f32_16x16x32_bf16 v[48:51], v[158:161], v[166:169], v[48:51]
	v_mfma_f32_16x16x32_bf16 v[48:51], v[162:165], v[170:173], v[48:51]
	v_mfma_f32_16x16x32_bf16 v[36:39], v[150:153], v[174:177], v[36:39]
	v_mfma_f32_16x16x32_bf16 v[36:39], v[154:157], v[178:181], v[36:39]
	v_mfma_f32_16x16x32_bf16 v[32:35], v[158:161], v[174:177], v[32:35]
	v_mfma_f32_16x16x32_bf16 v[32:35], v[162:165], v[178:181], v[32:35]
	v_mfma_f32_16x16x32_bf16 v[20:23], v[150:153], v[182:185], v[20:23]
	v_mfma_f32_16x16x32_bf16 v[20:23], v[154:157], v[186:189], v[20:23]
	v_mfma_f32_16x16x32_bf16 v[16:19], v[158:161], v[182:185], v[16:19]
	v_mfma_f32_16x16x32_bf16 v[16:19], v[162:165], v[186:189], v[16:19]
	v_mfma_f32_16x16x32_bf16 v[4:7], v[150:153], v[190:193], v[4:7]
	v_mfma_f32_16x16x32_bf16 v[4:7], v[154:157], v[200:203], v[4:7]
	v_mfma_f32_16x16x32_bf16 v[0:3], v[158:161], v[190:193], v[0:3]
	v_mfma_f32_16x16x32_bf16 v[0:3], v[162:165], v[200:203], v[0:3]
	s_setprio 0
	s_barrier
	s_add_i32 s17, s17, 2
	s_add_u32 s5, s5, 0x100
	s_addc_u32 s15, s15, 0
	s_cmp_gt_u32 s17, 5
	s_mov_b64 s[28:29], s[30:31]
	s_cbranch_scc0 .LBB0_788
	s_and_b64 vcc, exec, s[60:61]
	s_cbranch_vccz .LBB0_791
	s_barrier

.LBB0_1050:
	s_cmp_eq_u32 s83, 28
	s_cselect_b32 s56, s5, s39
	s_cselect_b32 s57, s4, s69
	s_cselect_b32 s84, s37, s72
	s_cselect_b32 s85, s11, s74
	s_add_u32 s12, s56, 0x80
	s_addc_u32 s13, s57, 0
	s_add_i32 vcc_lo, 0, 0x10000
	s_add_i32 vcc_hi, 0, 0x14000
	v_add_u32_e32 v136, vcc_lo, v184
	v_add_u32_e32 v156, vcc_hi, v184
	ds_read_b128 v[104:107], v136
	ds_read_b128 v[108:111], v136 offset:1024
	ds_read_b128 v[132:135], v136 offset:2048
	ds_read_b128 v[136:139], v136 offset:3072
	ds_read_b128 v[144:147], v156
	ds_read_b128 v[148:151], v156 offset:1024
	ds_read_b128 v[152:155], v156 offset:2048
	ds_read_b128 v[156:159], v156 offset:3072
	s_mov_b64 s[86:87], s[8:9]
	s_add_i32 m0, s92, 0xc000
	ds_read_b128 v[160:163], v185
	ds_read_b128 v[164:167], v185 offset:1024
	ds_read_b128 v[168:171], v185 offset:2048
	ds_read_b128 v[172:175], v185 offset:3072
	ds_read_b128 v[186:189], v185 offset:4096
	ds_read_b128 v[190:193], v185 offset:5120
	ds_read_b128 v[200:203], v185 offset:6144
	ds_read_b128 v[204:207], v185 offset:7168
	s_nop 0
	global_load_lds_dwordx4 v179, s[86:87]
	s_add_i32 m0, s92, 0xe000
	s_nop 0
	global_load_lds_dwordx4 v182, s[86:87]
	s_waitcnt vmcnt(8)
	s_waitcnt lgkmcnt(0)
	s_barrier
	s_setprio 1
	s_waitcnt lgkmcnt(0)
	v_mfma_f32_16x16x32_bf16 v[140:143], v[104:107], v[160:163], v[140:143]
	v_mfma_f32_16x16x32_bf16 v[140:143], v[108:111], v[164:167], v[140:143]
	v_mfma_f32_16x16x32_bf16 v[128:131], v[132:135], v[160:163], v[128:131]
	v_mfma_f32_16x16x32_bf16 v[128:131], v[136:139], v[164:167], v[128:131]
	v_mfma_f32_16x16x32_bf16 v[124:127], v[104:107], v[168:171], v[124:127]
	v_mfma_f32_16x16x32_bf16 v[124:127], v[108:111], v[172:175], v[124:127]
	v_mfma_f32_16x16x32_bf16 v[112:115], v[132:135], v[168:171], v[112:115]
	v_mfma_f32_16x16x32_bf16 v[112:115], v[136:139], v[172:175], v[112:115]
	v_mfma_f32_16x16x32_bf16 v[96:99], v[104:107], v[186:189], v[96:99]
	v_mfma_f32_16x16x32_bf16 v[96:99], v[108:111], v[190:193], v[96:99]
	v_mfma_f32_16x16x32_bf16 v[88:91], v[132:135], v[186:189], v[88:91]
	v_mfma_f32_16x16x32_bf16 v[88:91], v[136:139], v[190:193], v[88:91]
	v_mfma_f32_16x16x32_bf16 v[84:87], v[104:107], v[200:203], v[84:87]
	v_mfma_f32_16x16x32_bf16 v[84:87], v[108:111], v[204:207], v[84:87]
	v_mfma_f32_16x16x32_bf16 v[72:75], v[132:135], v[200:203], v[72:75]
	v_mfma_f32_16x16x32_bf16 v[72:75], v[136:139], v[204:207], v[72:75]
	s_setprio 0
	s_setprio 1
	v_mfma_f32_16x16x32_bf16 v[120:123], v[144:147], v[160:163], v[120:123]
	v_mfma_f32_16x16x32_bf16 v[120:123], v[148:151], v[164:167], v[120:123]
	v_mfma_f32_16x16x32_bf16 v[116:119], v[152:155], v[160:163], v[116:119]
	v_mfma_f32_16x16x32_bf16 v[116:119], v[156:159], v[164:167], v[116:119]
	v_mfma_f32_16x16x32_bf16 v[100:103], v[144:147], v[168:171], v[100:103]
	v_mfma_f32_16x16x32_bf16 v[100:103], v[148:151], v[172:175], v[100:103]
	v_mfma_f32_16x16x32_bf16 v[92:95], v[152:155], v[168:171], v[92:95]
	v_mfma_f32_16x16x32_bf16 v[92:95], v[156:159], v[172:175], v[92:95]
	v_mfma_f32_16x16x32_bf16 v[80:83], v[144:147], v[186:189], v[80:83]
	v_mfma_f32_16x16x32_bf16 v[80:83], v[148:151], v[190:193], v[80:83]
	v_mfma_f32_16x16x32_bf16 v[76:79], v[152:155], v[186:189], v[76:79]
	v_mfma_f32_16x16x32_bf16 v[76:79], v[156:159], v[190:193], v[76:79]
	v_mfma_f32_16x16x32_bf16 v[68:71], v[144:147], v[200:203], v[68:71]
	v_mfma_f32_16x16x32_bf16 v[68:71], v[148:151], v[204:207], v[68:71]
	v_mfma_f32_16x16x32_bf16 v[64:67], v[152:155], v[200:203], v[64:67]
	v_mfma_f32_16x16x32_bf16 v[64:67], v[156:159], v[204:207], v[64:67]
	s_setprio 0
	s_barrier
	s_add_i32 vcc_lo, vcc_lo, s97
	s_mov_b64 s[86:87], s[84:85]
	s_mov_b32 m0, vcc_lo
	ds_read_b128 v[160:163], v185 offset:16384
	ds_read_b128 v[164:167], v185 offset:17408
	ds_read_b128 v[168:171], v185 offset:18432
	ds_read_b128 v[172:175], v185 offset:19456
	ds_read_b128 v[186:189], v185 offset:20480
	ds_read_b128 v[190:193], v185 offset:21504
	ds_read_b128 v[200:203], v185 offset:22528
	ds_read_b128 v[204:207], v185 offset:23552
	s_nop 0
	global_load_lds_dwordx4 v181, s[86:87]
	s_add_i32 m0, vcc_lo, 0x2000
	s_nop 0
	global_load_lds_dwordx4 v183, s[86:87]
	s_add_u32 s86, s84, 0x80000
	s_addc_u32 s87, s85, 0
	s_add_i32 vcc_lo, vcc_hi, s97
	s_mov_b32 m0, vcc_lo
	s_nop 0
	global_load_lds_dwordx4 v181, s[86:87]
	s_add_i32 m0, vcc_lo, 0x2000
	s_nop 0
	global_load_lds_dwordx4 v183, s[86:87]
	s_mov_b64 s[86:87], s[56:57]
	s_mov_b32 m0, s92
	s_nop 0
	global_load_lds_dwordx4 v179, s[86:87]
	s_mov_b32 m0, s93
	s_nop 0
	global_load_lds_dwordx4 v182, s[86:87]
	s_waitcnt vmcnt(8)
	s_waitcnt lgkmcnt(0)
	s_barrier
	s_setprio 1
	s_waitcnt lgkmcnt(0)
	v_mfma_f32_16x16x32_bf16 v[60:63], v[104:107], v[160:163], v[60:63]
	v_mfma_f32_16x16x32_bf16 v[60:63], v[108:111], v[164:167], v[60:63]
	v_mfma_f32_16x16x32_bf16 v[56:59], v[132:135], v[160:163], v[56:59]
	v_mfma_f32_16x16x32_bf16 v[56:59], v[136:139], v[164:167], v[56:59]
	v_mfma_f32_16x16x32_bf16 v[48:51], v[104:107], v[168:171], v[48:51]
	v_mfma_f32_16x16x32_bf16 v[48:51], v[108:111], v[172:175], v[48:51]
	v_mfma_f32_16x16x32_bf16 v[40:43], v[132:135], v[168:171], v[40:43]
	v_mfma_f32_16x16x32_bf16 v[40:43], v[136:139], v[172:175], v[40:43]
	v_mfma_f32_16x16x32_bf16 v[32:35], v[104:107], v[186:189], v[32:35]
	v_mfma_f32_16x16x32_bf16 v[32:35], v[108:111], v[190:193], v[32:35]
	v_mfma_f32_16x16x32_bf16 v[24:27], v[132:135], v[186:189], v[24:27]
	v_mfma_f32_16x16x32_bf16 v[24:27], v[136:139], v[190:193], v[24:27]
	v_mfma_f32_16x16x32_bf16 v[16:19], v[104:107], v[200:203], v[16:19]
	v_mfma_f32_16x16x32_bf16 v[16:19], v[108:111], v[204:207], v[16:19]
	v_mfma_f32_16x16x32_bf16 v[8:11], v[132:135], v[200:203], v[8:11]
	v_mfma_f32_16x16x32_bf16 v[8:11], v[136:139], v[204:207], v[8:11]
	s_setprio 0
	s_setprio 1
	v_mfma_f32_16x16x32_bf16 v[52:55], v[144:147], v[160:163], v[52:55]
	v_mfma_f32_16x16x32_bf16 v[52:55], v[148:151], v[164:167], v[52:55]
	v_mfma_f32_16x16x32_bf16 v[44:47], v[152:155], v[160:163], v[44:47]
	v_mfma_f32_16x16x32_bf16 v[44:47], v[156:159], v[164:167], v[44:47]
	v_mfma_f32_16x16x32_bf16 v[36:39], v[144:147], v[168:171], v[36:39]
	v_mfma_f32_16x16x32_bf16 v[36:39], v[148:151], v[172:175], v[36:39]
	v_mfma_f32_16x16x32_bf16 v[28:31], v[152:155], v[168:171], v[28:31]
	v_mfma_f32_16x16x32_bf16 v[28:31], v[156:159], v[172:175], v[28:31]
	v_mfma_f32_16x16x32_bf16 v[20:23], v[144:147], v[186:189], v[20:23]
	v_mfma_f32_16x16x32_bf16 v[20:23], v[148:151], v[190:193], v[20:23]
	v_mfma_f32_16x16x32_bf16 v[12:15], v[152:155], v[186:189], v[12:15]
	v_mfma_f32_16x16x32_bf16 v[12:15], v[156:159], v[190:193], v[12:15]
	v_mfma_f32_16x16x32_bf16 v[4:7], v[144:147], v[200:203], v[4:7]
	v_mfma_f32_16x16x32_bf16 v[4:7], v[148:151], v[204:207], v[4:7]
	v_mfma_f32_16x16x32_bf16 v[0:3], v[152:155], v[200:203], v[0:3]
	v_mfma_f32_16x16x32_bf16 v[0:3], v[156:159], v[204:207], v[0:3]
	s_setprio 0
	s_barrier
	s_add_i32 s86, 0, 0x18000
	s_add_i32 s87, 0, 0x1c000
	v_add_u32_e32 v136, s86, v184
	v_add_u32_e32 v156, s87, v184
	ds_read_b128 v[104:107], v136
	ds_read_b128 v[108:111], v136 offset:1024
	ds_read_b128 v[132:135], v136 offset:2048
	ds_read_b128 v[136:139], v136 offset:3072
	ds_read_b128 v[144:147], v156
	ds_read_b128 v[148:151], v156 offset:1024
	ds_read_b128 v[152:155], v156 offset:2048
	ds_read_b128 v[156:159], v156 offset:3072
	s_add_u32 s56, s56, 0x80000
	s_addc_u32 s57, s57, 0
	s_mov_b32 m0, s80
	ds_read_b128 v[160:163], v185 offset:32768
	ds_read_b128 v[164:167], v185 offset:33792
	ds_read_b128 v[168:171], v185 offset:34816
	ds_read_b128 v[172:175], v185 offset:35840
	ds_read_b128 v[186:189], v185 offset:36864
	ds_read_b128 v[190:193], v185 offset:37888
	ds_read_b128 v[200:203], v185 offset:38912
	ds_read_b128 v[204:207], v185 offset:39936
	s_nop 0
	global_load_lds_dwordx4 v179, s[56:57]
	s_mov_b32 m0, s48
	s_nop 0
	global_load_lds_dwordx4 v182, s[56:57]
	s_waitcnt vmcnt(8)
	s_waitcnt lgkmcnt(0)
	s_barrier
	s_setprio 1
	s_waitcnt lgkmcnt(0)
	v_mfma_f32_16x16x32_bf16 v[140:143], v[104:107], v[160:163], v[140:143]
	v_mfma_f32_16x16x32_bf16 v[140:143], v[108:111], v[164:167], v[140:143]
	v_mfma_f32_16x16x32_bf16 v[128:131], v[132:135], v[160:163], v[128:131]
	v_mfma_f32_16x16x32_bf16 v[128:131], v[136:139], v[164:167], v[128:131]
	v_mfma_f32_16x16x32_bf16 v[124:127], v[104:107], v[168:171], v[124:127]
	v_mfma_f32_16x16x32_bf16 v[124:127], v[108:111], v[172:175], v[124:127]
	v_mfma_f32_16x16x32_bf16 v[112:115], v[132:135], v[168:171], v[112:115]
	v_mfma_f32_16x16x32_bf16 v[112:115], v[136:139], v[172:175], v[112:115]
	v_mfma_f32_16x16x32_bf16 v[96:99], v[104:107], v[186:189], v[96:99]
	v_mfma_f32_16x16x32_bf16 v[96:99], v[108:111], v[190:193], v[96:99]
	v_mfma_f32_16x16x32_bf16 v[88:91], v[132:135], v[186:189], v[88:91]
	v_mfma_f32_16x16x32_bf16 v[88:91], v[136:139], v[190:193], v[88:91]
	v_mfma_f32_16x16x32_bf16 v[84:87], v[104:107], v[200:203], v[84:87]
	v_mfma_f32_16x16x32_bf16 v[84:87], v[108:111], v[204:207], v[84:87]
	v_mfma_f32_16x16x32_bf16 v[72:75], v[132:135], v[200:203], v[72:75]
	v_mfma_f32_16x16x32_bf16 v[72:75], v[136:139], v[204:207], v[72:75]
	s_setprio 0
	s_setprio 1
	v_mfma_f32_16x16x32_bf16 v[120:123], v[144:147], v[160:163], v[120:123]
	v_mfma_f32_16x16x32_bf16 v[120:123], v[148:151], v[164:167], v[120:123]
	v_mfma_f32_16x16x32_bf16 v[116:119], v[152:155], v[160:163], v[116:119]
	v_mfma_f32_16x16x32_bf16 v[116:119], v[156:159], v[164:167], v[116:119]
	v_mfma_f32_16x16x32_bf16 v[100:103], v[144:147], v[168:171], v[100:103]
	v_mfma_f32_16x16x32_bf16 v[100:103], v[148:151], v[172:175], v[100:103]
	v_mfma_f32_16x16x32_bf16 v[92:95], v[152:155], v[168:171], v[92:95]
	v_mfma_f32_16x16x32_bf16 v[92:95], v[156:159], v[172:175], v[92:95]
	v_mfma_f32_16x16x32_bf16 v[80:83], v[144:147], v[186:189], v[80:83]
	v_mfma_f32_16x16x32_bf16 v[80:83], v[148:151], v[190:193], v[80:83]
	v_mfma_f32_16x16x32_bf16 v[76:79], v[152:155], v[186:189], v[76:79]
	v_mfma_f32_16x16x32_bf16 v[76:79], v[156:159], v[190:193], v[76:79]
	v_mfma_f32_16x16x32_bf16 v[68:71], v[144:147], v[200:203], v[68:71]
	v_mfma_f32_16x16x32_bf16 v[68:71], v[148:151], v[204:207], v[68:71]
	v_mfma_f32_16x16x32_bf16 v[64:67], v[152:155], v[200:203], v[64:67]
	v_mfma_f32_16x16x32_bf16 v[64:67], v[156:159], v[204:207], v[64:67]
	s_setprio 0
	s_barrier
	s_add_u32 s56, s84, 0x80
	s_addc_u32 s57, s85, 0
	s_add_i32 s86, s86, s97
	s_mov_b32 m0, s86
	ds_read_b128 v[160:163], v185 offset:49152
	ds_read_b128 v[164:167], v185 offset:50176
	ds_read_b128 v[168:171], v185 offset:51200
	ds_read_b128 v[172:175], v185 offset:52224
	ds_read_b128 v[186:189], v185 offset:53248
	ds_read_b128 v[190:193], v185 offset:54272
	ds_read_b128 v[200:203], v185 offset:55296
	ds_read_b128 v[204:207], v185 offset:56320
	s_nop 0
	global_load_lds_dwordx4 v181, s[56:57]
	s_add_i32 m0, s86, 0x2000
	s_nop 0
	global_load_lds_dwordx4 v183, s[56:57]
	s_add_u32 s56, s84, 0x80080
	s_addc_u32 s57, s85, 0
	s_add_i32 s84, s87, s97
	s_mov_b32 m0, s84
	s_nop 0
	global_load_lds_dwordx4 v181, s[56:57]
	s_add_i32 m0, s84, 0x2000
	s_nop 0
	global_load_lds_dwordx4 v183, s[56:57]
	s_mov_b32 m0, s81
	s_nop 0
	global_load_lds_dwordx4 v179, s[12:13]
	s_mov_b32 m0, s70
	s_nop 0
	global_load_lds_dwordx4 v182, s[12:13]
	s_waitcnt vmcnt(8)
	s_waitcnt lgkmcnt(0)
	s_barrier
	s_setprio 1
	s_waitcnt lgkmcnt(0)
	v_mfma_f32_16x16x32_bf16 v[60:63], v[104:107], v[160:163], v[60:63]
	v_mfma_f32_16x16x32_bf16 v[60:63], v[108:111], v[164:167], v[60:63]
	v_mfma_f32_16x16x32_bf16 v[56:59], v[132:135], v[160:163], v[56:59]
	v_mfma_f32_16x16x32_bf16 v[56:59], v[136:139], v[164:167], v[56:59]
	v_mfma_f32_16x16x32_bf16 v[48:51], v[104:107], v[168:171], v[48:51]
	v_mfma_f32_16x16x32_bf16 v[48:51], v[108:111], v[172:175], v[48:51]
	v_mfma_f32_16x16x32_bf16 v[40:43], v[132:135], v[168:171], v[40:43]
	v_mfma_f32_16x16x32_bf16 v[40:43], v[136:139], v[172:175], v[40:43]
	v_mfma_f32_16x16x32_bf16 v[32:35], v[104:107], v[186:189], v[32:35]
	v_mfma_f32_16x16x32_bf16 v[32:35], v[108:111], v[190:193], v[32:35]
	v_mfma_f32_16x16x32_bf16 v[24:27], v[132:135], v[186:189], v[24:27]
	v_mfma_f32_16x16x32_bf16 v[24:27], v[136:139], v[190:193], v[24:27]
	v_mfma_f32_16x16x32_bf16 v[16:19], v[104:107], v[200:203], v[16:19]
	v_mfma_f32_16x16x32_bf16 v[16:19], v[108:111], v[204:207], v[16:19]
	v_mfma_f32_16x16x32_bf16 v[8:11], v[132:135], v[200:203], v[8:11]
	v_mfma_f32_16x16x32_bf16 v[8:11], v[136:139], v[204:207], v[8:11]
	s_setprio 0
	s_setprio 1
	v_mfma_f32_16x16x32_bf16 v[52:55], v[144:147], v[160:163], v[52:55]
	v_mfma_f32_16x16x32_bf16 v[52:55], v[148:151], v[164:167], v[52:55]
	v_mfma_f32_16x16x32_bf16 v[44:47], v[152:155], v[160:163], v[44:47]
	v_mfma_f32_16x16x32_bf16 v[44:47], v[156:159], v[164:167], v[44:47]
	v_mfma_f32_16x16x32_bf16 v[36:39], v[144:147], v[168:171], v[36:39]
	v_mfma_f32_16x16x32_bf16 v[36:39], v[148:151], v[172:175], v[36:39]
	v_mfma_f32_16x16x32_bf16 v[28:31], v[152:155], v[168:171], v[28:31]
	v_mfma_f32_16x16x32_bf16 v[28:31], v[156:159], v[172:175], v[28:31]
	v_mfma_f32_16x16x32_bf16 v[20:23], v[144:147], v[186:189], v[20:23]
	v_mfma_f32_16x16x32_bf16 v[20:23], v[148:151], v[190:193], v[20:23]
	v_mfma_f32_16x16x32_bf16 v[12:15], v[152:155], v[186:189], v[12:15]
	v_mfma_f32_16x16x32_bf16 v[12:15], v[156:159], v[190:193], v[12:15]
	v_mfma_f32_16x16x32_bf16 v[4:7], v[144:147], v[200:203], v[4:7]
	v_mfma_f32_16x16x32_bf16 v[4:7], v[148:151], v[204:207], v[4:7]
	v_mfma_f32_16x16x32_bf16 v[0:3], v[152:155], v[200:203], v[0:3]
	v_mfma_f32_16x16x32_bf16 v[0:3], v[156:159], v[204:207], v[0:3]
	s_setprio 0
	s_barrier
	s_add_i32 s83, s83, 2
	s_add_u32 s39, s39, 0x100
	s_addc_u32 s69, s69, 0
	s_add_u32 s72, s72, 0x100
	s_addc_u32 s74, s74, 0
	s_add_u32 s8, s8, 0x100
	s_addc_u32 s9, s9, 0
	s_cmp_gt_u32 s83, 29
	s_cbranch_scc0 .LBB0_1050
	s_and_b64 vcc, exec, s[60:61]
	s_cbranch_vccz .LBB0_1053
	s_barrier

.LBB0_1127:
	s_cmp_eq_u32 s21, 4
	s_cselect_b32 s38, s22, s4
	s_cselect_b32 s39, s23, s5
	s_cselect_b32 s36, s24, s15
	s_cselect_b32 s37, s25, s17
	s_add_u32 s34, s38, 0x80
	s_addc_u32 s35, s39, 0
	s_add_i32 s65, 0, 0x10000
	s_add_i32 s69, 0, 0x14000
	v_add_u32_e32 v132, s65, v154
	v_add_u32_e32 v148, s69, v154
	ds_read_b128 v[112:115], v132
	ds_read_b128 v[120:123], v132 offset:1024
	ds_read_b128 v[128:131], v132 offset:2048
	ds_read_b128 v[132:135], v132 offset:3072
	ds_read_b128 v[144:147], v148
	ds_read_b128 v[156:159], v148 offset:1024
	ds_read_b128 v[160:163], v148 offset:2048
	ds_read_b128 v[164:167], v148 offset:3072
	s_add_u32 s56, s4, 0x7ff80
	s_addc_u32 s57, s5, 0
	s_add_i32 m0, s27, 0xc000
	ds_read_b128 v[168:171], v155
	ds_read_b128 v[172:175], v155 offset:1024
	ds_read_b128 v[176:179], v155 offset:2048
	ds_read_b128 v[180:183], v155 offset:3072
	ds_read_b128 v[184:187], v155 offset:4096
	ds_read_b128 v[188:191], v155 offset:5120
	ds_read_b128 v[192:195], v155 offset:6144
	ds_read_b128 v[200:203], v155 offset:7168
	s_nop 0
	global_load_lds_dwordx4 v151, s[56:57]
	s_add_i32 m0, s27, 0xe000
	s_nop 0
	global_load_lds_dwordx4 v150, s[56:57]
	s_waitcnt vmcnt(8)
	s_waitcnt lgkmcnt(0)
	s_barrier
	s_setprio 1
	s_waitcnt lgkmcnt(0)
	v_mfma_f32_16x16x32_bf16 v[140:143], v[112:115], v[168:171], v[140:143]
	v_mfma_f32_16x16x32_bf16 v[140:143], v[120:123], v[172:175], v[140:143]
	v_mfma_f32_16x16x32_bf16 v[136:139], v[128:131], v[168:171], v[136:139]
	v_mfma_f32_16x16x32_bf16 v[136:139], v[132:135], v[172:175], v[136:139]
	v_mfma_f32_16x16x32_bf16 v[108:111], v[112:115], v[176:179], v[108:111]
	v_mfma_f32_16x16x32_bf16 v[108:111], v[120:123], v[180:183], v[108:111]
	v_mfma_f32_16x16x32_bf16 v[104:107], v[128:131], v[176:179], v[104:107]
	v_mfma_f32_16x16x32_bf16 v[104:107], v[132:135], v[180:183], v[104:107]
	v_mfma_f32_16x16x32_bf16 v[92:95], v[112:115], v[184:187], v[92:95]
	v_mfma_f32_16x16x32_bf16 v[92:95], v[120:123], v[188:191], v[92:95]
	v_mfma_f32_16x16x32_bf16 v[88:91], v[128:131], v[184:187], v[88:91]
	v_mfma_f32_16x16x32_bf16 v[88:91], v[132:135], v[188:191], v[88:91]
	v_mfma_f32_16x16x32_bf16 v[76:79], v[112:115], v[192:195], v[76:79]
	v_mfma_f32_16x16x32_bf16 v[76:79], v[120:123], v[200:203], v[76:79]
	v_mfma_f32_16x16x32_bf16 v[72:75], v[128:131], v[192:195], v[72:75]
	v_mfma_f32_16x16x32_bf16 v[72:75], v[132:135], v[200:203], v[72:75]
	s_setprio 0
	s_setprio 1
	v_mfma_f32_16x16x32_bf16 v[124:127], v[144:147], v[168:171], v[124:127]
	v_mfma_f32_16x16x32_bf16 v[124:127], v[156:159], v[172:175], v[124:127]
	v_mfma_f32_16x16x32_bf16 v[116:119], v[160:163], v[168:171], v[116:119]
	v_mfma_f32_16x16x32_bf16 v[116:119], v[164:167], v[172:175], v[116:119]
	v_mfma_f32_16x16x32_bf16 v[100:103], v[144:147], v[176:179], v[100:103]
	v_mfma_f32_16x16x32_bf16 v[100:103], v[156:159], v[180:183], v[100:103]
	v_mfma_f32_16x16x32_bf16 v[96:99], v[160:163], v[176:179], v[96:99]
	v_mfma_f32_16x16x32_bf16 v[96:99], v[164:167], v[180:183], v[96:99]
	v_mfma_f32_16x16x32_bf16 v[84:87], v[144:147], v[184:187], v[84:87]
	v_mfma_f32_16x16x32_bf16 v[84:87], v[156:159], v[188:191], v[84:87]
	v_mfma_f32_16x16x32_bf16 v[80:83], v[160:163], v[184:187], v[80:83]
	v_mfma_f32_16x16x32_bf16 v[80:83], v[164:167], v[188:191], v[80:83]
	v_mfma_f32_16x16x32_bf16 v[68:71], v[144:147], v[192:195], v[68:71]
	v_mfma_f32_16x16x32_bf16 v[68:71], v[156:159], v[200:203], v[68:71]
	v_mfma_f32_16x16x32_bf16 v[64:67], v[160:163], v[192:195], v[64:67]
	v_mfma_f32_16x16x32_bf16 v[64:67], v[164:167], v[200:203], v[64:67]
	s_setprio 0
	s_barrier
	s_add_i32 s65, s65, s97
	s_mov_b64 s[56:57], s[36:37]
	s_mov_b32 m0, s65
	ds_read_b128 v[168:171], v155 offset:16384
	ds_read_b128 v[172:175], v155 offset:17408
	ds_read_b128 v[176:179], v155 offset:18432
	ds_read_b128 v[180:183], v155 offset:19456
	ds_read_b128 v[184:187], v155 offset:20480
	ds_read_b128 v[188:191], v155 offset:21504
	ds_read_b128 v[192:195], v155 offset:22528
	ds_read_b128 v[200:203], v155 offset:23552
	s_nop 0
	global_load_lds_dwordx4 v152, s[56:57]
	s_add_i32 m0, s65, 0x2000
	s_nop 0
	global_load_lds_dwordx4 v153, s[56:57]
	s_add_u32 s56, s36, 0x80000
	s_addc_u32 s57, s37, 0
	s_add_i32 s65, s69, s97
	s_mov_b32 m0, s65
	s_nop 0
	global_load_lds_dwordx4 v152, s[56:57]
	s_add_i32 m0, s65, 0x2000
	s_nop 0
	global_load_lds_dwordx4 v153, s[56:57]
	s_mov_b64 s[56:57], s[38:39]
	s_mov_b32 m0, s27
	s_nop 0
	global_load_lds_dwordx4 v151, s[56:57]
	s_mov_b32 m0, s29
	s_nop 0
	global_load_lds_dwordx4 v150, s[56:57]
	s_waitcnt vmcnt(8)
	s_waitcnt lgkmcnt(0)
	s_barrier
	s_setprio 1
	s_waitcnt lgkmcnt(0)
	v_mfma_f32_16x16x32_bf16 v[60:63], v[112:115], v[168:171], v[60:63]
	v_mfma_f32_16x16x32_bf16 v[60:63], v[120:123], v[172:175], v[60:63]
	v_mfma_f32_16x16x32_bf16 v[56:59], v[128:131], v[168:171], v[56:59]
	v_mfma_f32_16x16x32_bf16 v[56:59], v[132:135], v[172:175], v[56:59]
	v_mfma_f32_16x16x32_bf16 v[52:55], v[112:115], v[176:179], v[52:55]
	v_mfma_f32_16x16x32_bf16 v[52:55], v[120:123], v[180:183], v[52:55]
	v_mfma_f32_16x16x32_bf16 v[44:47], v[128:131], v[176:179], v[44:47]
	v_mfma_f32_16x16x32_bf16 v[44:47], v[132:135], v[180:183], v[44:47]
	v_mfma_f32_16x16x32_bf16 v[36:39], v[112:115], v[184:187], v[36:39]
	v_mfma_f32_16x16x32_bf16 v[36:39], v[120:123], v[188:191], v[36:39]
	v_mfma_f32_16x16x32_bf16 v[28:31], v[128:131], v[184:187], v[28:31]
	v_mfma_f32_16x16x32_bf16 v[28:31], v[132:135], v[188:191], v[28:31]
	v_mfma_f32_16x16x32_bf16 v[20:23], v[112:115], v[192:195], v[20:23]
	v_mfma_f32_16x16x32_bf16 v[20:23], v[120:123], v[200:203], v[20:23]
	v_mfma_f32_16x16x32_bf16 v[8:11], v[128:131], v[192:195], v[8:11]
	v_mfma_f32_16x16x32_bf16 v[8:11], v[132:135], v[200:203], v[8:11]
	s_setprio 0
	s_setprio 1
	v_mfma_f32_16x16x32_bf16 v[48:51], v[144:147], v[168:171], v[48:51]
	v_mfma_f32_16x16x32_bf16 v[48:51], v[156:159], v[172:175], v[48:51]
	v_mfma_f32_16x16x32_bf16 v[40:43], v[160:163], v[168:171], v[40:43]
	v_mfma_f32_16x16x32_bf16 v[40:43], v[164:167], v[172:175], v[40:43]
	v_mfma_f32_16x16x32_bf16 v[32:35], v[144:147], v[176:179], v[32:35]
	v_mfma_f32_16x16x32_bf16 v[32:35], v[156:159], v[180:183], v[32:35]
	v_mfma_f32_16x16x32_bf16 v[24:27], v[160:163], v[176:179], v[24:27]
	v_mfma_f32_16x16x32_bf16 v[24:27], v[164:167], v[180:183], v[24:27]
	v_mfma_f32_16x16x32_bf16 v[16:19], v[144:147], v[184:187], v[16:19]
	v_mfma_f32_16x16x32_bf16 v[16:19], v[156:159], v[188:191], v[16:19]
	v_mfma_f32_16x16x32_bf16 v[12:15], v[160:163], v[184:187], v[12:15]
	v_mfma_f32_16x16x32_bf16 v[12:15], v[164:167], v[188:191], v[12:15]
	v_mfma_f32_16x16x32_bf16 v[4:7], v[144:147], v[192:195], v[4:7]
	v_mfma_f32_16x16x32_bf16 v[4:7], v[156:159], v[200:203], v[4:7]
	v_mfma_f32_16x16x32_bf16 v[0:3], v[160:163], v[192:195], v[0:3]
	v_mfma_f32_16x16x32_bf16 v[0:3], v[164:167], v[200:203], v[0:3]
	s_setprio 0
	s_barrier
	s_add_i32 s56, 0, 0x18000
	s_add_i32 s57, 0, 0x1c000
	v_add_u32_e32 v132, s56, v154
	v_add_u32_e32 v148, s57, v154
	ds_read_b128 v[112:115], v132
	ds_read_b128 v[120:123], v132 offset:1024
	ds_read_b128 v[128:131], v132 offset:2048
	ds_read_b128 v[132:135], v132 offset:3072
	ds_read_b128 v[144:147], v148
	ds_read_b128 v[156:159], v148 offset:1024
	ds_read_b128 v[160:163], v148 offset:2048
	ds_read_b128 v[164:167], v148 offset:3072
	s_add_u32 s38, s38, 0x80000
	s_addc_u32 s39, s39, 0
	s_mov_b32 m0, s31
	ds_read_b128 v[168:171], v155 offset:32768
	ds_read_b128 v[172:175], v155 offset:33792
	ds_read_b128 v[176:179], v155 offset:34816
	ds_read_b128 v[180:183], v155 offset:35840
	ds_read_b128 v[184:187], v155 offset:36864
	ds_read_b128 v[188:191], v155 offset:37888
	ds_read_b128 v[192:195], v155 offset:38912
	ds_read_b128 v[200:203], v155 offset:39936
	s_nop 0
	global_load_lds_dwordx4 v151, s[38:39]
	s_mov_b32 m0, s46
	s_nop 0
	global_load_lds_dwordx4 v150, s[38:39]
	s_waitcnt vmcnt(8)
	s_waitcnt lgkmcnt(0)
	s_barrier
	s_setprio 1
	s_waitcnt lgkmcnt(0)
	v_mfma_f32_16x16x32_bf16 v[140:143], v[112:115], v[168:171], v[140:143]
	v_mfma_f32_16x16x32_bf16 v[140:143], v[120:123], v[172:175], v[140:143]
	v_mfma_f32_16x16x32_bf16 v[136:139], v[128:131], v[168:171], v[136:139]
	v_mfma_f32_16x16x32_bf16 v[136:139], v[132:135], v[172:175], v[136:139]
	v_mfma_f32_16x16x32_bf16 v[108:111], v[112:115], v[176:179], v[108:111]
	v_mfma_f32_16x16x32_bf16 v[108:111], v[120:123], v[180:183], v[108:111]
	v_mfma_f32_16x16x32_bf16 v[104:107], v[128:131], v[176:179], v[104:107]
	v_mfma_f32_16x16x32_bf16 v[104:107], v[132:135], v[180:183], v[104:107]
	v_mfma_f32_16x16x32_bf16 v[92:95], v[112:115], v[184:187], v[92:95]
	v_mfma_f32_16x16x32_bf16 v[92:95], v[120:123], v[188:191], v[92:95]
	v_mfma_f32_16x16x32_bf16 v[88:91], v[128:131], v[184:187], v[88:91]
	v_mfma_f32_16x16x32_bf16 v[88:91], v[132:135], v[188:191], v[88:91]
	v_mfma_f32_16x16x32_bf16 v[76:79], v[112:115], v[192:195], v[76:79]
	v_mfma_f32_16x16x32_bf16 v[76:79], v[120:123], v[200:203], v[76:79]
	v_mfma_f32_16x16x32_bf16 v[72:75], v[128:131], v[192:195], v[72:75]
	v_mfma_f32_16x16x32_bf16 v[72:75], v[132:135], v[200:203], v[72:75]
	s_setprio 0
	s_setprio 1
	v_mfma_f32_16x16x32_bf16 v[124:127], v[144:147], v[168:171], v[124:127]
	v_mfma_f32_16x16x32_bf16 v[124:127], v[156:159], v[172:175], v[124:127]
	v_mfma_f32_16x16x32_bf16 v[116:119], v[160:163], v[168:171], v[116:119]
	v_mfma_f32_16x16x32_bf16 v[116:119], v[164:167], v[172:175], v[116:119]
	v_mfma_f32_16x16x32_bf16 v[100:103], v[144:147], v[176:179], v[100:103]
	v_mfma_f32_16x16x32_bf16 v[100:103], v[156:159], v[180:183], v[100:103]
	v_mfma_f32_16x16x32_bf16 v[96:99], v[160:163], v[176:179], v[96:99]
	v_mfma_f32_16x16x32_bf16 v[96:99], v[164:167], v[180:183], v[96:99]
	v_mfma_f32_16x16x32_bf16 v[84:87], v[144:147], v[184:187], v[84:87]
	v_mfma_f32_16x16x32_bf16 v[84:87], v[156:159], v[188:191], v[84:87]
	v_mfma_f32_16x16x32_bf16 v[80:83], v[160:163], v[184:187], v[80:83]
	v_mfma_f32_16x16x32_bf16 v[80:83], v[164:167], v[188:191], v[80:83]
	v_mfma_f32_16x16x32_bf16 v[68:71], v[144:147], v[192:195], v[68:71]
	v_mfma_f32_16x16x32_bf16 v[68:71], v[156:159], v[200:203], v[68:71]
	v_mfma_f32_16x16x32_bf16 v[64:67], v[160:163], v[192:195], v[64:67]
	v_mfma_f32_16x16x32_bf16 v[64:67], v[164:167], v[200:203], v[64:67]
	s_setprio 0
	s_barrier
	s_add_u32 s38, s36, 0x80
	s_addc_u32 s39, s37, 0
	s_add_i32 s56, s56, s97
	s_mov_b32 m0, s56
	ds_read_b128 v[168:171], v155 offset:49152
	ds_read_b128 v[172:175], v155 offset:50176
	ds_read_b128 v[176:179], v155 offset:51200
	ds_read_b128 v[180:183], v155 offset:52224
	ds_read_b128 v[184:187], v155 offset:53248
	ds_read_b128 v[188:191], v155 offset:54272
	ds_read_b128 v[192:195], v155 offset:55296
	ds_read_b128 v[200:203], v155 offset:56320
	s_nop 0
	global_load_lds_dwordx4 v152, s[38:39]
	s_add_i32 m0, s56, 0x2000
	s_add_u32 s36, s36, 0x80080
	s_addc_u32 s37, s37, 0
	global_load_lds_dwordx4 v153, s[38:39]
	s_add_i32 s38, s57, s97
	s_mov_b32 m0, s38
	s_nop 0
	global_load_lds_dwordx4 v152, s[36:37]
	s_add_i32 m0, s38, 0x2000
	s_nop 0
	global_load_lds_dwordx4 v153, s[36:37]
	s_mov_b32 m0, s47
	s_nop 0
	global_load_lds_dwordx4 v151, s[34:35]
	s_mov_b32 m0, s48
	s_nop 0
	global_load_lds_dwordx4 v150, s[34:35]
	s_waitcnt vmcnt(8)
	s_waitcnt lgkmcnt(0)
	s_barrier
	s_setprio 1
	s_waitcnt lgkmcnt(0)
	v_mfma_f32_16x16x32_bf16 v[60:63], v[112:115], v[168:171], v[60:63]
	v_mfma_f32_16x16x32_bf16 v[60:63], v[120:123], v[172:175], v[60:63]
	v_mfma_f32_16x16x32_bf16 v[56:59], v[128:131], v[168:171], v[56:59]
	v_mfma_f32_16x16x32_bf16 v[56:59], v[132:135], v[172:175], v[56:59]
	v_mfma_f32_16x16x32_bf16 v[52:55], v[112:115], v[176:179], v[52:55]
	v_mfma_f32_16x16x32_bf16 v[52:55], v[120:123], v[180:183], v[52:55]
	v_mfma_f32_16x16x32_bf16 v[44:47], v[128:131], v[176:179], v[44:47]
	v_mfma_f32_16x16x32_bf16 v[44:47], v[132:135], v[180:183], v[44:47]
	v_mfma_f32_16x16x32_bf16 v[36:39], v[112:115], v[184:187], v[36:39]
	v_mfma_f32_16x16x32_bf16 v[36:39], v[120:123], v[188:191], v[36:39]
	v_mfma_f32_16x16x32_bf16 v[28:31], v[128:131], v[184:187], v[28:31]
	v_mfma_f32_16x16x32_bf16 v[28:31], v[132:135], v[188:191], v[28:31]
	v_mfma_f32_16x16x32_bf16 v[20:23], v[112:115], v[192:195], v[20:23]
	v_mfma_f32_16x16x32_bf16 v[20:23], v[120:123], v[200:203], v[20:23]
	v_mfma_f32_16x16x32_bf16 v[8:11], v[128:131], v[192:195], v[8:11]
	v_mfma_f32_16x16x32_bf16 v[8:11], v[132:135], v[200:203], v[8:11]
	s_setprio 0
	s_setprio 1
	v_mfma_f32_16x16x32_bf16 v[48:51], v[144:147], v[168:171], v[48:51]
	v_mfma_f32_16x16x32_bf16 v[48:51], v[156:159], v[172:175], v[48:51]
	v_mfma_f32_16x16x32_bf16 v[40:43], v[160:163], v[168:171], v[40:43]
	v_mfma_f32_16x16x32_bf16 v[40:43], v[164:167], v[172:175], v[40:43]
	v_mfma_f32_16x16x32_bf16 v[32:35], v[144:147], v[176:179], v[32:35]
	v_mfma_f32_16x16x32_bf16 v[32:35], v[156:159], v[180:183], v[32:35]
	v_mfma_f32_16x16x32_bf16 v[24:27], v[160:163], v[176:179], v[24:27]
	v_mfma_f32_16x16x32_bf16 v[24:27], v[164:167], v[180:183], v[24:27]
	v_mfma_f32_16x16x32_bf16 v[16:19], v[144:147], v[184:187], v[16:19]
	v_mfma_f32_16x16x32_bf16 v[16:19], v[156:159], v[188:191], v[16:19]
	v_mfma_f32_16x16x32_bf16 v[12:15], v[160:163], v[184:187], v[12:15]
	v_mfma_f32_16x16x32_bf16 v[12:15], v[164:167], v[188:191], v[12:15]
	v_mfma_f32_16x16x32_bf16 v[4:7], v[144:147], v[192:195], v[4:7]
	v_mfma_f32_16x16x32_bf16 v[4:7], v[156:159], v[200:203], v[4:7]
	v_mfma_f32_16x16x32_bf16 v[0:3], v[160:163], v[192:195], v[0:3]
	v_mfma_f32_16x16x32_bf16 v[0:3], v[164:167], v[200:203], v[0:3]
	s_setprio 0
	s_barrier
	s_add_i32 s21, s21, 2
	s_add_u32 s4, s4, 0x100
	s_addc_u32 s5, s5, 0
	s_add_u32 s15, s15, 0x100
	s_addc_u32 s17, s17, 0
	s_cmp_gt_u32 s21, 5
	s_cbranch_scc0 .LBB0_1127
	s_and_b64 vcc, exec, s[60:61]
	s_cbranch_vccz .LBB0_1130
	s_barrier

.LBB0_1253:
	s_add_u32 s34, s10, 0x100
	s_addc_u32 s35, s11, 0
	s_cmp_eq_u32 vcc_hi, 28
	s_cselect_b32 s40, s5, s34
	s_cselect_b32 s41, s4, s35
	s_cselect_b32 s38, s25, s27
	s_cselect_b32 s39, s9, vcc_lo
	s_add_u32 s36, s40, 0x80
	s_addc_u32 s37, s41, 0
	s_add_i32 s75, 0, 0x10000
	s_add_i32 s46, 0, 0x14000
	v_add_u32_e32 v140, s75, v196
	v_add_u32_e32 v156, s46, v196
	ds_read_b128 v[128:131], v140
	ds_read_b128 v[132:135], v140 offset:1024
	ds_read_b128 v[136:139], v140 offset:2048
	ds_read_b128 v[140:143], v140 offset:3072
	ds_read_b128 v[144:147], v156
	ds_read_b128 v[148:151], v156 offset:1024
	ds_read_b128 v[152:155], v156 offset:2048
	ds_read_b128 v[156:159], v156 offset:3072
	s_add_u32 s10, s10, 0x80080
	s_addc_u32 s11, s11, 0
	s_add_i32 m0, s15, 0xc000
	ds_read_b128 v[160:163], v200
	ds_read_b128 v[164:167], v200 offset:1024
	ds_read_b128 v[168:171], v200 offset:2048
	ds_read_b128 v[172:175], v200 offset:3072
	ds_read_b128 v[176:179], v200 offset:4096
	ds_read_b128 v[180:183], v200 offset:5120
	ds_read_b128 v[184:187], v200 offset:6144
	ds_read_b128 v[188:191], v200 offset:7168
	s_nop 0
	global_load_lds_dwordx4 v192, s[10:11]
	s_add_i32 m0, s15, 0xe000
	s_nop 0
	global_load_lds_dwordx4 v194, s[10:11]
	s_waitcnt vmcnt(8)
	s_waitcnt lgkmcnt(0)
	s_barrier
	s_setprio 1
	s_waitcnt lgkmcnt(0)
	v_mfma_f32_16x16x32_bf16 v[124:127], v[128:131], v[160:163], v[124:127]
	v_mfma_f32_16x16x32_bf16 v[124:127], v[132:135], v[164:167], v[124:127]
	v_mfma_f32_16x16x32_bf16 v[60:63], v[136:139], v[160:163], v[60:63]
	v_mfma_f32_16x16x32_bf16 v[60:63], v[140:143], v[164:167], v[60:63]
	v_mfma_f32_16x16x32_bf16 v[120:123], v[128:131], v[168:171], v[120:123]
	v_mfma_f32_16x16x32_bf16 v[120:123], v[132:135], v[172:175], v[120:123]
	v_mfma_f32_16x16x32_bf16 v[56:59], v[136:139], v[168:171], v[56:59]
	v_mfma_f32_16x16x32_bf16 v[56:59], v[140:143], v[172:175], v[56:59]
	v_mfma_f32_16x16x32_bf16 v[116:119], v[128:131], v[176:179], v[116:119]
	v_mfma_f32_16x16x32_bf16 v[116:119], v[132:135], v[180:183], v[116:119]
	v_mfma_f32_16x16x32_bf16 v[52:55], v[136:139], v[176:179], v[52:55]
	v_mfma_f32_16x16x32_bf16 v[52:55], v[140:143], v[180:183], v[52:55]
	v_mfma_f32_16x16x32_bf16 v[112:115], v[128:131], v[184:187], v[112:115]
	v_mfma_f32_16x16x32_bf16 v[112:115], v[132:135], v[188:191], v[112:115]
	v_mfma_f32_16x16x32_bf16 v[48:51], v[136:139], v[184:187], v[48:51]
	v_mfma_f32_16x16x32_bf16 v[48:51], v[140:143], v[188:191], v[48:51]
	s_setprio 0
	s_setprio 1
	v_mfma_f32_16x16x32_bf16 v[108:111], v[144:147], v[160:163], v[108:111]
	v_mfma_f32_16x16x32_bf16 v[108:111], v[148:151], v[164:167], v[108:111]
	v_mfma_f32_16x16x32_bf16 v[44:47], v[152:155], v[160:163], v[44:47]
	v_mfma_f32_16x16x32_bf16 v[44:47], v[156:159], v[164:167], v[44:47]
	v_mfma_f32_16x16x32_bf16 v[104:107], v[144:147], v[168:171], v[104:107]
	v_mfma_f32_16x16x32_bf16 v[104:107], v[148:151], v[172:175], v[104:107]
	v_mfma_f32_16x16x32_bf16 v[40:43], v[152:155], v[168:171], v[40:43]
	v_mfma_f32_16x16x32_bf16 v[40:43], v[156:159], v[172:175], v[40:43]
	v_mfma_f32_16x16x32_bf16 v[100:103], v[144:147], v[176:179], v[100:103]
	v_mfma_f32_16x16x32_bf16 v[100:103], v[148:151], v[180:183], v[100:103]
	v_mfma_f32_16x16x32_bf16 v[36:39], v[152:155], v[176:179], v[36:39]
	v_mfma_f32_16x16x32_bf16 v[36:39], v[156:159], v[180:183], v[36:39]
	v_mfma_f32_16x16x32_bf16 v[96:99], v[144:147], v[184:187], v[96:99]
	v_mfma_f32_16x16x32_bf16 v[96:99], v[148:151], v[188:191], v[96:99]
	v_mfma_f32_16x16x32_bf16 v[32:35], v[152:155], v[184:187], v[32:35]
	v_mfma_f32_16x16x32_bf16 v[32:35], v[156:159], v[188:191], v[32:35]
	s_setprio 0
	s_barrier
	s_add_i32 s47, s75, s97
	s_mov_b64 s[10:11], s[38:39]
	s_mov_b32 m0, s47
	ds_read_b128 v[160:163], v200 offset:16384
	ds_read_b128 v[164:167], v200 offset:17408
	ds_read_b128 v[168:171], v200 offset:18432
	ds_read_b128 v[172:175], v200 offset:19456
	ds_read_b128 v[176:179], v200 offset:20480
	ds_read_b128 v[180:183], v200 offset:21504
	ds_read_b128 v[184:187], v200 offset:22528
	ds_read_b128 v[188:191], v200 offset:23552
	s_nop 0
	global_load_lds_dwordx4 v193, s[10:11]
	s_add_i32 m0, s47, 0x2000
	s_nop 0
	global_load_lds_dwordx4 v195, s[10:11]
	s_add_u32 s10, s38, 0x80000
	s_addc_u32 s11, s39, 0
	s_add_i32 s46, s46, s97
	s_mov_b32 m0, s46
	s_nop 0
	global_load_lds_dwordx4 v193, s[10:11]
	s_add_i32 m0, s46, 0x2000
	s_nop 0
	global_load_lds_dwordx4 v195, s[10:11]
	s_mov_b64 s[10:11], s[40:41]
	s_mov_b32 m0, s15
	s_nop 0
	global_load_lds_dwordx4 v192, s[10:11]
	s_mov_b32 m0, s69
	s_nop 0
	global_load_lds_dwordx4 v194, s[10:11]
	s_waitcnt vmcnt(8)
	s_waitcnt lgkmcnt(0)
	s_barrier
	s_setprio 1
	s_waitcnt lgkmcnt(0)
	v_mfma_f32_16x16x32_bf16 v[92:95], v[128:131], v[160:163], v[92:95]
	v_mfma_f32_16x16x32_bf16 v[92:95], v[132:135], v[164:167], v[92:95]
	v_mfma_f32_16x16x32_bf16 v[28:31], v[136:139], v[160:163], v[28:31]
	v_mfma_f32_16x16x32_bf16 v[28:31], v[140:143], v[164:167], v[28:31]
	v_mfma_f32_16x16x32_bf16 v[88:91], v[128:131], v[168:171], v[88:91]
	v_mfma_f32_16x16x32_bf16 v[88:91], v[132:135], v[172:175], v[88:91]
	v_mfma_f32_16x16x32_bf16 v[16:19], v[136:139], v[168:171], v[16:19]
	v_mfma_f32_16x16x32_bf16 v[16:19], v[140:143], v[172:175], v[16:19]
	v_mfma_f32_16x16x32_bf16 v[84:87], v[128:131], v[176:179], v[84:87]
	v_mfma_f32_16x16x32_bf16 v[84:87], v[132:135], v[180:183], v[84:87]
	v_mfma_f32_16x16x32_bf16 v[20:23], v[136:139], v[176:179], v[20:23]
	v_mfma_f32_16x16x32_bf16 v[20:23], v[140:143], v[180:183], v[20:23]
	v_mfma_f32_16x16x32_bf16 v[80:83], v[128:131], v[184:187], v[80:83]
	v_mfma_f32_16x16x32_bf16 v[80:83], v[132:135], v[188:191], v[80:83]
	v_mfma_f32_16x16x32_bf16 v[8:11], v[136:139], v[184:187], v[8:11]
	v_mfma_f32_16x16x32_bf16 v[8:11], v[140:143], v[188:191], v[8:11]
	s_setprio 0
	s_setprio 1
	v_mfma_f32_16x16x32_bf16 v[76:79], v[144:147], v[160:163], v[76:79]
	v_mfma_f32_16x16x32_bf16 v[76:79], v[148:151], v[164:167], v[76:79]
	v_mfma_f32_16x16x32_bf16 v[24:27], v[152:155], v[160:163], v[24:27]
	v_mfma_f32_16x16x32_bf16 v[24:27], v[156:159], v[164:167], v[24:27]
	v_mfma_f32_16x16x32_bf16 v[72:75], v[144:147], v[168:171], v[72:75]
	v_mfma_f32_16x16x32_bf16 v[72:75], v[148:151], v[172:175], v[72:75]
	v_mfma_f32_16x16x32_bf16 v[12:15], v[152:155], v[168:171], v[12:15]
	v_mfma_f32_16x16x32_bf16 v[12:15], v[156:159], v[172:175], v[12:15]
	v_mfma_f32_16x16x32_bf16 v[68:71], v[144:147], v[176:179], v[68:71]
	v_mfma_f32_16x16x32_bf16 v[68:71], v[148:151], v[180:183], v[68:71]
	v_mfma_f32_16x16x32_bf16 v[4:7], v[152:155], v[176:179], v[4:7]
	v_mfma_f32_16x16x32_bf16 v[4:7], v[156:159], v[180:183], v[4:7]
	v_mfma_f32_16x16x32_bf16 v[64:67], v[144:147], v[184:187], v[64:67]
	v_mfma_f32_16x16x32_bf16 v[64:67], v[148:151], v[188:191], v[64:67]
	v_mfma_f32_16x16x32_bf16 v[0:3], v[152:155], v[184:187], v[0:3]
	v_mfma_f32_16x16x32_bf16 v[0:3], v[156:159], v[188:191], v[0:3]
	s_setprio 0
	s_barrier
	s_add_i32 s46, 0, 0x18000
	s_add_i32 s47, 0, 0x1c000
	v_add_u32_e32 v140, s46, v196
	v_add_u32_e32 v156, s47, v196
	ds_read_b128 v[128:131], v140
	ds_read_b128 v[132:135], v140 offset:1024
	ds_read_b128 v[136:139], v140 offset:2048
	ds_read_b128 v[140:143], v140 offset:3072
	ds_read_b128 v[144:147], v156
	ds_read_b128 v[148:151], v156 offset:1024
	ds_read_b128 v[152:155], v156 offset:2048
	ds_read_b128 v[156:159], v156 offset:3072
	s_add_u32 s10, s40, 0x80000
	s_addc_u32 s11, s41, 0
	s_mov_b32 m0, s78
	ds_read_b128 v[160:163], v200 offset:32768
	ds_read_b128 v[164:167], v200 offset:33792
	ds_read_b128 v[168:171], v200 offset:34816
	ds_read_b128 v[172:175], v200 offset:35840
	ds_read_b128 v[176:179], v200 offset:36864
	ds_read_b128 v[180:183], v200 offset:37888
	ds_read_b128 v[184:187], v200 offset:38912
	ds_read_b128 v[188:191], v200 offset:39936
	s_nop 0
	global_load_lds_dwordx4 v192, s[10:11]
	s_mov_b32 m0, s80
	s_nop 0
	global_load_lds_dwordx4 v194, s[10:11]
	s_waitcnt vmcnt(8)
	s_waitcnt lgkmcnt(0)
	s_barrier
	s_setprio 1
	s_waitcnt lgkmcnt(0)
	v_mfma_f32_16x16x32_bf16 v[124:127], v[128:131], v[160:163], v[124:127]
	v_mfma_f32_16x16x32_bf16 v[124:127], v[132:135], v[164:167], v[124:127]
	v_mfma_f32_16x16x32_bf16 v[60:63], v[136:139], v[160:163], v[60:63]
	v_mfma_f32_16x16x32_bf16 v[60:63], v[140:143], v[164:167], v[60:63]
	v_mfma_f32_16x16x32_bf16 v[120:123], v[128:131], v[168:171], v[120:123]
	v_mfma_f32_16x16x32_bf16 v[120:123], v[132:135], v[172:175], v[120:123]
	v_mfma_f32_16x16x32_bf16 v[56:59], v[136:139], v[168:171], v[56:59]
	v_mfma_f32_16x16x32_bf16 v[56:59], v[140:143], v[172:175], v[56:59]
	v_mfma_f32_16x16x32_bf16 v[116:119], v[128:131], v[176:179], v[116:119]
	v_mfma_f32_16x16x32_bf16 v[116:119], v[132:135], v[180:183], v[116:119]
	v_mfma_f32_16x16x32_bf16 v[52:55], v[136:139], v[176:179], v[52:55]
	v_mfma_f32_16x16x32_bf16 v[52:55], v[140:143], v[180:183], v[52:55]
	v_mfma_f32_16x16x32_bf16 v[112:115], v[128:131], v[184:187], v[112:115]
	v_mfma_f32_16x16x32_bf16 v[112:115], v[132:135], v[188:191], v[112:115]
	v_mfma_f32_16x16x32_bf16 v[48:51], v[136:139], v[184:187], v[48:51]
	v_mfma_f32_16x16x32_bf16 v[48:51], v[140:143], v[188:191], v[48:51]
	s_setprio 0
	s_setprio 1
	v_mfma_f32_16x16x32_bf16 v[108:111], v[144:147], v[160:163], v[108:111]
	v_mfma_f32_16x16x32_bf16 v[108:111], v[148:151], v[164:167], v[108:111]
	v_mfma_f32_16x16x32_bf16 v[44:47], v[152:155], v[160:163], v[44:47]
	v_mfma_f32_16x16x32_bf16 v[44:47], v[156:159], v[164:167], v[44:47]
	v_mfma_f32_16x16x32_bf16 v[104:107], v[144:147], v[168:171], v[104:107]
	v_mfma_f32_16x16x32_bf16 v[104:107], v[148:151], v[172:175], v[104:107]
	v_mfma_f32_16x16x32_bf16 v[40:43], v[152:155], v[168:171], v[40:43]
	v_mfma_f32_16x16x32_bf16 v[40:43], v[156:159], v[172:175], v[40:43]
	v_mfma_f32_16x16x32_bf16 v[100:103], v[144:147], v[176:179], v[100:103]
	v_mfma_f32_16x16x32_bf16 v[100:103], v[148:151], v[180:183], v[100:103]
	v_mfma_f32_16x16x32_bf16 v[36:39], v[152:155], v[176:179], v[36:39]
	v_mfma_f32_16x16x32_bf16 v[36:39], v[156:159], v[180:183], v[36:39]
	v_mfma_f32_16x16x32_bf16 v[96:99], v[144:147], v[184:187], v[96:99]
	v_mfma_f32_16x16x32_bf16 v[96:99], v[148:151], v[188:191], v[96:99]
	v_mfma_f32_16x16x32_bf16 v[32:35], v[152:155], v[184:187], v[32:35]
	v_mfma_f32_16x16x32_bf16 v[32:35], v[156:159], v[188:191], v[32:35]
	s_setprio 0
	s_barrier
	s_add_u32 s10, s38, 0x80
	s_addc_u32 s11, s39, 0
	s_add_i32 s40, s46, s97
	s_mov_b32 m0, s40
	ds_read_b128 v[160:163], v200 offset:49152
	ds_read_b128 v[164:167], v200 offset:50176
	ds_read_b128 v[168:171], v200 offset:51200
	ds_read_b128 v[172:175], v200 offset:52224
	ds_read_b128 v[176:179], v200 offset:53248
	ds_read_b128 v[180:183], v200 offset:54272
	ds_read_b128 v[184:187], v200 offset:55296
	ds_read_b128 v[188:191], v200 offset:56320
	s_nop 0
	global_load_lds_dwordx4 v193, s[10:11]
	s_add_i32 m0, s40, 0x2000
	s_nop 0
	global_load_lds_dwordx4 v195, s[10:11]
	s_add_u32 s10, s38, 0x80080
	s_addc_u32 s11, s39, 0
	s_add_i32 s38, s47, s97
	s_mov_b32 m0, s38
	s_nop 0
	global_load_lds_dwordx4 v193, s[10:11]
	s_add_i32 m0, s38, 0x2000
	s_nop 0
	global_load_lds_dwordx4 v195, s[10:11]
	s_mov_b32 m0, s85
	s_nop 0
	global_load_lds_dwordx4 v192, s[36:37]
	s_mov_b32 m0, s86
	s_nop 0
	global_load_lds_dwordx4 v194, s[36:37]
	s_waitcnt vmcnt(8)
	s_waitcnt lgkmcnt(0)
	s_barrier
	s_setprio 1
	s_waitcnt lgkmcnt(0)
	v_mfma_f32_16x16x32_bf16 v[92:95], v[128:131], v[160:163], v[92:95]
	v_mfma_f32_16x16x32_bf16 v[92:95], v[132:135], v[164:167], v[92:95]
	v_mfma_f32_16x16x32_bf16 v[28:31], v[136:139], v[160:163], v[28:31]
	v_mfma_f32_16x16x32_bf16 v[28:31], v[140:143], v[164:167], v[28:31]
	v_mfma_f32_16x16x32_bf16 v[88:91], v[128:131], v[168:171], v[88:91]
	v_mfma_f32_16x16x32_bf16 v[88:91], v[132:135], v[172:175], v[88:91]
	v_mfma_f32_16x16x32_bf16 v[16:19], v[136:139], v[168:171], v[16:19]
	v_mfma_f32_16x16x32_bf16 v[16:19], v[140:143], v[172:175], v[16:19]
	v_mfma_f32_16x16x32_bf16 v[84:87], v[128:131], v[176:179], v[84:87]
	v_mfma_f32_16x16x32_bf16 v[84:87], v[132:135], v[180:183], v[84:87]
	v_mfma_f32_16x16x32_bf16 v[20:23], v[136:139], v[176:179], v[20:23]
	v_mfma_f32_16x16x32_bf16 v[20:23], v[140:143], v[180:183], v[20:23]
	v_mfma_f32_16x16x32_bf16 v[80:83], v[128:131], v[184:187], v[80:83]
	v_mfma_f32_16x16x32_bf16 v[80:83], v[132:135], v[188:191], v[80:83]
	v_mfma_f32_16x16x32_bf16 v[8:11], v[136:139], v[184:187], v[8:11]
	v_mfma_f32_16x16x32_bf16 v[8:11], v[140:143], v[188:191], v[8:11]
	s_setprio 0
	s_setprio 1
	v_mfma_f32_16x16x32_bf16 v[76:79], v[144:147], v[160:163], v[76:79]
	v_mfma_f32_16x16x32_bf16 v[76:79], v[148:151], v[164:167], v[76:79]
	v_mfma_f32_16x16x32_bf16 v[24:27], v[152:155], v[160:163], v[24:27]
	v_mfma_f32_16x16x32_bf16 v[24:27], v[156:159], v[164:167], v[24:27]
	v_mfma_f32_16x16x32_bf16 v[72:75], v[144:147], v[168:171], v[72:75]
	v_mfma_f32_16x16x32_bf16 v[72:75], v[148:151], v[172:175], v[72:75]
	v_mfma_f32_16x16x32_bf16 v[12:15], v[152:155], v[168:171], v[12:15]
	v_mfma_f32_16x16x32_bf16 v[12:15], v[156:159], v[172:175], v[12:15]
	v_mfma_f32_16x16x32_bf16 v[68:71], v[144:147], v[176:179], v[68:71]
	v_mfma_f32_16x16x32_bf16 v[68:71], v[148:151], v[180:183], v[68:71]
	v_mfma_f32_16x16x32_bf16 v[4:7], v[152:155], v[176:179], v[4:7]
	v_mfma_f32_16x16x32_bf16 v[4:7], v[156:159], v[180:183], v[4:7]
	v_mfma_f32_16x16x32_bf16 v[64:67], v[144:147], v[184:187], v[64:67]
	v_mfma_f32_16x16x32_bf16 v[64:67], v[148:151], v[188:191], v[64:67]
	v_mfma_f32_16x16x32_bf16 v[0:3], v[152:155], v[184:187], v[0:3]
	v_mfma_f32_16x16x32_bf16 v[0:3], v[156:159], v[188:191], v[0:3]
	s_setprio 0
	s_barrier
	s_add_i32 vcc_hi, vcc_hi, 2
	s_add_u32 s27, s27, 0x100
	s_addc_u32 vcc_lo, vcc_lo, 0
	s_cmp_gt_u32 vcc_hi, 29
	s_mov_b64 s[10:11], s[34:35]
	s_cbranch_scc0 .LBB0_1253
	s_and_b64 vcc, exec, s[60:61]
	s_cbranch_vccz .LBB0_1256
	s_barrier

.LBB0_1290:
	s_cmp_eq_u32 s21, 12
	s_cselect_b32 s40, s24, s4
	s_cselect_b32 s41, s25, s5
	s_cselect_b32 s38, s30, s15
	s_cselect_b32 s39, s31, s17
	s_add_u32 s36, s40, 0x80
	s_addc_u32 s37, s41, 0
	s_add_i32 s23, 0, 0x10000
	v_add_u32_e32 v128, s23, v134
	s_add_i32 s46, 0, 0x14000
	ds_read_b128 v[136:139], v128
	ds_read_b128 v[140:143], v128 offset:1024
	ds_read_b128 v[144:147], v128 offset:2048
	ds_read_b128 v[148:151], v128 offset:3072
	v_add_u32_e32 v128, s46, v134
	ds_read_b128 v[152:155], v128
	ds_read_b128 v[156:159], v128 offset:1024
	ds_read_b128 v[160:163], v128 offset:2048
	ds_read_b128 v[164:167], v128 offset:3072
	s_mov_b64 s[74:75], s[34:35]
	s_add_i32 m0, s27, 0xc000
	ds_read_b128 v[168:171], v135
	ds_read_b128 v[172:175], v135 offset:1024
	ds_read_b128 v[176:179], v135 offset:2048
	ds_read_b128 v[180:183], v135 offset:3072
	ds_read_b128 v[184:187], v135 offset:4096
	ds_read_b128 v[188:191], v135 offset:5120
	ds_read_b128 v[192:195], v135 offset:6144
	ds_read_b128 v[200:203], v135 offset:7168
	s_nop 0
	global_load_lds_dwordx4 v133, s[74:75]
	s_add_i32 m0, s27, 0xe000
	s_nop 0
	global_load_lds_dwordx4 v131, s[74:75]
	s_waitcnt vmcnt(8)
	s_waitcnt lgkmcnt(0)
	s_barrier
	s_setprio 1
	s_waitcnt lgkmcnt(0)
	v_mfma_f32_16x16x32_bf16 v[124:127], v[136:139], v[168:171], v[124:127]
	v_mfma_f32_16x16x32_bf16 v[124:127], v[140:143], v[172:175], v[124:127]
	v_mfma_f32_16x16x32_bf16 v[120:123], v[144:147], v[168:171], v[120:123]
	v_mfma_f32_16x16x32_bf16 v[120:123], v[148:151], v[172:175], v[120:123]
	v_mfma_f32_16x16x32_bf16 v[116:119], v[136:139], v[176:179], v[116:119]
	v_mfma_f32_16x16x32_bf16 v[116:119], v[140:143], v[180:183], v[116:119]
	v_mfma_f32_16x16x32_bf16 v[108:111], v[144:147], v[176:179], v[108:111]
	v_mfma_f32_16x16x32_bf16 v[108:111], v[148:151], v[180:183], v[108:111]
	v_mfma_f32_16x16x32_bf16 v[100:103], v[136:139], v[184:187], v[100:103]
	v_mfma_f32_16x16x32_bf16 v[100:103], v[140:143], v[188:191], v[100:103]
	v_mfma_f32_16x16x32_bf16 v[92:95], v[144:147], v[184:187], v[92:95]
	v_mfma_f32_16x16x32_bf16 v[92:95], v[148:151], v[188:191], v[92:95]
	v_mfma_f32_16x16x32_bf16 v[84:87], v[136:139], v[192:195], v[84:87]
	v_mfma_f32_16x16x32_bf16 v[84:87], v[140:143], v[200:203], v[84:87]
	v_mfma_f32_16x16x32_bf16 v[76:79], v[144:147], v[192:195], v[76:79]
	v_mfma_f32_16x16x32_bf16 v[76:79], v[148:151], v[200:203], v[76:79]
	s_setprio 0
	s_setprio 1
	v_mfma_f32_16x16x32_bf16 v[112:115], v[152:155], v[168:171], v[112:115]
	v_mfma_f32_16x16x32_bf16 v[112:115], v[156:159], v[172:175], v[112:115]
	v_mfma_f32_16x16x32_bf16 v[104:107], v[160:163], v[168:171], v[104:107]
	v_mfma_f32_16x16x32_bf16 v[104:107], v[164:167], v[172:175], v[104:107]
	v_mfma_f32_16x16x32_bf16 v[96:99], v[152:155], v[176:179], v[96:99]
	v_mfma_f32_16x16x32_bf16 v[96:99], v[156:159], v[180:183], v[96:99]
	v_mfma_f32_16x16x32_bf16 v[88:91], v[160:163], v[176:179], v[88:91]
	v_mfma_f32_16x16x32_bf16 v[88:91], v[164:167], v[180:183], v[88:91]
	v_mfma_f32_16x16x32_bf16 v[80:83], v[152:155], v[184:187], v[80:83]
	v_mfma_f32_16x16x32_bf16 v[80:83], v[156:159], v[188:191], v[80:83]
	v_mfma_f32_16x16x32_bf16 v[72:75], v[160:163], v[184:187], v[72:75]
	v_mfma_f32_16x16x32_bf16 v[72:75], v[164:167], v[188:191], v[72:75]
	v_mfma_f32_16x16x32_bf16 v[68:71], v[152:155], v[192:195], v[68:71]
	v_mfma_f32_16x16x32_bf16 v[68:71], v[156:159], v[200:203], v[68:71]
	v_mfma_f32_16x16x32_bf16 v[64:67], v[160:163], v[192:195], v[64:67]
	v_mfma_f32_16x16x32_bf16 v[64:67], v[164:167], v[200:203], v[64:67]
	s_setprio 0
	s_barrier
	s_add_i32 s23, s23, s97
	s_mov_b64 s[74:75], s[38:39]
	s_mov_b32 m0, s23
	ds_read_b128 v[168:171], v135 offset:16384
	ds_read_b128 v[172:175], v135 offset:17408
	ds_read_b128 v[176:179], v135 offset:18432
	ds_read_b128 v[180:183], v135 offset:19456
	ds_read_b128 v[184:187], v135 offset:20480
	ds_read_b128 v[188:191], v135 offset:21504
	ds_read_b128 v[192:195], v135 offset:22528
	ds_read_b128 v[200:203], v135 offset:23552
	s_nop 0
	global_load_lds_dwordx4 v132, s[74:75]
	s_add_i32 m0, s23, 0x2000
	s_nop 0
	global_load_lds_dwordx4 v130, s[74:75]
	s_add_u32 s74, s38, 0x80000
	s_addc_u32 s75, s39, 0
	s_add_i32 s23, s46, s97
	s_mov_b32 m0, s23
	s_nop 0
	global_load_lds_dwordx4 v132, s[74:75]
	s_add_i32 m0, s23, 0x2000
	s_nop 0
	global_load_lds_dwordx4 v130, s[74:75]
	s_mov_b64 s[74:75], s[40:41]
	s_mov_b32 m0, s27
	s_nop 0
	global_load_lds_dwordx4 v133, s[74:75]
	s_mov_b32 m0, s29
	s_nop 0
	global_load_lds_dwordx4 v131, s[74:75]
	s_waitcnt vmcnt(8)
	s_waitcnt lgkmcnt(0)
	s_barrier
	s_setprio 1
	s_waitcnt lgkmcnt(0)
	v_mfma_f32_16x16x32_bf16 v[60:63], v[136:139], v[168:171], v[60:63]
	v_mfma_f32_16x16x32_bf16 v[60:63], v[140:143], v[172:175], v[60:63]
	v_mfma_f32_16x16x32_bf16 v[56:59], v[144:147], v[168:171], v[56:59]
	v_mfma_f32_16x16x32_bf16 v[56:59], v[148:151], v[172:175], v[56:59]
	v_mfma_f32_16x16x32_bf16 v[52:55], v[136:139], v[176:179], v[52:55]
	v_mfma_f32_16x16x32_bf16 v[52:55], v[140:143], v[180:183], v[52:55]
	v_mfma_f32_16x16x32_bf16 v[44:47], v[144:147], v[176:179], v[44:47]
	v_mfma_f32_16x16x32_bf16 v[44:47], v[148:151], v[180:183], v[44:47]
	v_mfma_f32_16x16x32_bf16 v[36:39], v[136:139], v[184:187], v[36:39]
	v_mfma_f32_16x16x32_bf16 v[36:39], v[140:143], v[188:191], v[36:39]
	v_mfma_f32_16x16x32_bf16 v[28:31], v[144:147], v[184:187], v[28:31]
	v_mfma_f32_16x16x32_bf16 v[28:31], v[148:151], v[188:191], v[28:31]
	v_mfma_f32_16x16x32_bf16 v[20:23], v[136:139], v[192:195], v[20:23]
	v_mfma_f32_16x16x32_bf16 v[20:23], v[140:143], v[200:203], v[20:23]
	v_mfma_f32_16x16x32_bf16 v[12:15], v[144:147], v[192:195], v[12:15]
	v_mfma_f32_16x16x32_bf16 v[12:15], v[148:151], v[200:203], v[12:15]
	s_setprio 0
	s_setprio 1
	v_mfma_f32_16x16x32_bf16 v[48:51], v[152:155], v[168:171], v[48:51]
	v_mfma_f32_16x16x32_bf16 v[48:51], v[156:159], v[172:175], v[48:51]
	v_mfma_f32_16x16x32_bf16 v[40:43], v[160:163], v[168:171], v[40:43]
	v_mfma_f32_16x16x32_bf16 v[40:43], v[164:167], v[172:175], v[40:43]
	v_mfma_f32_16x16x32_bf16 v[32:35], v[152:155], v[176:179], v[32:35]
	v_mfma_f32_16x16x32_bf16 v[32:35], v[156:159], v[180:183], v[32:35]
	v_mfma_f32_16x16x32_bf16 v[24:27], v[160:163], v[176:179], v[24:27]
	v_mfma_f32_16x16x32_bf16 v[24:27], v[164:167], v[180:183], v[24:27]
	v_mfma_f32_16x16x32_bf16 v[16:19], v[152:155], v[184:187], v[16:19]
	v_mfma_f32_16x16x32_bf16 v[16:19], v[156:159], v[188:191], v[16:19]
	v_mfma_f32_16x16x32_bf16 v[8:11], v[160:163], v[184:187], v[8:11]
	v_mfma_f32_16x16x32_bf16 v[8:11], v[164:167], v[188:191], v[8:11]
	v_mfma_f32_16x16x32_bf16 v[4:7], v[152:155], v[192:195], v[4:7]
	v_mfma_f32_16x16x32_bf16 v[4:7], v[156:159], v[200:203], v[4:7]
	v_mfma_f32_16x16x32_bf16 v[0:3], v[160:163], v[192:195], v[0:3]
	v_mfma_f32_16x16x32_bf16 v[0:3], v[164:167], v[200:203], v[0:3]
	s_setprio 0
	s_barrier
	s_add_i32 s23, 0, 0x18000
	v_add_u32_e32 v128, s23, v134
	s_add_i32 s46, 0, 0x1c000
	ds_read_b128 v[136:139], v128
	ds_read_b128 v[140:143], v128 offset:1024
	ds_read_b128 v[144:147], v128 offset:2048
	ds_read_b128 v[148:151], v128 offset:3072
	v_add_u32_e32 v128, s46, v134
	ds_read_b128 v[152:155], v128
	ds_read_b128 v[156:159], v128 offset:1024
	ds_read_b128 v[160:163], v128 offset:2048
	ds_read_b128 v[164:167], v128 offset:3072
	s_add_u32 s40, s40, 0x80000
	s_addc_u32 s41, s41, 0
	s_mov_b32 m0, s56
	ds_read_b128 v[168:171], v135 offset:32768
	ds_read_b128 v[172:175], v135 offset:33792
	ds_read_b128 v[176:179], v135 offset:34816
	ds_read_b128 v[180:183], v135 offset:35840
	ds_read_b128 v[184:187], v135 offset:36864
	ds_read_b128 v[188:191], v135 offset:37888
	ds_read_b128 v[192:195], v135 offset:38912
	ds_read_b128 v[200:203], v135 offset:39936
	s_nop 0
	global_load_lds_dwordx4 v133, s[40:41]
	s_mov_b32 m0, s57
	s_nop 0
	global_load_lds_dwordx4 v131, s[40:41]
	s_waitcnt vmcnt(8)
	s_waitcnt lgkmcnt(0)
	s_barrier
	s_setprio 1
	s_waitcnt lgkmcnt(0)
	v_mfma_f32_16x16x32_bf16 v[124:127], v[136:139], v[168:171], v[124:127]
	v_mfma_f32_16x16x32_bf16 v[124:127], v[140:143], v[172:175], v[124:127]
	v_mfma_f32_16x16x32_bf16 v[120:123], v[144:147], v[168:171], v[120:123]
	v_mfma_f32_16x16x32_bf16 v[120:123], v[148:151], v[172:175], v[120:123]
	v_mfma_f32_16x16x32_bf16 v[116:119], v[136:139], v[176:179], v[116:119]
	v_mfma_f32_16x16x32_bf16 v[116:119], v[140:143], v[180:183], v[116:119]
	v_mfma_f32_16x16x32_bf16 v[108:111], v[144:147], v[176:179], v[108:111]
	v_mfma_f32_16x16x32_bf16 v[108:111], v[148:151], v[180:183], v[108:111]
	v_mfma_f32_16x16x32_bf16 v[100:103], v[136:139], v[184:187], v[100:103]
	v_mfma_f32_16x16x32_bf16 v[100:103], v[140:143], v[188:191], v[100:103]
	v_mfma_f32_16x16x32_bf16 v[92:95], v[144:147], v[184:187], v[92:95]
	v_mfma_f32_16x16x32_bf16 v[92:95], v[148:151], v[188:191], v[92:95]
	v_mfma_f32_16x16x32_bf16 v[84:87], v[136:139], v[192:195], v[84:87]
	v_mfma_f32_16x16x32_bf16 v[84:87], v[140:143], v[200:203], v[84:87]
	v_mfma_f32_16x16x32_bf16 v[76:79], v[144:147], v[192:195], v[76:79]
	v_mfma_f32_16x16x32_bf16 v[76:79], v[148:151], v[200:203], v[76:79]
	s_setprio 0
	s_setprio 1
	v_mfma_f32_16x16x32_bf16 v[112:115], v[152:155], v[168:171], v[112:115]
	v_mfma_f32_16x16x32_bf16 v[112:115], v[156:159], v[172:175], v[112:115]
	v_mfma_f32_16x16x32_bf16 v[104:107], v[160:163], v[168:171], v[104:107]
	v_mfma_f32_16x16x32_bf16 v[104:107], v[164:167], v[172:175], v[104:107]
	v_mfma_f32_16x16x32_bf16 v[96:99], v[152:155], v[176:179], v[96:99]
	v_mfma_f32_16x16x32_bf16 v[96:99], v[156:159], v[180:183], v[96:99]
	v_mfma_f32_16x16x32_bf16 v[88:91], v[160:163], v[176:179], v[88:91]
	v_mfma_f32_16x16x32_bf16 v[88:91], v[164:167], v[180:183], v[88:91]
	v_mfma_f32_16x16x32_bf16 v[80:83], v[152:155], v[184:187], v[80:83]
	v_mfma_f32_16x16x32_bf16 v[80:83], v[156:159], v[188:191], v[80:83]
	v_mfma_f32_16x16x32_bf16 v[72:75], v[160:163], v[184:187], v[72:75]
	v_mfma_f32_16x16x32_bf16 v[72:75], v[164:167], v[188:191], v[72:75]
	v_mfma_f32_16x16x32_bf16 v[68:71], v[152:155], v[192:195], v[68:71]
	v_mfma_f32_16x16x32_bf16 v[68:71], v[156:159], v[200:203], v[68:71]
	v_mfma_f32_16x16x32_bf16 v[64:67], v[160:163], v[192:195], v[64:67]
	v_mfma_f32_16x16x32_bf16 v[64:67], v[164:167], v[200:203], v[64:67]
	s_setprio 0
	s_barrier
	s_add_u32 s40, s38, 0x80
	s_addc_u32 s41, s39, 0
	s_add_i32 s23, s23, s97
	s_mov_b32 m0, s23
	ds_read_b128 v[168:171], v135 offset:49152
	ds_read_b128 v[172:175], v135 offset:50176
	ds_read_b128 v[176:179], v135 offset:51200
	ds_read_b128 v[180:183], v135 offset:52224
	ds_read_b128 v[184:187], v135 offset:53248
	ds_read_b128 v[188:191], v135 offset:54272
	ds_read_b128 v[192:195], v135 offset:55296
	ds_read_b128 v[200:203], v135 offset:56320
	s_nop 0
	global_load_lds_dwordx4 v132, s[40:41]
	s_add_i32 m0, s23, 0x2000
	s_add_u32 s38, s38, 0x80080
	s_addc_u32 s39, s39, 0
	s_add_i32 s23, s46, s97
	s_nop 0
	global_load_lds_dwordx4 v130, s[40:41]
	s_mov_b32 m0, s23
	s_nop 0
	global_load_lds_dwordx4 v132, s[38:39]
	s_add_i32 m0, s23, 0x2000
	s_nop 0
	global_load_lds_dwordx4 v130, s[38:39]
	s_mov_b32 m0, s70
	s_nop 0
	global_load_lds_dwordx4 v133, s[36:37]
	s_mov_b32 m0, s71
	s_nop 0
	global_load_lds_dwordx4 v131, s[36:37]
	s_waitcnt vmcnt(8)
	s_waitcnt lgkmcnt(0)
	s_barrier
	s_setprio 1
	s_waitcnt lgkmcnt(0)
	v_mfma_f32_16x16x32_bf16 v[60:63], v[136:139], v[168:171], v[60:63]
	v_mfma_f32_16x16x32_bf16 v[60:63], v[140:143], v[172:175], v[60:63]
	v_mfma_f32_16x16x32_bf16 v[56:59], v[144:147], v[168:171], v[56:59]
	v_mfma_f32_16x16x32_bf16 v[56:59], v[148:151], v[172:175], v[56:59]
	v_mfma_f32_16x16x32_bf16 v[52:55], v[136:139], v[176:179], v[52:55]
	v_mfma_f32_16x16x32_bf16 v[52:55], v[140:143], v[180:183], v[52:55]
	v_mfma_f32_16x16x32_bf16 v[44:47], v[144:147], v[176:179], v[44:47]
	v_mfma_f32_16x16x32_bf16 v[44:47], v[148:151], v[180:183], v[44:47]
	v_mfma_f32_16x16x32_bf16 v[36:39], v[136:139], v[184:187], v[36:39]
	v_mfma_f32_16x16x32_bf16 v[36:39], v[140:143], v[188:191], v[36:39]
	v_mfma_f32_16x16x32_bf16 v[28:31], v[144:147], v[184:187], v[28:31]
	v_mfma_f32_16x16x32_bf16 v[28:31], v[148:151], v[188:191], v[28:31]
	v_mfma_f32_16x16x32_bf16 v[20:23], v[136:139], v[192:195], v[20:23]
	v_mfma_f32_16x16x32_bf16 v[20:23], v[140:143], v[200:203], v[20:23]
	v_mfma_f32_16x16x32_bf16 v[12:15], v[144:147], v[192:195], v[12:15]
	v_mfma_f32_16x16x32_bf16 v[12:15], v[148:151], v[200:203], v[12:15]
	s_setprio 0
	s_setprio 1
	v_mfma_f32_16x16x32_bf16 v[48:51], v[152:155], v[168:171], v[48:51]
	v_mfma_f32_16x16x32_bf16 v[48:51], v[156:159], v[172:175], v[48:51]
	v_mfma_f32_16x16x32_bf16 v[40:43], v[160:163], v[168:171], v[40:43]
	v_mfma_f32_16x16x32_bf16 v[40:43], v[164:167], v[172:175], v[40:43]
	v_mfma_f32_16x16x32_bf16 v[32:35], v[152:155], v[176:179], v[32:35]
	v_mfma_f32_16x16x32_bf16 v[32:35], v[156:159], v[180:183], v[32:35]
	v_mfma_f32_16x16x32_bf16 v[24:27], v[160:163], v[176:179], v[24:27]
	v_mfma_f32_16x16x32_bf16 v[24:27], v[164:167], v[180:183], v[24:27]
	v_mfma_f32_16x16x32_bf16 v[16:19], v[152:155], v[184:187], v[16:19]
	v_mfma_f32_16x16x32_bf16 v[16:19], v[156:159], v[188:191], v[16:19]
	v_mfma_f32_16x16x32_bf16 v[8:11], v[160:163], v[184:187], v[8:11]
	v_mfma_f32_16x16x32_bf16 v[8:11], v[164:167], v[188:191], v[8:11]
	v_mfma_f32_16x16x32_bf16 v[4:7], v[152:155], v[192:195], v[4:7]
	v_mfma_f32_16x16x32_bf16 v[4:7], v[156:159], v[200:203], v[4:7]
	v_mfma_f32_16x16x32_bf16 v[0:3], v[160:163], v[192:195], v[0:3]
	v_mfma_f32_16x16x32_bf16 v[0:3], v[164:167], v[200:203], v[0:3]
	s_setprio 0
	s_barrier
	s_add_i32 s21, s21, 2
	s_add_u32 s4, s4, 0x100
	s_addc_u32 s5, s5, 0
	s_add_u32 s15, s15, 0x100
	s_addc_u32 s17, s17, 0
	s_add_u32 s34, s34, 0x100
	s_addc_u32 s35, s35, 0
	s_cmp_gt_u32 s21, 13
	s_cbranch_scc0 .LBB0_1290
	s_and_b64 vcc, exec, s[60:61]
	s_cbranch_vccz .LBB0_1293
	s_barrier

.LBB0_1425:
	s_cmpk_eq_i32 s80, 0x54
	s_cselect_b32 s56, s48, s4
	s_cselect_b32 s57, s49, s5
	s_cselect_b32 s74, s70, s15
	s_cselect_b32 s75, s71, s72
	s_add_u32 s16, s56, 0x80
	s_addc_u32 s17, s57, 0
	s_add_i32 s81, 0, 0x10000
	s_add_i32 vcc_lo, 0, 0x14000
	v_add_u32_e32 v136, s81, v172
	v_add_u32_e32 v156, vcc_lo, v172
	ds_read_b128 v[120:123], v136
	ds_read_b128 v[124:127], v136 offset:1024
	ds_read_b128 v[132:135], v136 offset:2048
	ds_read_b128 v[136:139], v136 offset:3072
	ds_read_b128 v[144:147], v156
	ds_read_b128 v[148:151], v156 offset:1024
	ds_read_b128 v[152:155], v156 offset:2048
	ds_read_b128 v[156:159], v156 offset:3072
	s_mov_b64 s[12:13], s[28:29]
	s_add_i32 m0, s2, 0xc000
	ds_read_b128 v[160:163], v173
	ds_read_b128 v[164:167], v173 offset:1024
	ds_read_b128 v[174:177], v173 offset:2048
	ds_read_b128 v[178:181], v173 offset:3072
	ds_read_b128 v[182:185], v173 offset:4096
	ds_read_b128 v[186:189], v173 offset:5120
	ds_read_b128 v[190:193], v173 offset:6144
	ds_read_b128 v[200:203], v173 offset:7168
	s_nop 0
	global_load_lds_dwordx4 v168, s[12:13]
	s_add_i32 m0, s2, 0xe000
	s_nop 0
	global_load_lds_dwordx4 v170, s[12:13]
	s_waitcnt vmcnt(8)
	s_waitcnt lgkmcnt(0)
	s_barrier
	s_setprio 1
	s_waitcnt lgkmcnt(0)
	v_mfma_f32_16x16x32_bf16 v[140:143], v[120:123], v[160:163], v[140:143]
	v_mfma_f32_16x16x32_bf16 v[140:143], v[124:127], v[164:167], v[140:143]
	v_mfma_f32_16x16x32_bf16 v[128:131], v[132:135], v[160:163], v[128:131]
	v_mfma_f32_16x16x32_bf16 v[128:131], v[136:139], v[164:167], v[128:131]
	v_mfma_f32_16x16x32_bf16 v[116:119], v[120:123], v[174:177], v[116:119]
	v_mfma_f32_16x16x32_bf16 v[116:119], v[124:127], v[178:181], v[116:119]
	v_mfma_f32_16x16x32_bf16 v[104:107], v[132:135], v[174:177], v[104:107]
	v_mfma_f32_16x16x32_bf16 v[104:107], v[136:139], v[178:181], v[104:107]
	v_mfma_f32_16x16x32_bf16 v[96:99], v[120:123], v[182:185], v[96:99]
	v_mfma_f32_16x16x32_bf16 v[96:99], v[124:127], v[186:189], v[96:99]
	v_mfma_f32_16x16x32_bf16 v[88:91], v[132:135], v[182:185], v[88:91]
	v_mfma_f32_16x16x32_bf16 v[88:91], v[136:139], v[186:189], v[88:91]
	v_mfma_f32_16x16x32_bf16 v[84:87], v[120:123], v[190:193], v[84:87]
	v_mfma_f32_16x16x32_bf16 v[84:87], v[124:127], v[200:203], v[84:87]
	v_mfma_f32_16x16x32_bf16 v[72:75], v[132:135], v[190:193], v[72:75]
	v_mfma_f32_16x16x32_bf16 v[72:75], v[136:139], v[200:203], v[72:75]
	s_setprio 0
	s_setprio 1
	v_mfma_f32_16x16x32_bf16 v[112:115], v[144:147], v[160:163], v[112:115]
	v_mfma_f32_16x16x32_bf16 v[112:115], v[148:151], v[164:167], v[112:115]
	v_mfma_f32_16x16x32_bf16 v[108:111], v[152:155], v[160:163], v[108:111]
	v_mfma_f32_16x16x32_bf16 v[108:111], v[156:159], v[164:167], v[108:111]
	v_mfma_f32_16x16x32_bf16 v[100:103], v[144:147], v[174:177], v[100:103]
	v_mfma_f32_16x16x32_bf16 v[100:103], v[148:151], v[178:181], v[100:103]
	v_mfma_f32_16x16x32_bf16 v[92:95], v[152:155], v[174:177], v[92:95]
	v_mfma_f32_16x16x32_bf16 v[92:95], v[156:159], v[178:181], v[92:95]
	v_mfma_f32_16x16x32_bf16 v[80:83], v[144:147], v[182:185], v[80:83]
	v_mfma_f32_16x16x32_bf16 v[80:83], v[148:151], v[186:189], v[80:83]
	v_mfma_f32_16x16x32_bf16 v[76:79], v[152:155], v[182:185], v[76:79]
	v_mfma_f32_16x16x32_bf16 v[76:79], v[156:159], v[186:189], v[76:79]
	v_mfma_f32_16x16x32_bf16 v[68:71], v[144:147], v[190:193], v[68:71]
	v_mfma_f32_16x16x32_bf16 v[68:71], v[148:151], v[200:203], v[68:71]
	v_mfma_f32_16x16x32_bf16 v[64:67], v[152:155], v[190:193], v[64:67]
	v_mfma_f32_16x16x32_bf16 v[64:67], v[156:159], v[200:203], v[64:67]
	s_setprio 0
	s_barrier
	s_add_i32 s81, s81, s97
	s_mov_b64 s[12:13], s[74:75]
	s_mov_b32 m0, s81
	ds_read_b128 v[160:163], v173 offset:16384
	ds_read_b128 v[164:167], v173 offset:17408
	ds_read_b128 v[174:177], v173 offset:18432
	ds_read_b128 v[178:181], v173 offset:19456
	ds_read_b128 v[182:185], v173 offset:20480
	ds_read_b128 v[186:189], v173 offset:21504
	ds_read_b128 v[190:193], v173 offset:22528
	ds_read_b128 v[200:203], v173 offset:23552
	s_nop 0
	global_load_lds_dwordx4 v169, s[12:13]
	s_add_i32 m0, s81, 0x2000
	s_nop 0
	global_load_lds_dwordx4 v171, s[12:13]
	s_add_u32 s12, s74, 0x160000
	s_addc_u32 s13, s75, 0
	s_add_i32 s81, vcc_lo, s97
	s_mov_b32 m0, s81
	s_nop 0
	global_load_lds_dwordx4 v169, s[12:13]
	s_add_i32 m0, s81, 0x2000
	s_nop 0
	global_load_lds_dwordx4 v171, s[12:13]
	s_mov_b64 s[12:13], s[56:57]
	s_mov_b32 m0, s2
	s_nop 0
	global_load_lds_dwordx4 v168, s[12:13]
	s_mov_b32 m0, s65
	s_nop 0
	global_load_lds_dwordx4 v170, s[12:13]
	s_waitcnt vmcnt(8)
	s_waitcnt lgkmcnt(0)
	s_barrier
	s_setprio 1
	s_waitcnt lgkmcnt(0)
	v_mfma_f32_16x16x32_bf16 v[60:63], v[120:123], v[160:163], v[60:63]
	v_mfma_f32_16x16x32_bf16 v[60:63], v[124:127], v[164:167], v[60:63]
	v_mfma_f32_16x16x32_bf16 v[56:59], v[132:135], v[160:163], v[56:59]
	v_mfma_f32_16x16x32_bf16 v[56:59], v[136:139], v[164:167], v[56:59]
	v_mfma_f32_16x16x32_bf16 v[48:51], v[120:123], v[174:177], v[48:51]
	v_mfma_f32_16x16x32_bf16 v[48:51], v[124:127], v[178:181], v[48:51]
	v_mfma_f32_16x16x32_bf16 v[40:43], v[132:135], v[174:177], v[40:43]
	v_mfma_f32_16x16x32_bf16 v[40:43], v[136:139], v[178:181], v[40:43]
	v_mfma_f32_16x16x32_bf16 v[32:35], v[120:123], v[182:185], v[32:35]
	v_mfma_f32_16x16x32_bf16 v[32:35], v[124:127], v[186:189], v[32:35]
	v_mfma_f32_16x16x32_bf16 v[24:27], v[132:135], v[182:185], v[24:27]
	v_mfma_f32_16x16x32_bf16 v[24:27], v[136:139], v[186:189], v[24:27]
	v_mfma_f32_16x16x32_bf16 v[16:19], v[120:123], v[190:193], v[16:19]
	v_mfma_f32_16x16x32_bf16 v[16:19], v[124:127], v[200:203], v[16:19]
	v_mfma_f32_16x16x32_bf16 v[8:11], v[132:135], v[190:193], v[8:11]
	v_mfma_f32_16x16x32_bf16 v[8:11], v[136:139], v[200:203], v[8:11]
	s_setprio 0
	s_setprio 1
	v_mfma_f32_16x16x32_bf16 v[52:55], v[144:147], v[160:163], v[52:55]
	v_mfma_f32_16x16x32_bf16 v[52:55], v[148:151], v[164:167], v[52:55]
	v_mfma_f32_16x16x32_bf16 v[44:47], v[152:155], v[160:163], v[44:47]
	v_mfma_f32_16x16x32_bf16 v[44:47], v[156:159], v[164:167], v[44:47]
	v_mfma_f32_16x16x32_bf16 v[36:39], v[144:147], v[174:177], v[36:39]
	v_mfma_f32_16x16x32_bf16 v[36:39], v[148:151], v[178:181], v[36:39]
	v_mfma_f32_16x16x32_bf16 v[28:31], v[152:155], v[174:177], v[28:31]
	v_mfma_f32_16x16x32_bf16 v[28:31], v[156:159], v[178:181], v[28:31]
	v_mfma_f32_16x16x32_bf16 v[20:23], v[144:147], v[182:185], v[20:23]
	v_mfma_f32_16x16x32_bf16 v[20:23], v[148:151], v[186:189], v[20:23]
	v_mfma_f32_16x16x32_bf16 v[12:15], v[152:155], v[182:185], v[12:15]
	v_mfma_f32_16x16x32_bf16 v[12:15], v[156:159], v[186:189], v[12:15]
	v_mfma_f32_16x16x32_bf16 v[4:7], v[144:147], v[190:193], v[4:7]
	v_mfma_f32_16x16x32_bf16 v[4:7], v[148:151], v[200:203], v[4:7]
	v_mfma_f32_16x16x32_bf16 v[0:3], v[152:155], v[190:193], v[0:3]
	v_mfma_f32_16x16x32_bf16 v[0:3], v[156:159], v[200:203], v[0:3]
	s_setprio 0
	s_barrier
	s_add_i32 s81, 0, 0x18000
	s_add_i32 vcc_lo, 0, 0x1c000
	v_add_u32_e32 v136, s81, v172
	v_add_u32_e32 v156, vcc_lo, v172
	ds_read_b128 v[120:123], v136
	ds_read_b128 v[124:127], v136 offset:1024
	ds_read_b128 v[132:135], v136 offset:2048
	ds_read_b128 v[136:139], v136 offset:3072
	ds_read_b128 v[144:147], v156
	ds_read_b128 v[148:151], v156 offset:1024
	ds_read_b128 v[152:155], v156 offset:2048
	ds_read_b128 v[156:159], v156 offset:3072
	s_add_u32 s12, s56, 0x160000
	s_addc_u32 s13, s57, 0
	s_mov_b32 m0, s93
	ds_read_b128 v[160:163], v173 offset:32768
	ds_read_b128 v[164:167], v173 offset:33792
	ds_read_b128 v[174:177], v173 offset:34816
	ds_read_b128 v[178:181], v173 offset:35840
	ds_read_b128 v[182:185], v173 offset:36864
	ds_read_b128 v[186:189], v173 offset:37888
	ds_read_b128 v[190:193], v173 offset:38912
	ds_read_b128 v[200:203], v173 offset:39936
	s_nop 0
	global_load_lds_dwordx4 v168, s[12:13]
	s_mov_b32 m0, s92
	s_nop 0
	global_load_lds_dwordx4 v170, s[12:13]
	s_waitcnt vmcnt(8)
	s_waitcnt lgkmcnt(0)
	s_barrier
	s_setprio 1
	s_waitcnt lgkmcnt(0)
	v_mfma_f32_16x16x32_bf16 v[140:143], v[120:123], v[160:163], v[140:143]
	v_mfma_f32_16x16x32_bf16 v[140:143], v[124:127], v[164:167], v[140:143]
	v_mfma_f32_16x16x32_bf16 v[128:131], v[132:135], v[160:163], v[128:131]
	v_mfma_f32_16x16x32_bf16 v[128:131], v[136:139], v[164:167], v[128:131]
	v_mfma_f32_16x16x32_bf16 v[116:119], v[120:123], v[174:177], v[116:119]
	v_mfma_f32_16x16x32_bf16 v[116:119], v[124:127], v[178:181], v[116:119]
	v_mfma_f32_16x16x32_bf16 v[104:107], v[132:135], v[174:177], v[104:107]
	v_mfma_f32_16x16x32_bf16 v[104:107], v[136:139], v[178:181], v[104:107]
	v_mfma_f32_16x16x32_bf16 v[96:99], v[120:123], v[182:185], v[96:99]
	v_mfma_f32_16x16x32_bf16 v[96:99], v[124:127], v[186:189], v[96:99]
	v_mfma_f32_16x16x32_bf16 v[88:91], v[132:135], v[182:185], v[88:91]
	v_mfma_f32_16x16x32_bf16 v[88:91], v[136:139], v[186:189], v[88:91]
	v_mfma_f32_16x16x32_bf16 v[84:87], v[120:123], v[190:193], v[84:87]
	v_mfma_f32_16x16x32_bf16 v[84:87], v[124:127], v[200:203], v[84:87]
	v_mfma_f32_16x16x32_bf16 v[72:75], v[132:135], v[190:193], v[72:75]
	v_mfma_f32_16x16x32_bf16 v[72:75], v[136:139], v[200:203], v[72:75]
	s_setprio 0
	s_setprio 1
	v_mfma_f32_16x16x32_bf16 v[112:115], v[144:147], v[160:163], v[112:115]
	v_mfma_f32_16x16x32_bf16 v[112:115], v[148:151], v[164:167], v[112:115]
	v_mfma_f32_16x16x32_bf16 v[108:111], v[152:155], v[160:163], v[108:111]
	v_mfma_f32_16x16x32_bf16 v[108:111], v[156:159], v[164:167], v[108:111]
	v_mfma_f32_16x16x32_bf16 v[100:103], v[144:147], v[174:177], v[100:103]
	v_mfma_f32_16x16x32_bf16 v[100:103], v[148:151], v[178:181], v[100:103]
	v_mfma_f32_16x16x32_bf16 v[92:95], v[152:155], v[174:177], v[92:95]
	v_mfma_f32_16x16x32_bf16 v[92:95], v[156:159], v[178:181], v[92:95]
	v_mfma_f32_16x16x32_bf16 v[80:83], v[144:147], v[182:185], v[80:83]
	v_mfma_f32_16x16x32_bf16 v[80:83], v[148:151], v[186:189], v[80:83]
	v_mfma_f32_16x16x32_bf16 v[76:79], v[152:155], v[182:185], v[76:79]
	v_mfma_f32_16x16x32_bf16 v[76:79], v[156:159], v[186:189], v[76:79]
	v_mfma_f32_16x16x32_bf16 v[68:71], v[144:147], v[190:193], v[68:71]
	v_mfma_f32_16x16x32_bf16 v[68:71], v[148:151], v[200:203], v[68:71]
	v_mfma_f32_16x16x32_bf16 v[64:67], v[152:155], v[190:193], v[64:67]
	v_mfma_f32_16x16x32_bf16 v[64:67], v[156:159], v[200:203], v[64:67]
	s_setprio 0
	s_barrier
	s_add_u32 s12, s74, 0x80
	s_addc_u32 s13, s75, 0
	s_add_i32 s56, s81, s97
	s_mov_b32 m0, s56
	ds_read_b128 v[160:163], v173 offset:49152
	ds_read_b128 v[164:167], v173 offset:50176
	ds_read_b128 v[174:177], v173 offset:51200
	ds_read_b128 v[178:181], v173 offset:52224
	ds_read_b128 v[182:185], v173 offset:53248
	ds_read_b128 v[186:189], v173 offset:54272
	ds_read_b128 v[190:193], v173 offset:55296
	ds_read_b128 v[200:203], v173 offset:56320
	s_nop 0
	global_load_lds_dwordx4 v169, s[12:13]
	s_add_i32 m0, s56, 0x2000
	s_nop 0
	global_load_lds_dwordx4 v171, s[12:13]
	s_add_u32 s12, s74, 0x160080
	s_addc_u32 s13, s75, 0
	s_add_i32 s56, vcc_lo, s97
	s_mov_b32 m0, s56
	s_nop 0
	global_load_lds_dwordx4 v169, s[12:13]
	s_add_i32 m0, s56, 0x2000
	s_nop 0
	global_load_lds_dwordx4 v171, s[12:13]
	s_mov_b32 m0, s19
	s_nop 0
	global_load_lds_dwordx4 v168, s[16:17]
	s_mov_b32 m0, s89
	s_nop 0
	global_load_lds_dwordx4 v170, s[16:17]
	s_waitcnt vmcnt(8)
	s_waitcnt lgkmcnt(0)
	s_barrier
	s_setprio 1
	s_waitcnt lgkmcnt(0)
	v_mfma_f32_16x16x32_bf16 v[60:63], v[120:123], v[160:163], v[60:63]
	v_mfma_f32_16x16x32_bf16 v[60:63], v[124:127], v[164:167], v[60:63]
	v_mfma_f32_16x16x32_bf16 v[56:59], v[132:135], v[160:163], v[56:59]
	v_mfma_f32_16x16x32_bf16 v[56:59], v[136:139], v[164:167], v[56:59]
	v_mfma_f32_16x16x32_bf16 v[48:51], v[120:123], v[174:177], v[48:51]
	v_mfma_f32_16x16x32_bf16 v[48:51], v[124:127], v[178:181], v[48:51]
	v_mfma_f32_16x16x32_bf16 v[40:43], v[132:135], v[174:177], v[40:43]
	v_mfma_f32_16x16x32_bf16 v[40:43], v[136:139], v[178:181], v[40:43]
	v_mfma_f32_16x16x32_bf16 v[32:35], v[120:123], v[182:185], v[32:35]
	v_mfma_f32_16x16x32_bf16 v[32:35], v[124:127], v[186:189], v[32:35]
	v_mfma_f32_16x16x32_bf16 v[24:27], v[132:135], v[182:185], v[24:27]
	v_mfma_f32_16x16x32_bf16 v[24:27], v[136:139], v[186:189], v[24:27]
	v_mfma_f32_16x16x32_bf16 v[16:19], v[120:123], v[190:193], v[16:19]
	v_mfma_f32_16x16x32_bf16 v[16:19], v[124:127], v[200:203], v[16:19]
	v_mfma_f32_16x16x32_bf16 v[8:11], v[132:135], v[190:193], v[8:11]
	v_mfma_f32_16x16x32_bf16 v[8:11], v[136:139], v[200:203], v[8:11]
	s_setprio 0
	s_setprio 1
	v_mfma_f32_16x16x32_bf16 v[52:55], v[144:147], v[160:163], v[52:55]
	v_mfma_f32_16x16x32_bf16 v[52:55], v[148:151], v[164:167], v[52:55]
	v_mfma_f32_16x16x32_bf16 v[44:47], v[152:155], v[160:163], v[44:47]
	v_mfma_f32_16x16x32_bf16 v[44:47], v[156:159], v[164:167], v[44:47]
	v_mfma_f32_16x16x32_bf16 v[36:39], v[144:147], v[174:177], v[36:39]
	v_mfma_f32_16x16x32_bf16 v[36:39], v[148:151], v[178:181], v[36:39]
	v_mfma_f32_16x16x32_bf16 v[28:31], v[152:155], v[174:177], v[28:31]
	v_mfma_f32_16x16x32_bf16 v[28:31], v[156:159], v[178:181], v[28:31]
	v_mfma_f32_16x16x32_bf16 v[20:23], v[144:147], v[182:185], v[20:23]
	v_mfma_f32_16x16x32_bf16 v[20:23], v[148:151], v[186:189], v[20:23]
	v_mfma_f32_16x16x32_bf16 v[12:15], v[152:155], v[182:185], v[12:15]
	v_mfma_f32_16x16x32_bf16 v[12:15], v[156:159], v[186:189], v[12:15]
	v_mfma_f32_16x16x32_bf16 v[4:7], v[144:147], v[190:193], v[4:7]
	v_mfma_f32_16x16x32_bf16 v[4:7], v[148:151], v[200:203], v[4:7]
	v_mfma_f32_16x16x32_bf16 v[0:3], v[152:155], v[190:193], v[0:3]
	v_mfma_f32_16x16x32_bf16 v[0:3], v[156:159], v[200:203], v[0:3]
	s_setprio 0
	s_barrier
	s_add_i32 s80, s80, 2
	s_add_u32 s4, s4, 0x100
	s_addc_u32 s5, s5, 0
	s_add_u32 s15, s15, 0x100
	s_addc_u32 s72, s72, 0
	s_add_u32 s28, s28, 0x100
	s_addc_u32 s29, s29, 0
	s_cmpk_gt_u32 s80, 0x55
	s_cbranch_scc0 .LBB0_1425
	s_and_b64 vcc, exec, s[60:61]
	s_cbranch_vccz .LBB0_1428
	s_barrier

.LBB0_1579:
	s_cmp_eq_u32 s49, 4
	s_cselect_b32 s26, s14, s13
	s_cselect_b32 s27, s15, s21
	s_cselect_b32 s24, s16, s47
	s_cselect_b32 s25, s17, s48
	s_add_u32 s22, s26, 0x80
	s_addc_u32 s23, s27, 0
	s_add_i32 s65, 0, 0x10000
	s_add_i32 s69, 0, 0x14000
	v_add_u32_e32 v132, s65, v154
	v_add_u32_e32 v148, s69, v154
	ds_read_b128 v[112:115], v132
	ds_read_b128 v[120:123], v132 offset:1024
	ds_read_b128 v[128:131], v132 offset:2048
	ds_read_b128 v[132:135], v132 offset:3072
	ds_read_b128 v[144:147], v148
	ds_read_b128 v[156:159], v148 offset:1024
	ds_read_b128 v[160:163], v148 offset:2048
	ds_read_b128 v[164:167], v148 offset:3072
	s_add_u32 s56, s13, 0x15ff80
	s_addc_u32 s57, s21, 0
	s_add_i32 m0, s31, 0xc000
	ds_read_b128 v[168:171], v155
	ds_read_b128 v[172:175], v155 offset:1024
	ds_read_b128 v[176:179], v155 offset:2048
	ds_read_b128 v[180:183], v155 offset:3072
	ds_read_b128 v[184:187], v155 offset:4096
	ds_read_b128 v[188:191], v155 offset:5120
	ds_read_b128 v[192:195], v155 offset:6144
	ds_read_b128 v[200:203], v155 offset:7168
	s_nop 0
	global_load_lds_dwordx4 v151, s[56:57]
	s_add_i32 m0, s31, 0xe000
	s_nop 0
	global_load_lds_dwordx4 v150, s[56:57]
	s_waitcnt vmcnt(8)
	s_waitcnt lgkmcnt(0)
	s_barrier
	s_setprio 1
	s_waitcnt lgkmcnt(0)
	v_mfma_f32_16x16x32_bf16 v[140:143], v[112:115], v[168:171], v[140:143]
	v_mfma_f32_16x16x32_bf16 v[140:143], v[120:123], v[172:175], v[140:143]
	v_mfma_f32_16x16x32_bf16 v[136:139], v[128:131], v[168:171], v[136:139]
	v_mfma_f32_16x16x32_bf16 v[136:139], v[132:135], v[172:175], v[136:139]
	v_mfma_f32_16x16x32_bf16 v[108:111], v[112:115], v[176:179], v[108:111]
	v_mfma_f32_16x16x32_bf16 v[108:111], v[120:123], v[180:183], v[108:111]
	v_mfma_f32_16x16x32_bf16 v[104:107], v[128:131], v[176:179], v[104:107]
	v_mfma_f32_16x16x32_bf16 v[104:107], v[132:135], v[180:183], v[104:107]
	v_mfma_f32_16x16x32_bf16 v[92:95], v[112:115], v[184:187], v[92:95]
	v_mfma_f32_16x16x32_bf16 v[92:95], v[120:123], v[188:191], v[92:95]
	v_mfma_f32_16x16x32_bf16 v[88:91], v[128:131], v[184:187], v[88:91]
	v_mfma_f32_16x16x32_bf16 v[88:91], v[132:135], v[188:191], v[88:91]
	v_mfma_f32_16x16x32_bf16 v[76:79], v[112:115], v[192:195], v[76:79]
	v_mfma_f32_16x16x32_bf16 v[76:79], v[120:123], v[200:203], v[76:79]
	v_mfma_f32_16x16x32_bf16 v[72:75], v[128:131], v[192:195], v[72:75]
	v_mfma_f32_16x16x32_bf16 v[72:75], v[132:135], v[200:203], v[72:75]
	s_setprio 0
	s_setprio 1
	v_mfma_f32_16x16x32_bf16 v[124:127], v[144:147], v[168:171], v[124:127]
	v_mfma_f32_16x16x32_bf16 v[124:127], v[156:159], v[172:175], v[124:127]
	v_mfma_f32_16x16x32_bf16 v[116:119], v[160:163], v[168:171], v[116:119]
	v_mfma_f32_16x16x32_bf16 v[116:119], v[164:167], v[172:175], v[116:119]
	v_mfma_f32_16x16x32_bf16 v[100:103], v[144:147], v[176:179], v[100:103]
	v_mfma_f32_16x16x32_bf16 v[100:103], v[156:159], v[180:183], v[100:103]
	v_mfma_f32_16x16x32_bf16 v[96:99], v[160:163], v[176:179], v[96:99]
	v_mfma_f32_16x16x32_bf16 v[96:99], v[164:167], v[180:183], v[96:99]
	v_mfma_f32_16x16x32_bf16 v[84:87], v[144:147], v[184:187], v[84:87]
	v_mfma_f32_16x16x32_bf16 v[84:87], v[156:159], v[188:191], v[84:87]
	v_mfma_f32_16x16x32_bf16 v[80:83], v[160:163], v[184:187], v[80:83]
	v_mfma_f32_16x16x32_bf16 v[80:83], v[164:167], v[188:191], v[80:83]
	v_mfma_f32_16x16x32_bf16 v[68:71], v[144:147], v[192:195], v[68:71]
	v_mfma_f32_16x16x32_bf16 v[68:71], v[156:159], v[200:203], v[68:71]
	v_mfma_f32_16x16x32_bf16 v[64:67], v[160:163], v[192:195], v[64:67]
	v_mfma_f32_16x16x32_bf16 v[64:67], v[164:167], v[200:203], v[64:67]
	s_setprio 0
	s_barrier
	s_add_i32 s65, s65, s97
	s_mov_b64 s[56:57], s[24:25]
	s_mov_b32 m0, s65
	ds_read_b128 v[168:171], v155 offset:16384
	ds_read_b128 v[172:175], v155 offset:17408
	ds_read_b128 v[176:179], v155 offset:18432
	ds_read_b128 v[180:183], v155 offset:19456
	ds_read_b128 v[184:187], v155 offset:20480
	ds_read_b128 v[188:191], v155 offset:21504
	ds_read_b128 v[192:195], v155 offset:22528
	ds_read_b128 v[200:203], v155 offset:23552
	s_nop 0
	global_load_lds_dwordx4 v152, s[56:57]
	s_add_i32 m0, s65, 0x2000
	s_nop 0
	global_load_lds_dwordx4 v153, s[56:57]
	s_add_u32 s56, s24, 0x160000
	s_addc_u32 s57, s25, 0
	s_add_i32 s65, s69, s97
	s_mov_b32 m0, s65
	s_nop 0
	global_load_lds_dwordx4 v152, s[56:57]
	s_add_i32 m0, s65, 0x2000
	s_nop 0
	global_load_lds_dwordx4 v153, s[56:57]
	s_mov_b64 s[56:57], s[26:27]
	s_mov_b32 m0, s31
	s_nop 0
	global_load_lds_dwordx4 v151, s[56:57]
	s_mov_b32 m0, s34
	s_nop 0
	global_load_lds_dwordx4 v150, s[56:57]
	s_waitcnt vmcnt(8)
	s_waitcnt lgkmcnt(0)
	s_barrier
	s_setprio 1
	s_waitcnt lgkmcnt(0)
	v_mfma_f32_16x16x32_bf16 v[60:63], v[112:115], v[168:171], v[60:63]
	v_mfma_f32_16x16x32_bf16 v[60:63], v[120:123], v[172:175], v[60:63]
	v_mfma_f32_16x16x32_bf16 v[56:59], v[128:131], v[168:171], v[56:59]
	v_mfma_f32_16x16x32_bf16 v[56:59], v[132:135], v[172:175], v[56:59]
	v_mfma_f32_16x16x32_bf16 v[52:55], v[112:115], v[176:179], v[52:55]
	v_mfma_f32_16x16x32_bf16 v[52:55], v[120:123], v[180:183], v[52:55]
	v_mfma_f32_16x16x32_bf16 v[44:47], v[128:131], v[176:179], v[44:47]
	v_mfma_f32_16x16x32_bf16 v[44:47], v[132:135], v[180:183], v[44:47]
	v_mfma_f32_16x16x32_bf16 v[36:39], v[112:115], v[184:187], v[36:39]
	v_mfma_f32_16x16x32_bf16 v[36:39], v[120:123], v[188:191], v[36:39]
	v_mfma_f32_16x16x32_bf16 v[28:31], v[128:131], v[184:187], v[28:31]
	v_mfma_f32_16x16x32_bf16 v[28:31], v[132:135], v[188:191], v[28:31]
	v_mfma_f32_16x16x32_bf16 v[20:23], v[112:115], v[192:195], v[20:23]
	v_mfma_f32_16x16x32_bf16 v[20:23], v[120:123], v[200:203], v[20:23]
	v_mfma_f32_16x16x32_bf16 v[8:11], v[128:131], v[192:195], v[8:11]
	v_mfma_f32_16x16x32_bf16 v[8:11], v[132:135], v[200:203], v[8:11]
	s_setprio 0
	s_setprio 1
	v_mfma_f32_16x16x32_bf16 v[48:51], v[144:147], v[168:171], v[48:51]
	v_mfma_f32_16x16x32_bf16 v[48:51], v[156:159], v[172:175], v[48:51]
	v_mfma_f32_16x16x32_bf16 v[40:43], v[160:163], v[168:171], v[40:43]
	v_mfma_f32_16x16x32_bf16 v[40:43], v[164:167], v[172:175], v[40:43]
	v_mfma_f32_16x16x32_bf16 v[32:35], v[144:147], v[176:179], v[32:35]
	v_mfma_f32_16x16x32_bf16 v[32:35], v[156:159], v[180:183], v[32:35]
	v_mfma_f32_16x16x32_bf16 v[24:27], v[160:163], v[176:179], v[24:27]
	v_mfma_f32_16x16x32_bf16 v[24:27], v[164:167], v[180:183], v[24:27]
	v_mfma_f32_16x16x32_bf16 v[16:19], v[144:147], v[184:187], v[16:19]
	v_mfma_f32_16x16x32_bf16 v[16:19], v[156:159], v[188:191], v[16:19]
	v_mfma_f32_16x16x32_bf16 v[12:15], v[160:163], v[184:187], v[12:15]
	v_mfma_f32_16x16x32_bf16 v[12:15], v[164:167], v[188:191], v[12:15]
	v_mfma_f32_16x16x32_bf16 v[4:7], v[144:147], v[192:195], v[4:7]
	v_mfma_f32_16x16x32_bf16 v[4:7], v[156:159], v[200:203], v[4:7]
	v_mfma_f32_16x16x32_bf16 v[0:3], v[160:163], v[192:195], v[0:3]
	v_mfma_f32_16x16x32_bf16 v[0:3], v[164:167], v[200:203], v[0:3]
	s_setprio 0
	s_barrier
	s_add_i32 s56, 0, 0x18000
	s_add_i32 s57, 0, 0x1c000
	v_add_u32_e32 v132, s56, v154
	v_add_u32_e32 v148, s57, v154
	ds_read_b128 v[112:115], v132
	ds_read_b128 v[120:123], v132 offset:1024
	ds_read_b128 v[128:131], v132 offset:2048
	ds_read_b128 v[132:135], v132 offset:3072
	ds_read_b128 v[144:147], v148
	ds_read_b128 v[156:159], v148 offset:1024
	ds_read_b128 v[160:163], v148 offset:2048
	ds_read_b128 v[164:167], v148 offset:3072
	s_add_u32 s26, s26, 0x160000
	s_addc_u32 s27, s27, 0
	s_mov_b32 m0, s35
	ds_read_b128 v[168:171], v155 offset:32768
	ds_read_b128 v[172:175], v155 offset:33792
	ds_read_b128 v[176:179], v155 offset:34816
	ds_read_b128 v[180:183], v155 offset:35840
	ds_read_b128 v[184:187], v155 offset:36864
	ds_read_b128 v[188:191], v155 offset:37888
	ds_read_b128 v[192:195], v155 offset:38912
	ds_read_b128 v[200:203], v155 offset:39936
	s_nop 0
	global_load_lds_dwordx4 v151, s[26:27]
	s_mov_b32 m0, s36
	s_nop 0
	global_load_lds_dwordx4 v150, s[26:27]
	s_waitcnt vmcnt(8)
	s_waitcnt lgkmcnt(0)
	s_barrier
	s_setprio 1
	s_waitcnt lgkmcnt(0)
	v_mfma_f32_16x16x32_bf16 v[140:143], v[112:115], v[168:171], v[140:143]
	v_mfma_f32_16x16x32_bf16 v[140:143], v[120:123], v[172:175], v[140:143]
	v_mfma_f32_16x16x32_bf16 v[136:139], v[128:131], v[168:171], v[136:139]
	v_mfma_f32_16x16x32_bf16 v[136:139], v[132:135], v[172:175], v[136:139]
	v_mfma_f32_16x16x32_bf16 v[108:111], v[112:115], v[176:179], v[108:111]
	v_mfma_f32_16x16x32_bf16 v[108:111], v[120:123], v[180:183], v[108:111]
	v_mfma_f32_16x16x32_bf16 v[104:107], v[128:131], v[176:179], v[104:107]
	v_mfma_f32_16x16x32_bf16 v[104:107], v[132:135], v[180:183], v[104:107]
	v_mfma_f32_16x16x32_bf16 v[92:95], v[112:115], v[184:187], v[92:95]
	v_mfma_f32_16x16x32_bf16 v[92:95], v[120:123], v[188:191], v[92:95]
	v_mfma_f32_16x16x32_bf16 v[88:91], v[128:131], v[184:187], v[88:91]
	v_mfma_f32_16x16x32_bf16 v[88:91], v[132:135], v[188:191], v[88:91]
	v_mfma_f32_16x16x32_bf16 v[76:79], v[112:115], v[192:195], v[76:79]
	v_mfma_f32_16x16x32_bf16 v[76:79], v[120:123], v[200:203], v[76:79]
	v_mfma_f32_16x16x32_bf16 v[72:75], v[128:131], v[192:195], v[72:75]
	v_mfma_f32_16x16x32_bf16 v[72:75], v[132:135], v[200:203], v[72:75]
	s_setprio 0
	s_setprio 1
	v_mfma_f32_16x16x32_bf16 v[124:127], v[144:147], v[168:171], v[124:127]
	v_mfma_f32_16x16x32_bf16 v[124:127], v[156:159], v[172:175], v[124:127]
	v_mfma_f32_16x16x32_bf16 v[116:119], v[160:163], v[168:171], v[116:119]
	v_mfma_f32_16x16x32_bf16 v[116:119], v[164:167], v[172:175], v[116:119]
	v_mfma_f32_16x16x32_bf16 v[100:103], v[144:147], v[176:179], v[100:103]
	v_mfma_f32_16x16x32_bf16 v[100:103], v[156:159], v[180:183], v[100:103]
	v_mfma_f32_16x16x32_bf16 v[96:99], v[160:163], v[176:179], v[96:99]
	v_mfma_f32_16x16x32_bf16 v[96:99], v[164:167], v[180:183], v[96:99]
	v_mfma_f32_16x16x32_bf16 v[84:87], v[144:147], v[184:187], v[84:87]
	v_mfma_f32_16x16x32_bf16 v[84:87], v[156:159], v[188:191], v[84:87]
	v_mfma_f32_16x16x32_bf16 v[80:83], v[160:163], v[184:187], v[80:83]
	v_mfma_f32_16x16x32_bf16 v[80:83], v[164:167], v[188:191], v[80:83]
	v_mfma_f32_16x16x32_bf16 v[68:71], v[144:147], v[192:195], v[68:71]
	v_mfma_f32_16x16x32_bf16 v[68:71], v[156:159], v[200:203], v[68:71]
	v_mfma_f32_16x16x32_bf16 v[64:67], v[160:163], v[192:195], v[64:67]
	v_mfma_f32_16x16x32_bf16 v[64:67], v[164:167], v[200:203], v[64:67]
	s_setprio 0
	s_barrier
	s_add_u32 s26, s24, 0x80
	s_addc_u32 s27, s25, 0
	s_add_i32 s56, s56, s97
	s_mov_b32 m0, s56
	ds_read_b128 v[168:171], v155 offset:49152
	ds_read_b128 v[172:175], v155 offset:50176
	ds_read_b128 v[176:179], v155 offset:51200
	ds_read_b128 v[180:183], v155 offset:52224
	ds_read_b128 v[184:187], v155 offset:53248
	ds_read_b128 v[188:191], v155 offset:54272
	ds_read_b128 v[192:195], v155 offset:55296
	ds_read_b128 v[200:203], v155 offset:56320
	s_nop 0
	global_load_lds_dwordx4 v152, s[26:27]
	s_add_i32 m0, s56, 0x2000
	s_add_u32 s24, s24, 0x160080
	s_addc_u32 s25, s25, 0
	global_load_lds_dwordx4 v153, s[26:27]
	s_add_i32 s26, s57, s97
	s_mov_b32 m0, s26
	s_nop 0
	global_load_lds_dwordx4 v152, s[24:25]
	s_add_i32 m0, s26, 0x2000
	s_nop 0
	global_load_lds_dwordx4 v153, s[24:25]
	s_mov_b32 m0, s37
	s_nop 0
	global_load_lds_dwordx4 v151, s[22:23]
	s_mov_b32 m0, s38
	s_nop 0
	global_load_lds_dwordx4 v150, s[22:23]
	s_waitcnt vmcnt(8)
	s_waitcnt lgkmcnt(0)
	s_barrier
	s_setprio 1
	s_waitcnt lgkmcnt(0)
	v_mfma_f32_16x16x32_bf16 v[60:63], v[112:115], v[168:171], v[60:63]
	v_mfma_f32_16x16x32_bf16 v[60:63], v[120:123], v[172:175], v[60:63]
	v_mfma_f32_16x16x32_bf16 v[56:59], v[128:131], v[168:171], v[56:59]
	v_mfma_f32_16x16x32_bf16 v[56:59], v[132:135], v[172:175], v[56:59]
	v_mfma_f32_16x16x32_bf16 v[52:55], v[112:115], v[176:179], v[52:55]
	v_mfma_f32_16x16x32_bf16 v[52:55], v[120:123], v[180:183], v[52:55]
	v_mfma_f32_16x16x32_bf16 v[44:47], v[128:131], v[176:179], v[44:47]
	v_mfma_f32_16x16x32_bf16 v[44:47], v[132:135], v[180:183], v[44:47]
	v_mfma_f32_16x16x32_bf16 v[36:39], v[112:115], v[184:187], v[36:39]
	v_mfma_f32_16x16x32_bf16 v[36:39], v[120:123], v[188:191], v[36:39]
	v_mfma_f32_16x16x32_bf16 v[28:31], v[128:131], v[184:187], v[28:31]
	v_mfma_f32_16x16x32_bf16 v[28:31], v[132:135], v[188:191], v[28:31]
	v_mfma_f32_16x16x32_bf16 v[20:23], v[112:115], v[192:195], v[20:23]
	v_mfma_f32_16x16x32_bf16 v[20:23], v[120:123], v[200:203], v[20:23]
	v_mfma_f32_16x16x32_bf16 v[8:11], v[128:131], v[192:195], v[8:11]
	v_mfma_f32_16x16x32_bf16 v[8:11], v[132:135], v[200:203], v[8:11]
	s_setprio 0
	s_setprio 1
	v_mfma_f32_16x16x32_bf16 v[48:51], v[144:147], v[168:171], v[48:51]
	v_mfma_f32_16x16x32_bf16 v[48:51], v[156:159], v[172:175], v[48:51]
	v_mfma_f32_16x16x32_bf16 v[40:43], v[160:163], v[168:171], v[40:43]
	v_mfma_f32_16x16x32_bf16 v[40:43], v[164:167], v[172:175], v[40:43]
	v_mfma_f32_16x16x32_bf16 v[32:35], v[144:147], v[176:179], v[32:35]
	v_mfma_f32_16x16x32_bf16 v[32:35], v[156:159], v[180:183], v[32:35]
	v_mfma_f32_16x16x32_bf16 v[24:27], v[160:163], v[176:179], v[24:27]
	v_mfma_f32_16x16x32_bf16 v[24:27], v[164:167], v[180:183], v[24:27]
	v_mfma_f32_16x16x32_bf16 v[16:19], v[144:147], v[184:187], v[16:19]
	v_mfma_f32_16x16x32_bf16 v[16:19], v[156:159], v[188:191], v[16:19]
	v_mfma_f32_16x16x32_bf16 v[12:15], v[160:163], v[184:187], v[12:15]
	v_mfma_f32_16x16x32_bf16 v[12:15], v[164:167], v[188:191], v[12:15]
	v_mfma_f32_16x16x32_bf16 v[4:7], v[144:147], v[192:195], v[4:7]
	v_mfma_f32_16x16x32_bf16 v[4:7], v[156:159], v[200:203], v[4:7]
	v_mfma_f32_16x16x32_bf16 v[0:3], v[160:163], v[192:195], v[0:3]
	v_mfma_f32_16x16x32_bf16 v[0:3], v[164:167], v[200:203], v[0:3]
	s_setprio 0
	s_barrier
	s_add_i32 s49, s49, 2
	s_add_u32 s13, s13, 0x100
	s_addc_u32 s21, s21, 0
	s_add_u32 s47, s47, 0x100
	s_addc_u32 s48, s48, 0
	s_cmp_gt_u32 s49, 5
	s_cbranch_scc0 .LBB0_1579
	s_and_b64 vcc, exec, s[60:61]
	s_cbranch_vccz .LBB0_1582
	s_barrier
